# combination on v18: K reads one per PV gap + wait consolidation/m0 save-restore removal in attention loops + back-edge rotation + rsq/Newton 1/sqrt in P3/P5a/P7 epilogues
# speedup vs baseline: 1.0211x; 1.0101x over previous
; __device__ __forceinline__ void glds16(const void*gsrc,unsigned lds_dst){unsigned keep;
;   asm volatile("s_mov_b32 %0, m0\n\ts_mov_b32 m0, %2\n\ts_nop 0\n\tglobal_load_lds_dwordx4 %1, off\n\ts_mov_b32 m0, %0":"=&s"(keep):"v"(gsrc),"s"(lds_dst):"memory");}
.LBB0_863:
	v_mfma_f32_32x32x16_bf16 v[112:127], v[100:103], v[218:221], 0
	v_lshl_add_u32 v206, s89, 1, v168
	ds_read_b64_tr_b16 v[194:195], v206 offset:24576
	ds_read_b64_tr_b16 v[196:197], v206 offset:25088
	v_add_f32_e32 v108, v80, v81
	v_add_f32_e32 v108, v82, v108
	v_add_f32_e32 v108, v83, v108
	v_add_f32_e32 v108, v84, v108
	v_add_f32_e32 v108, v85, v108
	v_cvt_pk_bf16_f32 v156, v80, v81
	v_cvt_pk_bf16_f32 v157, v82, v83
	ds_read_b64_tr_b16 v[80:81], v206 offset:28672
	ds_read_b64_tr_b16 v[82:83], v206 offset:29184
	v_add_f32_e32 v104, v86, v108
	v_add_f32_e32 v104, v87, v104
	v_add_f32_e32 v104, v88, v104
	v_add_f32_e32 v144, v89, v104
	v_mfma_f32_32x32x16_bf16 v[96:111], v[96:99], v[218:221], 0
	v_cvt_pk_bf16_f32 v158, v84, v85
	v_cvt_pk_bf16_f32 v159, v86, v87
	ds_read_b64_tr_b16 v[84:85], v206 offset:25600
	ds_read_b64_tr_b16 v[86:87], v206 offset:26112
	v_add_f32_e32 v144, v90, v144
	v_add_f32_e32 v144, v91, v144
	v_add_f32_e32 v144, v92, v144
	v_add_f32_e32 v144, v93, v144
	v_cvt_pk_bf16_f32 v152, v88, v89
	v_cvt_pk_bf16_f32 v153, v90, v91
	v_mfma_f32_32x32x16_bf16 v[112:127], v[164:167], v[222:225], v[112:127]
	ds_read_b64_tr_b16 v[88:89], v206 offset:29696
	ds_read_b64_tr_b16 v[90:91], v206 offset:30208
	v_add_f32_e32 v144, v94, v144
	v_add_f32_e32 v144, v95, v144
	v_add_f32_e32 v144, v64, v144
	v_add_f32_e32 v144, v65, v144
	v_mfma_f32_32x32x16_bf16 v[96:111], v[160:163], v[222:225], v[96:111]
	v_cvt_pk_bf16_f32 v154, v92, v93
	v_cvt_pk_bf16_f32 v155, v94, v95
	ds_read_b64_tr_b16 v[92:93], v206 offset:26624
	ds_read_b64_tr_b16 v[94:95], v206 offset:27136
	v_add_f32_e32 v144, v66, v144
	v_add_f32_e32 v144, v67, v144
	v_add_f32_e32 v144, v68, v144
	v_add_f32_e32 v144, v69, v144
	v_cvt_pk_bf16_f32 v148, v64, v65
	v_cvt_pk_bf16_f32 v149, v66, v67
	v_mfma_f32_32x32x16_bf16 v[112:127], v[140:143], v[226:229], v[112:127]
	ds_read_b64_tr_b16 v[198:199], v206 offset:30720
	ds_read_b64_tr_b16 v[200:201], v206 offset:31232
	v_add_f32_e32 v140, v70, v144
	v_add_f32_e32 v140, v71, v140
	v_add_f32_e32 v140, v72, v140
	v_add_f32_e32 v140, v73, v140
	v_mfma_f32_32x32x16_bf16 v[96:111], v[136:139], v[226:229], v[96:111]
	v_cvt_pk_bf16_f32 v150, v68, v69
	v_cvt_pk_bf16_f32 v151, v70, v71
	ds_read_b64_tr_b16 v[202:203], v206 offset:27648
	ds_read_b64_tr_b16 v[204:205], v206 offset:28160
	v_add_f32_e32 v68, v74, v140
	v_add_f32_e32 v68, v75, v68
	v_add_f32_e32 v68, v76, v68
	v_add_f32_e32 v68, v77, v68
	v_cvt_pk_bf16_f32 v144, v72, v73
	v_cvt_pk_bf16_f32 v145, v74, v75
	v_mfma_f32_32x32x16_bf16 v[112:127], v[132:135], v[230:233], v[112:127]
	ds_read_b64_tr_b16 v[72:73], v206 offset:31744
	ds_read_b64_tr_b16 v[74:75], v206 offset:32256
	v_add_f32_e32 v68, v78, v68
	v_add_f32_e32 v68, v79, v68
	v_cvt_pk_bf16_f32 v146, v76, v77
	v_mfma_f32_32x32x16_bf16 v[96:111], v[128:131], v[230:233], v[96:111]
	v_cvt_pk_bf16_f32 v147, v78, v79
	s_add_i32 m0, s87, s35
	v_lshl_add_u64 v[64:65], v[180:181], 0, s[54:55]
	global_load_lds_dwordx4 v[64:65], off
	s_lshl_b32 s88, s86, 1
	s_add_i32 s88, s88, s16
	s_mov_b32 m0, s88
	v_lshl_add_u64 v[64:65], v[178:179], 0, s[54:55]
	global_load_lds_dwordx4 v[64:65], off
	s_addk_i32 m0, 0x2000
	v_lshl_add_u64 v[64:65], v[176:177], 0, s[54:55]
	global_load_lds_dwordx4 v[64:65], off
	v_add_f32_e32 v193, v193, v68
	v_add_u32_e32 v242, s86, v234
	v_add_u32_e32 v243, s86, v235
	v_add_u32_e32 v244, s86, v236
	v_add_u32_e32 v245, s86, v237
	s_waitcnt lgkmcnt(12)
	v_mfma_f32_32x32x16_bf16 v[48:63], v[156:159], v[194:197], v[48:63]
	ds_read_b64_tr_b16 v[76:77], v206 offset:32768
	ds_read_b64_tr_b16 v[78:79], v206 offset:33280
	v_exp_f32_e32 v112, v112
	v_exp_f32_e32 v113, v113
	ds_read_b128 v[68:71], v242
	v_mfma_f32_32x32x16_bf16 v[32:47], v[156:159], v[80:83], v[32:47]
	ds_read_b64_tr_b16 v[194:195], v206 offset:36864
	ds_read_b64_tr_b16 v[196:197], v206 offset:37376
	v_exp_f32_e32 v114, v114
	v_exp_f32_e32 v115, v115
	ds_read_b128 v[64:67], v242 offset:4096
	s_waitcnt lgkmcnt(14)
	v_mfma_f32_32x32x16_bf16 v[48:63], v[152:155], v[84:87], v[48:63]
	ds_read_b64_tr_b16 v[80:81], v206 offset:33792
	ds_read_b64_tr_b16 v[82:83], v206 offset:34304
	v_exp_f32_e32 v116, v116
	v_exp_f32_e32 v117, v117
	ds_read_b128 v[164:167], v243
	v_mfma_f32_32x32x16_bf16 v[32:47], v[152:155], v[88:91], v[32:47]
	ds_read_b64_tr_b16 v[84:85], v206 offset:37888
	ds_read_b64_tr_b16 v[86:87], v206 offset:38400
	v_exp_f32_e32 v118, v118
	v_exp_f32_e32 v119, v119
	ds_read_b128 v[140:143], v243 offset:4096
	s_waitcnt lgkmcnt(14)
	v_mfma_f32_32x32x16_bf16 v[48:63], v[148:151], v[92:95], v[48:63]
	ds_read_b64_tr_b16 v[88:89], v206 offset:34816
	ds_read_b64_tr_b16 v[90:91], v206 offset:35328
	v_exp_f32_e32 v120, v120
	v_exp_f32_e32 v121, v121
	ds_read_b128 v[160:163], v244
	v_mfma_f32_32x32x16_bf16 v[32:47], v[148:151], v[198:201], v[32:47]
	ds_read_b64_tr_b16 v[92:93], v206 offset:38912
	ds_read_b64_tr_b16 v[94:95], v206 offset:39424
	v_exp_f32_e32 v122, v122
	v_exp_f32_e32 v123, v123
	ds_read_b128 v[132:135], v244 offset:4096
	s_waitcnt lgkmcnt(14)
	v_mfma_f32_32x32x16_bf16 v[48:63], v[144:147], v[202:205], v[48:63]
	ds_read_b64_tr_b16 v[198:199], v206 offset:35840
	ds_read_b64_tr_b16 v[200:201], v206 offset:36352
	v_exp_f32_e32 v124, v124
	v_exp_f32_e32 v125, v125
	ds_read_b128 v[136:139], v245
	v_mfma_f32_32x32x16_bf16 v[32:47], v[144:147], v[72:75], v[32:47]
	ds_read_b64_tr_b16 v[202:203], v206 offset:39936
	ds_read_b64_tr_b16 v[204:205], v206 offset:40448
	v_exp_f32_e32 v126, v126
	v_exp_f32_e32 v127, v127
	ds_read_b128 v[128:131], v245 offset:4096
	s_waitcnt lgkmcnt(14)
	v_mfma_f32_32x32x16_bf16 v[16:31], v[156:159], v[76:79], v[16:31]
	v_exp_f32_e32 v96, v96
	v_exp_f32_e32 v97, v97
	v_mfma_f32_32x32x16_bf16 v[0:15], v[156:159], v[194:197], v[0:15]
	v_exp_f32_e32 v98, v98
	v_exp_f32_e32 v99, v99
	v_mfma_f32_32x32x16_bf16 v[16:31], v[152:155], v[80:83], v[16:31]
	v_exp_f32_e32 v100, v100
	v_exp_f32_e32 v101, v101
	s_waitcnt lgkmcnt(12)
	v_mfma_f32_32x32x16_bf16 v[0:15], v[152:155], v[84:87], v[0:15]
	v_exp_f32_e32 v102, v102
	v_exp_f32_e32 v103, v103
	s_waitcnt lgkmcnt(8)
	v_mfma_f32_32x32x16_bf16 v[16:31], v[148:151], v[88:91], v[16:31]
	v_exp_f32_e32 v104, v104
	v_exp_f32_e32 v105, v105
	s_waitcnt lgkmcnt(4)
	v_mfma_f32_32x32x16_bf16 v[0:15], v[148:151], v[92:95], v[0:15]
	v_exp_f32_e32 v106, v106
	v_exp_f32_e32 v107, v107
	s_waitcnt lgkmcnt(2)
	v_mfma_f32_32x32x16_bf16 v[16:31], v[144:147], v[198:201], v[16:31]
	v_exp_f32_e32 v108, v108
	v_exp_f32_e32 v109, v109
	s_waitcnt lgkmcnt(0)
	v_mfma_f32_32x32x16_bf16 v[0:15], v[144:147], v[202:205], v[0:15]
	v_exp_f32_e32 v110, v110
	v_exp_f32_e32 v111, v111
	s_waitcnt vmcnt(3) lgkmcnt(0)
	s_barrier
; __device__ __forceinline__ void glds16(const void*gsrc,unsigned lds_dst){unsigned keep;
;   asm volatile("s_mov_b32 %0, m0\n\ts_mov_b32 m0, %2\n\ts_nop 0\n\tglobal_load_lds_dwordx4 %1, off\n\ts_mov_b32 m0, %0":"=&s"(keep):"v"(gsrc),"s"(lds_dst):"memory");}
	v_mfma_f32_32x32x16_bf16 v[80:95], v[68:71], v[218:221], 0
	s_add_i32 s88, s86, 0x2000
	s_cmpk_lg_i32 s86, 0x4000
	s_cselect_b32 s88, s88, 0
	v_lshl_add_u32 v206, s87, 1, v168
	ds_read_b64_tr_b16 v[194:195], v206 offset:24576
	ds_read_b64_tr_b16 v[196:197], v206 offset:25088
	v_add_f32_e32 v76, v112, v113
	v_add_f32_e32 v76, v114, v76
	v_add_f32_e32 v76, v115, v76
	v_add_f32_e32 v76, v116, v76
	v_add_f32_e32 v76, v117, v76
	v_cvt_pk_bf16_f32 v156, v112, v113
	v_cvt_pk_bf16_f32 v157, v114, v115
	ds_read_b64_tr_b16 v[112:113], v206 offset:28672
	ds_read_b64_tr_b16 v[114:115], v206 offset:29184
	v_add_f32_e32 v72, v118, v76
	v_add_f32_e32 v72, v119, v72
	v_add_f32_e32 v72, v120, v72
	v_add_f32_e32 v144, v121, v72
	v_mfma_f32_32x32x16_bf16 v[64:79], v[64:67], v[218:221], 0
	v_cvt_pk_bf16_f32 v158, v116, v117
	v_cvt_pk_bf16_f32 v159, v118, v119
	ds_read_b64_tr_b16 v[116:117], v206 offset:25600
	ds_read_b64_tr_b16 v[118:119], v206 offset:26112
	v_add_f32_e32 v144, v122, v144
	v_add_f32_e32 v144, v123, v144
	v_add_f32_e32 v144, v124, v144
	v_add_f32_e32 v144, v125, v144
	v_mfma_f32_32x32x16_bf16 v[80:95], v[164:167], v[222:225], v[80:95]
	v_cvt_pk_bf16_f32 v152, v120, v121
	v_cvt_pk_bf16_f32 v153, v122, v123
	ds_read_b64_tr_b16 v[120:121], v206 offset:29696
	ds_read_b64_tr_b16 v[122:123], v206 offset:30208
	v_add_f32_e32 v144, v126, v144
	v_add_f32_e32 v144, v127, v144
	v_add_f32_e32 v144, v96, v144
	v_add_f32_e32 v144, v97, v144
	v_mfma_f32_32x32x16_bf16 v[64:79], v[140:143], v[222:225], v[64:79]
	v_cvt_pk_bf16_f32 v154, v124, v125
	v_cvt_pk_bf16_f32 v155, v126, v127
	ds_read_b64_tr_b16 v[124:125], v206 offset:26624
	ds_read_b64_tr_b16 v[126:127], v206 offset:27136
	v_add_f32_e32 v144, v98, v144
	v_add_f32_e32 v144, v99, v144
	v_add_f32_e32 v144, v100, v144
	v_add_f32_e32 v144, v101, v144
	v_mfma_f32_32x32x16_bf16 v[80:95], v[160:163], v[226:229], v[80:95]
	v_cvt_pk_bf16_f32 v148, v96, v97
	v_cvt_pk_bf16_f32 v149, v98, v99
	ds_read_b64_tr_b16 v[198:199], v206 offset:30720
	ds_read_b64_tr_b16 v[200:201], v206 offset:31232
	v_add_f32_e32 v140, v102, v144
	v_add_f32_e32 v140, v103, v140
	v_add_f32_e32 v140, v104, v140
	v_add_f32_e32 v140, v105, v140
	v_mfma_f32_32x32x16_bf16 v[64:79], v[132:135], v[226:229], v[64:79]
	v_cvt_pk_bf16_f32 v150, v100, v101
	v_cvt_pk_bf16_f32 v151, v102, v103
	ds_read_b64_tr_b16 v[202:203], v206 offset:27648
	ds_read_b64_tr_b16 v[204:205], v206 offset:28160
	v_add_f32_e32 v100, v106, v140
	v_add_f32_e32 v100, v107, v100
	v_add_f32_e32 v100, v108, v100
	v_add_f32_e32 v100, v109, v100
	v_mfma_f32_32x32x16_bf16 v[80:95], v[136:139], v[230:233], v[80:95]
	v_cvt_pk_bf16_f32 v144, v104, v105
	v_cvt_pk_bf16_f32 v145, v106, v107
	ds_read_b64_tr_b16 v[104:105], v206 offset:31744
	ds_read_b64_tr_b16 v[106:107], v206 offset:32256
	v_add_f32_e32 v100, v110, v100
	v_add_f32_e32 v100, v111, v100
	v_cvt_pk_bf16_f32 v146, v108, v109
	v_mfma_f32_32x32x16_bf16 v[64:79], v[128:131], v[230:233], v[64:79]
	v_cvt_pk_bf16_f32 v147, v110, v111
	s_add_i32 m0, s86, s35
	s_nop 0
	global_load_lds_dwordx4 v[180:181], off
	s_lshl_b32 s87, s88, 1
	s_add_i32 s87, s87, s16
	s_mov_b32 m0, s87
	s_nop 0
	global_load_lds_dwordx4 v[178:179], off
	s_addk_i32 m0, 0x2000
	s_nop 0
	global_load_lds_dwordx4 v[176:177], off
	v_add_f32_e32 v193, v193, v100
	v_add_u32_e32 v242, s88, v234
	v_add_u32_e32 v243, s88, v235
	v_add_u32_e32 v244, s88, v236
	v_add_u32_e32 v245, s88, v237
	s_waitcnt lgkmcnt(12)
	v_mfma_f32_32x32x16_bf16 v[48:63], v[156:159], v[194:197], v[48:63]
	ds_read_b64_tr_b16 v[108:109], v206 offset:32768
	ds_read_b64_tr_b16 v[110:111], v206 offset:33280
	v_exp_f32_e32 v80, v80
	v_exp_f32_e32 v81, v81
	ds_read_b128 v[100:103], v242
	v_mfma_f32_32x32x16_bf16 v[32:47], v[156:159], v[112:115], v[32:47]
	ds_read_b64_tr_b16 v[194:195], v206 offset:36864
	ds_read_b64_tr_b16 v[196:197], v206 offset:37376
	v_exp_f32_e32 v82, v82
	v_exp_f32_e32 v83, v83
	ds_read_b128 v[96:99], v242 offset:4096
	s_waitcnt lgkmcnt(14)
	v_mfma_f32_32x32x16_bf16 v[48:63], v[152:155], v[116:119], v[48:63]
	ds_read_b64_tr_b16 v[112:113], v206 offset:33792
	ds_read_b64_tr_b16 v[114:115], v206 offset:34304
	v_exp_f32_e32 v84, v84
	v_exp_f32_e32 v85, v85
	ds_read_b128 v[164:167], v243
	v_mfma_f32_32x32x16_bf16 v[32:47], v[152:155], v[120:123], v[32:47]
	ds_read_b64_tr_b16 v[116:117], v206 offset:37888
	ds_read_b64_tr_b16 v[118:119], v206 offset:38400
	v_exp_f32_e32 v86, v86
	v_exp_f32_e32 v87, v87
	ds_read_b128 v[160:163], v243 offset:4096
	s_waitcnt lgkmcnt(14)
	v_mfma_f32_32x32x16_bf16 v[48:63], v[148:151], v[124:127], v[48:63]
	ds_read_b64_tr_b16 v[120:121], v206 offset:34816
	ds_read_b64_tr_b16 v[122:123], v206 offset:35328
	v_exp_f32_e32 v88, v88
	v_exp_f32_e32 v89, v89
	ds_read_b128 v[140:143], v244
	v_mfma_f32_32x32x16_bf16 v[32:47], v[148:151], v[198:201], v[32:47]
	ds_read_b64_tr_b16 v[124:125], v206 offset:38912
	ds_read_b64_tr_b16 v[126:127], v206 offset:39424
	v_exp_f32_e32 v90, v90
	v_exp_f32_e32 v91, v91
	ds_read_b128 v[136:139], v244 offset:4096
	s_waitcnt lgkmcnt(14)
	v_mfma_f32_32x32x16_bf16 v[48:63], v[144:147], v[202:205], v[48:63]
	ds_read_b64_tr_b16 v[198:199], v206 offset:35840
	ds_read_b64_tr_b16 v[200:201], v206 offset:36352
	v_exp_f32_e32 v92, v92
	v_exp_f32_e32 v93, v93
	ds_read_b128 v[132:135], v245
	v_mfma_f32_32x32x16_bf16 v[32:47], v[144:147], v[104:107], v[32:47]
	ds_read_b64_tr_b16 v[202:203], v206 offset:39936
	ds_read_b64_tr_b16 v[204:205], v206 offset:40448
	v_exp_f32_e32 v94, v94
	v_exp_f32_e32 v95, v95
	ds_read_b128 v[128:131], v245 offset:4096
	s_waitcnt lgkmcnt(14)
	v_mfma_f32_32x32x16_bf16 v[16:31], v[156:159], v[108:111], v[16:31]
	v_exp_f32_e32 v64, v64
	v_exp_f32_e32 v65, v65
	v_mfma_f32_32x32x16_bf16 v[0:15], v[156:159], v[194:197], v[0:15]
	v_exp_f32_e32 v66, v66
	v_exp_f32_e32 v67, v67
	v_mfma_f32_32x32x16_bf16 v[16:31], v[152:155], v[112:115], v[16:31]
	v_exp_f32_e32 v68, v68
	v_exp_f32_e32 v69, v69
	s_waitcnt lgkmcnt(12)
	v_mfma_f32_32x32x16_bf16 v[0:15], v[152:155], v[116:119], v[0:15]
	v_exp_f32_e32 v70, v70
	v_exp_f32_e32 v71, v71
	s_waitcnt lgkmcnt(8)
	v_mfma_f32_32x32x16_bf16 v[16:31], v[148:151], v[120:123], v[16:31]
	v_exp_f32_e32 v72, v72
	v_exp_f32_e32 v73, v73
	s_waitcnt lgkmcnt(4)
	v_mfma_f32_32x32x16_bf16 v[0:15], v[148:151], v[124:127], v[0:15]
	v_exp_f32_e32 v74, v74
	v_exp_f32_e32 v75, v75
	s_waitcnt lgkmcnt(2)
	v_mfma_f32_32x32x16_bf16 v[16:31], v[144:147], v[198:201], v[16:31]
	v_exp_f32_e32 v76, v76
	v_exp_f32_e32 v77, v77
	s_waitcnt lgkmcnt(0)
	v_mfma_f32_32x32x16_bf16 v[0:15], v[144:147], v[202:205], v[0:15]
	v_exp_f32_e32 v78, v78
	v_exp_f32_e32 v79, v79
	s_add_i32 s90, s88, 0x2000
	s_cmpk_lg_i32 s88, 0x4000
	s_mov_b32 s89, s86
	s_cselect_b32 s86, s90, 0
	s_add_i32 s85, s85, 2
	v_lshl_add_u64 v[176:177], v[176:177], 0, s[56:57]
	v_lshl_add_u64 v[178:179], v[178:179], 0, s[56:57]
	v_lshl_add_u64 v[180:181], v[180:181], 0, s[56:57]
	s_mov_b32 s87, s88
	s_cmpk_lt_u32 s85, 0x79
	s_waitcnt vmcnt(3) lgkmcnt(0)
	s_barrier
; #define WAIT_BAR(N) asm volatile("s_waitcnt vmcnt(" #N ") lgkmcnt(0)\n\ts_barrier":::"memory")
;   #define RESC() do{ if(!NOMAX&&resc){ asm volatile("s_waitcnt lgkmcnt(0)":::"memory"); \
;       _Pragma("unroll") for(int d_=0;d_<2*VM;++d_) _Pragma("unroll") for(int r=0;r<16;++r)o[d_][r]*=wsf[crow(r,hi)]; } }while(0)
;   #define ROT() do{sl_prev=sl_cur;sl_cur=sl_next;sl_next=(sl_next==(NSLOT-1)*SLOTB)?0:sl_next+SLOTB;}while(0)
;   #define ENDW(tt) do{ if((tt)+3<NT){ if constexpr(VM==2){WAIT_BAR(3);}else{WAIT_BAR(2);} } else if((tt)+2<NT){ if constexpr(VM==2){WAIT_BAR(2);}else{WAIT_BAR(1);} } else {WAIT_BAR(0);} }while(0)
; template<int THRL,int VM,bool NOMAX> __device__ __forceinline__ void attn_unit(const bf16*Qb,const bf16*__restrict__ Kh,const bf16*__restrict__ Vh,bf16*Ob,const int NT,const int sp,float*wscr,char*shm){
;     ...
;   for(;t+5<NT;t+=2){
;     STEP(pB0,pB1,pA0,pA1,t,true,true,true);     if constexpr(VM==2){WAIT_BAR(3);}else{WAIT_BAR(2);} RESC(); ROT();
;     STEP(pA0,pA1,pB0,pB1,t+1,true,true,true);   if constexpr(VM==2){WAIT_BAR(3);}else{WAIT_BAR(2);} RESC(); ROT();
;   }
;     ...
;   for(;t+1<NT;t+=2){
;     STEP(pB0,pB1,pA0,pA1,t,(t+3<NT),(t+1<NT),(t+1<NT));       ENDW(t);   RESC(); ROT();
;     STEP(pA0,pA1,pB0,pB1,t+1,(t+4<NT),(t+2<NT),(t+2<NT));     ENDW(t+1); RESC(); ROT();
	s_cbranch_scc1 .LBB0_863
	s_and_b32 s34, s34, 0x3fffffc0
	s_lshl_b32 s34, s34, 2
	s_add_i32 s34, s34, 0
	s_add_i32 s34, s34, 0x12000
	s_cmp_lg_u32 0, -1
	s_cselect_b32 s85, 0, 0
	s_add_i32 s86, s85, 0x6000
	v_add_u32_e32 v104, s86, v191
	v_add3_u32 v176, v104, v190, v192
	v_add_u32_e32 v177, 0x6000, v168
	ds_read_b64_tr_b16 v[178:179], v168 offset:57344
	ds_read_b64_tr_b16 v[180:181], v168 offset:57856
	v_add_f32_e32 v108, v80, v81
	ds_read_b128 v[104:107], v188
	v_add_f32_e32 v108, v82, v108
	v_add_f32_e32 v108, v83, v108
	v_add_f32_e32 v108, v84, v108
	v_add_f32_e32 v108, v85, v108
	v_cvt_pk_bf16_f32 v156, v80, v81
	v_cvt_pk_bf16_f32 v157, v82, v83
	s_waitcnt lgkmcnt(0)
	v_mfma_f32_32x32x16_bf16 v[112:127], v[100:103], v[104:107], 0
	ds_read_b64_tr_b16 v[80:81], v168 offset:61440
	ds_read_b64_tr_b16 v[82:83], v168 offset:61952
	ds_read_b128 v[100:103], v188
	v_add_f32_e32 v104, v86, v108
	v_add_f32_e32 v104, v87, v104
	v_add_f32_e32 v104, v88, v104
	v_add_f32_e32 v144, v89, v104
	v_cvt_pk_bf16_f32 v158, v84, v85
	v_cvt_pk_bf16_f32 v159, v86, v87
	s_waitcnt lgkmcnt(0)
	v_mfma_f32_32x32x16_bf16 v[96:111], v[96:99], v[100:103], 0
	ds_read_b64_tr_b16 v[84:85], v168 offset:58368
	ds_read_b64_tr_b16 v[86:87], v168 offset:58880
	ds_read_b128 v[194:197], v188 offset:1024
	v_add_f32_e32 v144, v90, v144
	v_add_f32_e32 v144, v91, v144
	v_add_f32_e32 v144, v92, v144
	v_add_f32_e32 v144, v93, v144
	v_cvt_pk_bf16_f32 v152, v88, v89
	v_cvt_pk_bf16_f32 v153, v90, v91
	s_waitcnt lgkmcnt(0)
	v_mfma_f32_32x32x16_bf16 v[112:127], v[164:167], v[194:197], v[112:127]
	ds_read_b64_tr_b16 v[88:89], v168 offset:62464
	ds_read_b64_tr_b16 v[90:91], v168 offset:62976
	ds_read_b128 v[164:167], v188 offset:1024
	v_add_f32_e32 v144, v94, v144
	v_add_f32_e32 v144, v95, v144
	v_add_f32_e32 v144, v64, v144
	v_add_f32_e32 v144, v65, v144
	v_cvt_pk_bf16_f32 v154, v92, v93
	v_cvt_pk_bf16_f32 v155, v94, v95
	s_waitcnt lgkmcnt(0)
	v_mfma_f32_32x32x16_bf16 v[96:111], v[160:163], v[164:167], v[96:111]
	ds_read_b64_tr_b16 v[194:195], v168 offset:59392
	ds_read_b64_tr_b16 v[196:197], v168 offset:59904
	ds_read_b128 v[92:95], v188 offset:2048
	v_add_f32_e32 v144, v66, v144
	v_add_f32_e32 v144, v67, v144
	v_add_f32_e32 v144, v68, v144
	v_add_f32_e32 v144, v69, v144
	v_cvt_pk_bf16_f32 v148, v64, v65
	v_cvt_pk_bf16_f32 v149, v66, v67
	s_waitcnt lgkmcnt(0)
	v_mfma_f32_32x32x16_bf16 v[112:127], v[140:143], v[92:95], v[112:127]
	ds_read_b64_tr_b16 v[140:141], v168 offset:63488
	ds_read_b64_tr_b16 v[142:143], v168 offset:64000
	ds_read_b128 v[64:67], v188 offset:2048
	v_add_f32_e32 v92, v70, v144
	v_add_f32_e32 v92, v71, v92
	v_add_f32_e32 v92, v72, v92
	v_add_f32_e32 v92, v73, v92
	v_cvt_pk_bf16_f32 v150, v68, v69
	v_cvt_pk_bf16_f32 v151, v70, v71
	s_waitcnt lgkmcnt(0)
	v_mfma_f32_32x32x16_bf16 v[96:111], v[136:139], v[64:67], v[96:111]
	ds_read_b64_tr_b16 v[136:137], v168 offset:60416
	ds_read_b64_tr_b16 v[138:139], v168 offset:60928
	ds_read_b128 v[64:67], v188 offset:3072
	v_add_f32_e32 v68, v74, v92
	v_add_f32_e32 v68, v75, v68
	v_add_f32_e32 v68, v76, v68
	v_add_f32_e32 v68, v77, v68
	v_cvt_pk_bf16_f32 v144, v72, v73
	v_cvt_pk_bf16_f32 v145, v74, v75
	s_waitcnt lgkmcnt(0)
	v_mfma_f32_32x32x16_bf16 v[112:127], v[132:135], v[64:67], v[112:127]
	ds_read_b64_tr_b16 v[72:73], v168 offset:64512
	ds_read_b64_tr_b16 v[74:75], v168 offset:65024
	ds_read_b128 v[64:67], v188 offset:3072
	v_add_f32_e32 v68, v78, v68
	v_add_f32_e32 v68, v79, v68
	v_add_f32_e32 v68, 0, v68
	v_cvt_pk_bf16_f32 v146, v76, v77
	v_cvt_pk_bf16_f32 v147, v78, v79
	s_waitcnt lgkmcnt(0)
	v_mfma_f32_32x32x16_bf16 v[96:111], v[128:131], v[64:67], v[96:111]
	v_lshl_add_u64 v[64:65], v[174:175], 0, s[58:59]
	s_mov_b32 s86, m0
	s_mov_b32 m0, s35
	s_nop 0
	global_load_lds_dwordx4 v[64:65], off
	s_mov_b32 m0, s86
	s_add_i32 s85, s85, s17
	v_lshl_add_u64 v[64:65], v[170:171], 0, s[60:61]
	s_add_i32 s17, s85, 0xa000
	s_mov_b32 s35, m0
	s_mov_b32 m0, s17
	s_nop 0
	global_load_lds_dwordx4 v[64:65], off
	s_mov_b32 m0, s35
	v_lshl_add_u64 v[64:65], v[172:173], 0, s[60:61]
	s_add_i32 s35, s17, 0x2000
	s_mov_b32 s86, m0
	s_mov_b32 m0, s35
	s_nop 0
	global_load_lds_dwordx4 v[64:65], off
	s_mov_b32 m0, s86
	v_add_f32_e32 v198, v193, v68
	v_mfma_f32_32x32x16_bf16 v[48:63], v[156:159], v[178:181], v[48:63]
	ds_read_b64_tr_b16 v[76:77], v177 offset:40960
	ds_read_b64_tr_b16 v[78:79], v177 offset:41472
	v_exp_f32_e32 v112, v112
	v_exp_f32_e32 v113, v113
	v_mfma_f32_32x32x16_bf16 v[32:47], v[156:159], v[80:83], v[32:47]
	ds_read_b64_tr_b16 v[128:129], v177 offset:45056
	ds_read_b64_tr_b16 v[130:131], v177 offset:45568
	v_exp_f32_e32 v114, v114
	v_exp_f32_e32 v115, v115
	ds_read_b128 v[68:71], v234 offset:8192
	ds_read_b128 v[64:67], v234 offset:12288
	v_mfma_f32_32x32x16_bf16 v[48:63], v[152:155], v[84:87], v[48:63]
	ds_read_b64_tr_b16 v[132:133], v177 offset:41984
	ds_read_b64_tr_b16 v[134:135], v177 offset:42496
	v_exp_f32_e32 v116, v116
	v_exp_f32_e32 v117, v117
	ds_read_b128 v[164:167], v235 offset:8192
	ds_read_b128 v[92:95], v235 offset:12288
	v_mfma_f32_32x32x16_bf16 v[32:47], v[152:155], v[88:91], v[32:47]
	ds_read_b64_tr_b16 v[178:179], v177 offset:46080
	ds_read_b64_tr_b16 v[180:181], v177 offset:46592
	v_exp_f32_e32 v118, v118
	v_exp_f32_e32 v119, v119
	ds_read_b128 v[160:163], v236 offset:8192
	ds_read_b128 v[84:87], v236 offset:12288
	v_mfma_f32_32x32x16_bf16 v[48:63], v[148:151], v[194:197], v[48:63]
	ds_read_b64_tr_b16 v[190:191], v177 offset:43008
	ds_read_b64_tr_b16 v[192:193], v177 offset:43520
	v_exp_f32_e32 v120, v120
	v_exp_f32_e32 v121, v121
	ds_read_b128 v[88:91], v237 offset:8192
	ds_read_b128 v[80:83], v237 offset:12288
	v_mfma_f32_32x32x16_bf16 v[32:47], v[148:151], v[140:143], v[32:47]
	ds_read_b64_tr_b16 v[194:195], v177 offset:47104
	ds_read_b64_tr_b16 v[196:197], v177 offset:47616
	v_exp_f32_e32 v122, v122
	v_exp_f32_e32 v123, v123
	v_mfma_f32_32x32x16_bf16 v[48:63], v[144:147], v[136:139], v[48:63]
	ds_read_b64_tr_b16 v[140:141], v177 offset:44032
	ds_read_b64_tr_b16 v[142:143], v177 offset:44544
	v_exp_f32_e32 v124, v124
	v_exp_f32_e32 v125, v125
	v_mfma_f32_32x32x16_bf16 v[32:47], v[144:147], v[72:75], v[32:47]
	ds_read_b64_tr_b16 v[136:137], v177 offset:48128
	ds_read_b64_tr_b16 v[138:139], v177 offset:48640
	v_exp_f32_e32 v126, v126
	v_exp_f32_e32 v127, v127
	s_waitcnt lgkmcnt(14)
	v_mfma_f32_32x32x16_bf16 v[16:31], v[156:159], v[76:79], v[16:31]
	v_exp_f32_e32 v96, v96
	v_exp_f32_e32 v97, v97
	v_mfma_f32_32x32x16_bf16 v[0:15], v[156:159], v[128:131], v[0:15]
	v_exp_f32_e32 v98, v98
	v_exp_f32_e32 v99, v99
	v_mfma_f32_32x32x16_bf16 v[16:31], v[152:155], v[132:135], v[16:31]
	v_exp_f32_e32 v100, v100
	v_exp_f32_e32 v101, v101
	s_waitcnt lgkmcnt(12)
	v_mfma_f32_32x32x16_bf16 v[0:15], v[152:155], v[178:181], v[0:15]
	v_exp_f32_e32 v102, v102
	v_exp_f32_e32 v103, v103
	s_waitcnt lgkmcnt(8)
	v_mfma_f32_32x32x16_bf16 v[16:31], v[148:151], v[190:193], v[16:31]
	v_exp_f32_e32 v104, v104
	v_exp_f32_e32 v105, v105
	s_waitcnt lgkmcnt(4)
	v_mfma_f32_32x32x16_bf16 v[0:15], v[148:151], v[194:197], v[0:15]
	v_exp_f32_e32 v106, v106
	v_exp_f32_e32 v107, v107
	s_waitcnt lgkmcnt(2)
	v_mfma_f32_32x32x16_bf16 v[16:31], v[144:147], v[140:143], v[16:31]
	v_exp_f32_e32 v108, v108
	v_exp_f32_e32 v109, v109
	s_waitcnt lgkmcnt(0)
	v_mfma_f32_32x32x16_bf16 v[0:15], v[144:147], v[136:139], v[0:15]
	v_exp_f32_e32 v110, v110
	v_exp_f32_e32 v111, v111
	s_waitcnt vmcnt(3) lgkmcnt(0)
	s_barrier
	ds_read_b64_tr_b16 v[178:179], v168 offset:24576
	ds_read_b64_tr_b16 v[180:181], v168 offset:25088
	v_add_f32_e32 v76, v112, v113
	ds_read_b128 v[72:75], v188
	v_add_f32_e32 v76, v114, v76
	v_add_f32_e32 v76, v115, v76
	v_add_f32_e32 v76, v116, v76
	v_add_f32_e32 v76, v117, v76
	v_cvt_pk_bf16_f32 v156, v112, v113
	v_cvt_pk_bf16_f32 v157, v114, v115
	s_waitcnt lgkmcnt(0)
	v_mfma_f32_32x32x16_bf16 v[128:143], v[68:71], v[72:75], 0
	ds_read_b64_tr_b16 v[112:113], v168 offset:28672
	ds_read_b64_tr_b16 v[114:115], v168 offset:29184
	ds_read_b128 v[68:71], v188
	v_add_f32_e32 v72, v118, v76
	v_add_f32_e32 v72, v119, v72
	v_add_f32_e32 v72, v120, v72
	v_add_f32_e32 v144, v121, v72
	s_waitcnt lgkmcnt(0)
	v_mfma_f32_32x32x16_bf16 v[64:79], v[64:67], v[68:71], 0
	v_cvt_pk_bf16_f32 v158, v116, v117
	v_cvt_pk_bf16_f32 v159, v118, v119
	ds_read_b64_tr_b16 v[116:117], v168 offset:25600
	ds_read_b64_tr_b16 v[118:119], v168 offset:26112
	ds_read_b128 v[190:193], v188 offset:1024
	v_add_f32_e32 v144, v122, v144
	v_add_f32_e32 v144, v123, v144
	v_add_f32_e32 v144, v124, v144
	v_add_f32_e32 v144, v125, v144
	v_cvt_pk_bf16_f32 v152, v120, v121
	v_cvt_pk_bf16_f32 v153, v122, v123
	s_waitcnt lgkmcnt(0)
	v_mfma_f32_32x32x16_bf16 v[128:143], v[164:167], v[190:193], v[128:143]
	ds_read_b64_tr_b16 v[120:121], v168 offset:29696
	ds_read_b64_tr_b16 v[122:123], v168 offset:30208
	ds_read_b128 v[164:167], v188 offset:1024
	v_add_f32_e32 v144, v126, v144
	v_add_f32_e32 v144, v127, v144
	v_add_f32_e32 v144, v96, v144
	v_add_f32_e32 v144, v97, v144
	s_waitcnt lgkmcnt(0)
	v_mfma_f32_32x32x16_bf16 v[64:79], v[92:95], v[164:167], v[64:79]
	v_cvt_pk_bf16_f32 v154, v124, v125
	v_cvt_pk_bf16_f32 v155, v126, v127
	ds_read_b64_tr_b16 v[92:93], v168 offset:26624
	ds_read_b64_tr_b16 v[94:95], v168 offset:27136
	ds_read_b128 v[124:127], v188 offset:2048
	v_add_f32_e32 v144, v98, v144
	v_add_f32_e32 v144, v99, v144
	v_add_f32_e32 v144, v100, v144
	v_add_f32_e32 v144, v101, v144
	v_cvt_pk_bf16_f32 v148, v96, v97
	v_cvt_pk_bf16_f32 v149, v98, v99
	s_waitcnt lgkmcnt(0)
	v_mfma_f32_32x32x16_bf16 v[128:143], v[160:163], v[124:127], v[128:143]
	ds_read_b64_tr_b16 v[96:97], v168 offset:30720
	ds_read_b64_tr_b16 v[98:99], v168 offset:31232
	ds_read_b128 v[124:127], v188 offset:2048
	v_add_f32_e32 v144, v102, v144
	v_add_f32_e32 v144, v103, v144
	v_add_f32_e32 v144, v104, v144
	v_add_f32_e32 v144, v105, v144
	s_waitcnt lgkmcnt(0)
	v_mfma_f32_32x32x16_bf16 v[64:79], v[84:87], v[124:127], v[64:79]
	v_cvt_pk_bf16_f32 v150, v100, v101
	v_cvt_pk_bf16_f32 v151, v102, v103
	ds_read_b64_tr_b16 v[100:101], v168 offset:27648
	ds_read_b64_tr_b16 v[102:103], v168 offset:28160
	ds_read_b128 v[84:87], v188 offset:3072
	v_add_f32_e32 v124, v106, v144
	v_add_f32_e32 v124, v107, v124
	v_add_f32_e32 v124, v108, v124
	v_add_f32_e32 v124, v109, v124
	v_cvt_pk_bf16_f32 v144, v104, v105
	v_cvt_pk_bf16_f32 v145, v106, v107
	s_waitcnt lgkmcnt(0)
	v_mfma_f32_32x32x16_bf16 v[128:143], v[88:91], v[84:87], v[128:143]
	ds_read_b64_tr_b16 v[88:89], v168 offset:31744
	ds_read_b64_tr_b16 v[90:91], v168 offset:32256
	ds_read_b128 v[84:87], v188 offset:3072
	v_add_f32_e32 v104, v110, v124
	v_add_f32_e32 v104, v111, v104
	v_add_f32_e32 v104, 0, v104
	v_cvt_pk_bf16_f32 v146, v108, v109
	s_waitcnt lgkmcnt(0)
	v_mfma_f32_32x32x16_bf16 v[64:79], v[80:83], v[84:87], v[64:79]
	v_cvt_pk_bf16_f32 v147, v110, v111
	v_lshl_add_u64 v[80:81], v[174:175], 0, s[62:63]
	s_add_i32 s86, s85, 0x2000
	s_mov_b32 s87, m0
	s_mov_b32 m0, s86
	s_nop 0
	global_load_lds_dwordx4 v[80:81], off
	s_mov_b32 m0, s87
	v_lshl_add_u64 v[80:81], v[170:171], 0, s[64:65]
	s_add_i32 s86, s85, 0xe000
	s_mov_b32 s87, m0
	s_mov_b32 m0, s86
	s_nop 0
	global_load_lds_dwordx4 v[80:81], off
	s_mov_b32 m0, s87
	v_lshl_add_u64 v[80:81], v[172:173], 0, s[64:65]
	s_add_i32 s85, s85, 0x10000
	s_mov_b32 s86, m0
	s_mov_b32 m0, s85
	s_nop 0
	global_load_lds_dwordx4 v[80:81], off
	s_mov_b32 m0, s86
	v_add_f32_e32 v198, v198, v104
	v_mfma_f32_32x32x16_bf16 v[48:63], v[156:159], v[178:181], v[48:63]
	ds_read_b64_tr_b16 v[104:105], v168 offset:32768
	ds_read_b64_tr_b16 v[106:107], v168 offset:33280
	v_exp_f32_e32 v128, v128
	v_exp_f32_e32 v129, v129
	v_mfma_f32_32x32x16_bf16 v[32:47], v[156:159], v[112:115], v[32:47]
	ds_read_b64_tr_b16 v[108:109], v168 offset:36864
	ds_read_b64_tr_b16 v[110:111], v168 offset:37376
	v_exp_f32_e32 v130, v130
	v_exp_f32_e32 v131, v131
	ds_read_b128 v[84:87], v234 offset:16384
	ds_read_b128 v[80:83], v234 offset:20480
	v_mfma_f32_32x32x16_bf16 v[48:63], v[152:155], v[116:119], v[48:63]
	ds_read_b64_tr_b16 v[178:179], v168 offset:33792
	ds_read_b64_tr_b16 v[180:181], v168 offset:34304
	v_exp_f32_e32 v132, v132
	v_exp_f32_e32 v133, v133
	ds_read_b128 v[164:167], v235 offset:16384
	ds_read_b128 v[124:127], v235 offset:20480
	v_mfma_f32_32x32x16_bf16 v[32:47], v[152:155], v[120:123], v[32:47]
	ds_read_b64_tr_b16 v[190:191], v168 offset:37888
	ds_read_b64_tr_b16 v[192:193], v168 offset:38400
	v_exp_f32_e32 v134, v134
	v_exp_f32_e32 v135, v135
	ds_read_b128 v[160:163], v236 offset:16384
	ds_read_b128 v[116:119], v236 offset:20480
	v_mfma_f32_32x32x16_bf16 v[48:63], v[148:151], v[92:95], v[48:63]
	ds_read_b64_tr_b16 v[194:195], v168 offset:34816
	ds_read_b64_tr_b16 v[196:197], v168 offset:35328
	v_exp_f32_e32 v136, v136
	v_exp_f32_e32 v137, v137
	ds_read_b128 v[120:123], v237 offset:16384
	ds_read_b128 v[112:115], v237 offset:20480
	v_mfma_f32_32x32x16_bf16 v[32:47], v[148:151], v[96:99], v[32:47]
	ds_read_b64_tr_b16 v[92:93], v168 offset:38912
	ds_read_b64_tr_b16 v[94:95], v168 offset:39424
	v_exp_f32_e32 v138, v138
	v_exp_f32_e32 v139, v139
	v_mfma_f32_32x32x16_bf16 v[48:63], v[144:147], v[100:103], v[48:63]
	ds_read_b64_tr_b16 v[96:97], v168 offset:35840
	ds_read_b64_tr_b16 v[98:99], v168 offset:36352
	v_exp_f32_e32 v140, v140
	v_exp_f32_e32 v141, v141
	v_mfma_f32_32x32x16_bf16 v[32:47], v[144:147], v[88:91], v[32:47]
	ds_read_b64_tr_b16 v[100:101], v168 offset:39936
	ds_read_b64_tr_b16 v[102:103], v168 offset:40448
	v_exp_f32_e32 v142, v142
	v_exp_f32_e32 v143, v143
	s_waitcnt lgkmcnt(14)
	v_mfma_f32_32x32x16_bf16 v[16:31], v[156:159], v[104:107], v[16:31]
	v_exp_f32_e32 v64, v64
	v_exp_f32_e32 v65, v65
	v_mfma_f32_32x32x16_bf16 v[0:15], v[156:159], v[108:111], v[0:15]
	v_exp_f32_e32 v66, v66
	v_exp_f32_e32 v67, v67
	v_mfma_f32_32x32x16_bf16 v[16:31], v[152:155], v[178:181], v[16:31]
	v_exp_f32_e32 v68, v68
	v_exp_f32_e32 v69, v69
	s_waitcnt lgkmcnt(12)
	v_mfma_f32_32x32x16_bf16 v[0:15], v[152:155], v[190:193], v[0:15]
	v_exp_f32_e32 v70, v70
	v_exp_f32_e32 v71, v71
	s_waitcnt lgkmcnt(8)
	v_mfma_f32_32x32x16_bf16 v[16:31], v[148:151], v[194:197], v[16:31]
	v_exp_f32_e32 v72, v72
	v_exp_f32_e32 v73, v73
	s_waitcnt lgkmcnt(4)
	v_mfma_f32_32x32x16_bf16 v[0:15], v[148:151], v[92:95], v[0:15]
	v_exp_f32_e32 v74, v74
	v_exp_f32_e32 v75, v75
	s_waitcnt lgkmcnt(2)
	v_mfma_f32_32x32x16_bf16 v[16:31], v[144:147], v[96:99], v[16:31]
	v_exp_f32_e32 v76, v76
	v_exp_f32_e32 v77, v77
	s_waitcnt lgkmcnt(0)
	v_mfma_f32_32x32x16_bf16 v[0:15], v[144:147], v[100:103], v[0:15]
	v_exp_f32_e32 v78, v78
	v_exp_f32_e32 v79, v79
	s_waitcnt vmcnt(3) lgkmcnt(0)
	s_barrier
	ds_read_b64_tr_b16 v[178:179], v168 offset:40960
	ds_read_b64_tr_b16 v[180:181], v168 offset:41472
	v_add_f32_e32 v92, v128, v129
	ds_read_b128 v[88:91], v188
	v_add_f32_e32 v92, v130, v92
	v_add_f32_e32 v92, v131, v92
	v_add_f32_e32 v92, v132, v92
	v_add_f32_e32 v92, v133, v92
	v_cvt_pk_bf16_f32 v156, v128, v129
	v_cvt_pk_bf16_f32 v157, v130, v131
	s_waitcnt lgkmcnt(0)
	v_mfma_f32_32x32x16_bf16 v[96:111], v[84:87], v[88:91], 0
	ds_read_b64_tr_b16 v[128:129], v168 offset:45056
	ds_read_b64_tr_b16 v[130:131], v168 offset:45568
	ds_read_b128 v[84:87], v188
	v_add_f32_e32 v88, v134, v92
	v_add_f32_e32 v88, v135, v88
	v_add_f32_e32 v88, v136, v88
	v_add_f32_e32 v144, v137, v88
	v_cvt_pk_bf16_f32 v158, v132, v133
	v_cvt_pk_bf16_f32 v159, v134, v135
	s_waitcnt lgkmcnt(0)
	v_mfma_f32_32x32x16_bf16 v[80:95], v[80:83], v[84:87], 0
	ds_read_b64_tr_b16 v[132:133], v168 offset:41984
	ds_read_b64_tr_b16 v[134:135], v168 offset:42496
	ds_read_b128 v[190:193], v188 offset:1024
	v_add_f32_e32 v144, v138, v144
	v_add_f32_e32 v144, v139, v144
	v_add_f32_e32 v144, v140, v144
	v_add_f32_e32 v144, v141, v144
	v_cvt_pk_bf16_f32 v152, v136, v137
	v_cvt_pk_bf16_f32 v153, v138, v139
	s_waitcnt lgkmcnt(0)
	v_mfma_f32_32x32x16_bf16 v[96:111], v[164:167], v[190:193], v[96:111]
	ds_read_b64_tr_b16 v[136:137], v168 offset:46080
	ds_read_b64_tr_b16 v[138:139], v168 offset:46592
	ds_read_b128 v[164:167], v188 offset:1024
	v_add_f32_e32 v144, v142, v144
	v_add_f32_e32 v144, v143, v144
	v_add_f32_e32 v144, v64, v144
	v_add_f32_e32 v144, v65, v144
	v_cvt_pk_bf16_f32 v154, v140, v141
	v_cvt_pk_bf16_f32 v155, v142, v143
	s_waitcnt lgkmcnt(0)
; #define WAIT_BAR(N) asm volatile("s_waitcnt vmcnt(" #N ") lgkmcnt(0)\n\ts_barrier":::"memory")
;   #define RESC() do{ if(!NOMAX&&resc){ asm volatile("s_waitcnt lgkmcnt(0)":::"memory"); \
;       _Pragma("unroll") for(int d_=0;d_<2*VM;++d_) _Pragma("unroll") for(int r=0;r<16;++r)o[d_][r]*=wsf[crow(r,hi)]; } }while(0)
;   #define ROT() do{sl_prev=sl_cur;sl_cur=sl_next;sl_next=(sl_next==(NSLOT-1)*SLOTB)?0:sl_next+SLOTB;}while(0)
;   #define ENDW(tt) do{ if((tt)+3<NT){ if constexpr(VM==2){WAIT_BAR(3);}else{WAIT_BAR(2);} } else if((tt)+2<NT){ if constexpr(VM==2){WAIT_BAR(2);}else{WAIT_BAR(1);} } else {WAIT_BAR(0);} }while(0)
; template<int THRL,int VM,bool NOMAX> __device__ __forceinline__ void attn_unit(const bf16*Qb,const bf16*__restrict__ Kh,const bf16*__restrict__ Vh,bf16*Ob,const int NT,const int sp,float*wscr,char*shm){
;     ...
;   int t=1;
;   for(;t+5<NT;t+=2){
;     STEP(pB0,pB1,pA0,pA1,t,true,true,true);     if constexpr(VM==2){WAIT_BAR(3);}else{WAIT_BAR(2);} RESC(); ROT();
;     STEP(pA0,pA1,pB0,pB1,t+1,true,true,true);   if constexpr(VM==2){WAIT_BAR(3);}else{WAIT_BAR(2);} RESC(); ROT();
;   }
;     ...
;   for(;t+1<NT;t+=2){
;     STEP(pB0,pB1,pA0,pA1,t,(t+3<NT),(t+1<NT),(t+1<NT));       ENDW(t);   RESC(); ROT();
;     STEP(pA0,pA1,pB0,pB1,t+1,(t+4<NT),(t+2<NT),(t+2<NT));     ENDW(t+1); RESC(); ROT();
	v_mfma_f32_32x32x16_bf16 v[80:95], v[124:127], v[164:167], v[80:95]
	ds_read_b64_tr_b16 v[124:125], v168 offset:43008
	ds_read_b64_tr_b16 v[126:127], v168 offset:43520
	ds_read_b128 v[140:143], v188 offset:2048
	v_add_f32_e32 v144, v66, v144
	v_add_f32_e32 v144, v67, v144
	v_add_f32_e32 v144, v68, v144
	v_add_f32_e32 v144, v69, v144
	v_cvt_pk_bf16_f32 v148, v64, v65
	v_cvt_pk_bf16_f32 v149, v66, v67
	s_waitcnt lgkmcnt(0)
	v_mfma_f32_32x32x16_bf16 v[96:111], v[160:163], v[140:143], v[96:111]
	ds_read_b64_tr_b16 v[190:191], v168 offset:47104
	ds_read_b64_tr_b16 v[192:193], v168 offset:47616
	ds_read_b128 v[64:67], v188 offset:2048
	v_add_f32_e32 v140, v70, v144
	v_add_f32_e32 v140, v71, v140
	v_add_f32_e32 v140, v72, v140
	v_add_f32_e32 v140, v73, v140
	v_cvt_pk_bf16_f32 v150, v68, v69
	v_cvt_pk_bf16_f32 v151, v70, v71
	s_waitcnt lgkmcnt(0)
	v_mfma_f32_32x32x16_bf16 v[80:95], v[116:119], v[64:67], v[80:95]
	ds_read_b64_tr_b16 v[116:117], v168 offset:44032
	ds_read_b64_tr_b16 v[118:119], v168 offset:44544
	ds_read_b128 v[64:67], v188 offset:3072
	v_add_f32_e32 v68, v74, v140
	v_add_f32_e32 v68, v75, v68
	v_add_f32_e32 v68, v76, v68
	v_add_f32_e32 v68, v77, v68
	v_cvt_pk_bf16_f32 v144, v72, v73
	v_cvt_pk_bf16_f32 v145, v74, v75
	s_waitcnt lgkmcnt(0)
	v_mfma_f32_32x32x16_bf16 v[96:111], v[120:123], v[64:67], v[96:111]
	ds_read_b64_tr_b16 v[72:73], v168 offset:48128
	ds_read_b64_tr_b16 v[74:75], v168 offset:48640
	ds_read_b128 v[64:67], v188 offset:3072
	v_add_f32_e32 v68, v78, v68
	v_add_f32_e32 v68, v79, v68
	v_add_f32_e32 v68, 0, v68
	v_cvt_pk_bf16_f32 v146, v76, v77
	v_cvt_pk_bf16_f32 v147, v78, v79
	s_waitcnt lgkmcnt(0)
	v_mfma_f32_32x32x16_bf16 v[80:95], v[112:115], v[64:67], v[80:95]
	v_lshl_add_u64 v[64:65], v[170:171], 0, s[58:59]
	s_mov_b32 s85, m0
	s_mov_b32 m0, s16
	s_nop 0
	global_load_lds_dwordx4 v[64:65], off
	s_mov_b32 m0, s85
	v_lshl_add_u64 v[64:65], v[172:173], 0, s[58:59]
	s_addk_i32 s16, 0x2000
	s_mov_b32 s85, m0
	s_mov_b32 m0, s16
	s_nop 0
	global_load_lds_dwordx4 v[64:65], off
	s_mov_b32 m0, s85
	v_add_f32_e32 v174, v198, v68
	v_mfma_f32_32x32x16_bf16 v[48:63], v[156:159], v[178:181], v[48:63]
	ds_read_b64_tr_b16 v[76:77], v168 offset:49152
	ds_read_b64_tr_b16 v[78:79], v168 offset:49664
	v_exp_f32_e32 v96, v96
	v_exp_f32_e32 v97, v97
	v_mfma_f32_32x32x16_bf16 v[32:47], v[156:159], v[128:131], v[32:47]
	ds_read_b64_tr_b16 v[112:113], v168 offset:53248
	ds_read_b64_tr_b16 v[114:115], v168 offset:53760
	v_exp_f32_e32 v98, v98
	v_exp_f32_e32 v99, v99
	ds_read_b128 v[68:71], v234
	ds_read_b128 v[64:67], v234 offset:4096
	v_mfma_f32_32x32x16_bf16 v[48:63], v[152:155], v[132:135], v[48:63]
	ds_read_b64_tr_b16 v[120:121], v168 offset:50176
	ds_read_b64_tr_b16 v[122:123], v168 offset:50688
	v_exp_f32_e32 v100, v100
	v_exp_f32_e32 v101, v101
	ds_read_b128 v[164:167], v235
	ds_read_b128 v[140:143], v235 offset:4096
	v_mfma_f32_32x32x16_bf16 v[32:47], v[152:155], v[136:139], v[32:47]
	ds_read_b64_tr_b16 v[178:179], v168 offset:54272
	ds_read_b64_tr_b16 v[180:181], v168 offset:54784
	v_exp_f32_e32 v102, v102
	v_exp_f32_e32 v103, v103
	ds_read_b128 v[160:163], v236
	ds_read_b128 v[132:135], v236 offset:4096
	v_mfma_f32_32x32x16_bf16 v[48:63], v[148:151], v[124:127], v[48:63]
	ds_read_b64_tr_b16 v[194:195], v168 offset:51200
	ds_read_b64_tr_b16 v[196:197], v168 offset:51712
	v_exp_f32_e32 v104, v104
	v_exp_f32_e32 v105, v105
	ds_read_b128 v[136:139], v237
	ds_read_b128 v[128:131], v237 offset:4096
	v_mfma_f32_32x32x16_bf16 v[32:47], v[148:151], v[190:193], v[32:47]
	ds_read_b64_tr_b16 v[124:125], v168 offset:55296
	ds_read_b64_tr_b16 v[126:127], v168 offset:55808
	v_exp_f32_e32 v106, v106
	v_exp_f32_e32 v107, v107
	v_mfma_f32_32x32x16_bf16 v[48:63], v[144:147], v[116:119], v[48:63]
	ds_read_b64_tr_b16 v[190:191], v168 offset:52224
	ds_read_b64_tr_b16 v[192:193], v168 offset:52736
	v_exp_f32_e32 v108, v108
	v_exp_f32_e32 v109, v109
	v_mfma_f32_32x32x16_bf16 v[32:47], v[144:147], v[72:75], v[32:47]
	ds_read_b64_tr_b16 v[116:117], v168 offset:56320
	ds_read_b64_tr_b16 v[118:119], v168 offset:56832
	v_exp_f32_e32 v110, v110
	v_exp_f32_e32 v111, v111
	s_waitcnt lgkmcnt(14)
	v_mfma_f32_32x32x16_bf16 v[16:31], v[156:159], v[76:79], v[16:31]
	v_exp_f32_e32 v80, v80
	v_exp_f32_e32 v81, v81
	v_mfma_f32_32x32x16_bf16 v[0:15], v[156:159], v[112:115], v[0:15]
	v_exp_f32_e32 v82, v82
	v_exp_f32_e32 v83, v83
	v_mfma_f32_32x32x16_bf16 v[16:31], v[152:155], v[120:123], v[16:31]
	v_exp_f32_e32 v84, v84
	v_exp_f32_e32 v85, v85
	s_waitcnt lgkmcnt(12)
	v_mfma_f32_32x32x16_bf16 v[0:15], v[152:155], v[178:181], v[0:15]
	v_exp_f32_e32 v86, v86
	v_exp_f32_e32 v87, v87
	s_waitcnt lgkmcnt(8)
	v_mfma_f32_32x32x16_bf16 v[16:31], v[148:151], v[194:197], v[16:31]
	v_exp_f32_e32 v88, v88
	v_exp_f32_e32 v89, v89
	s_waitcnt lgkmcnt(4)
	v_mfma_f32_32x32x16_bf16 v[0:15], v[148:151], v[124:127], v[0:15]
	v_exp_f32_e32 v90, v90
	v_exp_f32_e32 v91, v91
	s_waitcnt lgkmcnt(2)
	v_mfma_f32_32x32x16_bf16 v[16:31], v[144:147], v[190:193], v[16:31]
	v_exp_f32_e32 v92, v92
	v_exp_f32_e32 v93, v93
	s_waitcnt lgkmcnt(0)
	v_mfma_f32_32x32x16_bf16 v[0:15], v[144:147], v[116:119], v[0:15]
	v_exp_f32_e32 v94, v94
	v_exp_f32_e32 v95, v95
	s_waitcnt vmcnt(2) lgkmcnt(0)
	s_barrier
; #define WAIT_BAR(N) asm volatile("s_waitcnt vmcnt(" #N ") lgkmcnt(0)\n\ts_barrier":::"memory")
;   #define RESC() do{ if(!NOMAX&&resc){ asm volatile("s_waitcnt lgkmcnt(0)":::"memory"); \
;       _Pragma("unroll") for(int d_=0;d_<2*VM;++d_) _Pragma("unroll") for(int r=0;r<16;++r)o[d_][r]*=wsf[crow(r,hi)]; } }while(0)
;   #define ROT() do{sl_prev=sl_cur;sl_cur=sl_next;sl_next=(sl_next==(NSLOT-1)*SLOTB)?0:sl_next+SLOTB;}while(0)
;   #define ENDW(tt) do{ if((tt)+3<NT){ if constexpr(VM==2){WAIT_BAR(3);}else{WAIT_BAR(2);} } else if((tt)+2<NT){ if constexpr(VM==2){WAIT_BAR(2);}else{WAIT_BAR(1);} } else {WAIT_BAR(0);} }while(0)
; template<int THRL,int VM,bool NOMAX> __device__ __forceinline__ void attn_unit(const bf16*Qb,const bf16*__restrict__ Kh,const bf16*__restrict__ Vh,bf16*Ob,const int NT,const int sp,float*wscr,char*shm){
;     ...
;   int t=1;
;   for(;t+5<NT;t+=2){
;     STEP(pB0,pB1,pA0,pA1,t,true,true,true);     if constexpr(VM==2){WAIT_BAR(3);}else{WAIT_BAR(2);} RESC(); ROT();
;     STEP(pA0,pA1,pB0,pB1,t+1,true,true,true);   if constexpr(VM==2){WAIT_BAR(3);}else{WAIT_BAR(2);} RESC(); ROT();
;   }
;     ...
;   for(;t+1<NT;t+=2){
;     STEP(pB0,pB1,pA0,pA1,t,(t+3<NT),(t+1<NT),(t+1<NT));       ENDW(t);   RESC(); ROT();
;     STEP(pA0,pA1,pB0,pB1,t+1,(t+4<NT),(t+2<NT),(t+2<NT));     ENDW(t+1); RESC(); ROT();
	ds_read_b64_tr_b16 v[178:179], v168 offset:57344
	ds_read_b64_tr_b16 v[180:181], v168 offset:57856
	v_add_f32_e32 v76, v96, v97
	ds_read_b128 v[72:75], v188
	v_add_f32_e32 v76, v98, v76
	v_add_f32_e32 v76, v99, v76
	v_add_f32_e32 v76, v100, v76
	v_add_f32_e32 v76, v101, v76
	v_cvt_pk_bf16_f32 v156, v96, v97
	v_cvt_pk_bf16_f32 v157, v98, v99
	s_waitcnt lgkmcnt(0)
	v_mfma_f32_32x32x16_bf16 v[112:127], v[68:71], v[72:75], 0
	ds_read_b64_tr_b16 v[96:97], v168 offset:61440
	ds_read_b64_tr_b16 v[98:99], v168 offset:61952
	ds_read_b128 v[68:71], v188
	v_add_f32_e32 v72, v102, v76
	v_add_f32_e32 v72, v103, v72
	v_add_f32_e32 v72, v104, v72
	v_add_f32_e32 v144, v105, v72
	s_waitcnt lgkmcnt(0)
	v_mfma_f32_32x32x16_bf16 v[64:79], v[64:67], v[68:71], 0
	v_cvt_pk_bf16_f32 v158, v100, v101
	v_cvt_pk_bf16_f32 v159, v102, v103
	ds_read_b64_tr_b16 v[100:101], v168 offset:58368
	ds_read_b64_tr_b16 v[102:103], v168 offset:58880
	ds_read_b128 v[190:193], v188 offset:1024
	v_add_f32_e32 v144, v106, v144
	v_add_f32_e32 v144, v107, v144
	v_add_f32_e32 v144, v108, v144
	v_add_f32_e32 v144, v109, v144
	v_cvt_pk_bf16_f32 v152, v104, v105
	v_cvt_pk_bf16_f32 v153, v106, v107
	s_waitcnt lgkmcnt(0)
	v_mfma_f32_32x32x16_bf16 v[112:127], v[164:167], v[190:193], v[112:127]
	ds_read_b64_tr_b16 v[104:105], v168 offset:62464
	ds_read_b64_tr_b16 v[106:107], v168 offset:62976
	ds_read_b128 v[164:167], v188 offset:1024
	v_add_f32_e32 v144, v110, v144
	v_add_f32_e32 v144, v111, v144
	v_add_f32_e32 v144, v80, v144
	v_add_f32_e32 v144, v81, v144
	s_waitcnt lgkmcnt(0)
	v_mfma_f32_32x32x16_bf16 v[64:79], v[140:143], v[164:167], v[64:79]
	v_cvt_pk_bf16_f32 v154, v108, v109
	v_cvt_pk_bf16_f32 v155, v110, v111
	ds_read_b64_tr_b16 v[108:109], v168 offset:59392
	ds_read_b64_tr_b16 v[110:111], v168 offset:59904
	ds_read_b128 v[140:143], v188 offset:2048
	v_add_f32_e32 v144, v82, v144
	v_add_f32_e32 v144, v83, v144
	v_add_f32_e32 v144, v84, v144
	v_add_f32_e32 v144, v85, v144
	v_cvt_pk_bf16_f32 v148, v80, v81
	v_cvt_pk_bf16_f32 v149, v82, v83
	s_waitcnt lgkmcnt(0)
	v_mfma_f32_32x32x16_bf16 v[112:127], v[160:163], v[140:143], v[112:127]
	ds_read_b64_tr_b16 v[190:191], v168 offset:63488
	ds_read_b64_tr_b16 v[192:193], v168 offset:64000
	ds_read_b128 v[80:83], v188 offset:2048
	v_add_f32_e32 v140, v86, v144
	v_add_f32_e32 v140, v87, v140
	v_add_f32_e32 v140, v88, v140
	v_add_f32_e32 v140, v89, v140
	s_waitcnt lgkmcnt(0)
	v_mfma_f32_32x32x16_bf16 v[64:79], v[132:135], v[80:83], v[64:79]
	v_cvt_pk_bf16_f32 v150, v84, v85
	v_cvt_pk_bf16_f32 v151, v86, v87
	ds_read_b64_tr_b16 v[84:85], v168 offset:60416
	ds_read_b64_tr_b16 v[86:87], v168 offset:60928
	ds_read_b128 v[80:83], v188 offset:3072
	v_add_f32_e32 v132, v90, v140
	v_add_f32_e32 v132, v91, v132
	v_add_f32_e32 v132, v92, v132
	v_add_f32_e32 v132, v93, v132
	v_cvt_pk_bf16_f32 v144, v88, v89
	v_cvt_pk_bf16_f32 v145, v90, v91
	s_waitcnt lgkmcnt(0)
	v_mfma_f32_32x32x16_bf16 v[112:127], v[136:139], v[80:83], v[112:127]
	ds_read_b64_tr_b16 v[88:89], v168 offset:64512
	ds_read_b64_tr_b16 v[90:91], v168 offset:65024
	ds_read_b128 v[80:83], v188 offset:3072
	v_add_f32_e32 v132, v94, v132
	v_add_f32_e32 v132, v95, v132
	v_add_f32_e32 v132, 0, v132
	v_cvt_pk_bf16_f32 v146, v92, v93
	s_waitcnt lgkmcnt(0)
	v_mfma_f32_32x32x16_bf16 v[64:79], v[128:131], v[80:83], v[64:79]
	v_cvt_pk_bf16_f32 v147, v94, v95
	v_lshl_add_u64 v[80:81], v[170:171], 0, s[62:63]
	s_mov_b32 s16, m0
	s_mov_b32 m0, s17
	s_nop 0
	global_load_lds_dwordx4 v[80:81], off
	s_mov_b32 m0, s16
	v_lshl_add_u64 v[80:81], v[172:173], 0, s[62:63]
	s_mov_b32 s16, m0
	s_mov_b32 m0, s35
	s_nop 0
	global_load_lds_dwordx4 v[80:81], off
	s_mov_b32 m0, s16
	v_add_f32_e32 v174, v174, v132
	v_mfma_f32_32x32x16_bf16 v[48:63], v[156:159], v[178:181], v[48:63]
	ds_read_b64_tr_b16 v[92:93], v177 offset:40960
	ds_read_b64_tr_b16 v[94:95], v177 offset:41472
	v_exp_f32_e32 v112, v112
	v_exp_f32_e32 v113, v113
	v_mfma_f32_32x32x16_bf16 v[32:47], v[156:159], v[96:99], v[32:47]
	ds_read_b64_tr_b16 v[170:171], v177 offset:45056
	ds_read_b64_tr_b16 v[172:173], v177 offset:45568
	v_exp_f32_e32 v114, v114
	v_exp_f32_e32 v115, v115
	ds_read_b128 v[80:83], v234 offset:8192
	ds_read_b128 v[96:99], v234 offset:12288
	v_mfma_f32_32x32x16_bf16 v[48:63], v[152:155], v[100:103], v[48:63]
	ds_read_b64_tr_b16 v[178:179], v177 offset:41984
	ds_read_b64_tr_b16 v[180:181], v177 offset:42496
	v_exp_f32_e32 v116, v116
	v_exp_f32_e32 v117, v117
	ds_read_b128 v[164:167], v235 offset:8192
	ds_read_b128 v[140:143], v235 offset:12288
	v_mfma_f32_32x32x16_bf16 v[32:47], v[152:155], v[104:107], v[32:47]
	ds_read_b64_tr_b16 v[100:101], v177 offset:46080
	ds_read_b64_tr_b16 v[102:103], v177 offset:46592
	v_exp_f32_e32 v118, v118
	v_exp_f32_e32 v119, v119
	ds_read_b128 v[160:163], v236 offset:8192
	ds_read_b128 v[132:135], v236 offset:12288
	v_mfma_f32_32x32x16_bf16 v[48:63], v[148:151], v[108:111], v[48:63]
	ds_read_b64_tr_b16 v[104:105], v177 offset:43008
	ds_read_b64_tr_b16 v[106:107], v177 offset:43520
	v_exp_f32_e32 v120, v120
	v_exp_f32_e32 v121, v121
	ds_read_b128 v[136:139], v237 offset:8192
	ds_read_b128 v[128:131], v237 offset:12288
	v_mfma_f32_32x32x16_bf16 v[32:47], v[148:151], v[190:193], v[32:47]
	ds_read_b64_tr_b16 v[108:109], v177 offset:47104
	ds_read_b64_tr_b16 v[110:111], v177 offset:47616
	v_exp_f32_e32 v122, v122
	v_exp_f32_e32 v123, v123
	v_mfma_f32_32x32x16_bf16 v[48:63], v[144:147], v[84:87], v[48:63]
	ds_read_b64_tr_b16 v[190:191], v177 offset:44032
	ds_read_b64_tr_b16 v[192:193], v177 offset:44544
	v_exp_f32_e32 v124, v124
	v_exp_f32_e32 v125, v125
	v_mfma_f32_32x32x16_bf16 v[32:47], v[144:147], v[88:91], v[32:47]
	ds_read_b64_tr_b16 v[84:85], v177 offset:48128
	ds_read_b64_tr_b16 v[86:87], v177 offset:48640
	v_exp_f32_e32 v126, v126
	v_exp_f32_e32 v127, v127
	s_waitcnt lgkmcnt(14)
	v_mfma_f32_32x32x16_bf16 v[16:31], v[156:159], v[92:95], v[16:31]
	v_exp_f32_e32 v64, v64
	v_exp_f32_e32 v65, v65
	v_mfma_f32_32x32x16_bf16 v[0:15], v[156:159], v[170:173], v[0:15]
	v_exp_f32_e32 v66, v66
	v_exp_f32_e32 v67, v67
	v_mfma_f32_32x32x16_bf16 v[16:31], v[152:155], v[178:181], v[16:31]
	v_exp_f32_e32 v68, v68
	v_exp_f32_e32 v69, v69
	s_waitcnt lgkmcnt(12)
	v_mfma_f32_32x32x16_bf16 v[0:15], v[152:155], v[100:103], v[0:15]
	v_exp_f32_e32 v70, v70
	v_exp_f32_e32 v71, v71
	s_waitcnt lgkmcnt(8)
	v_mfma_f32_32x32x16_bf16 v[16:31], v[148:151], v[104:107], v[16:31]
	v_exp_f32_e32 v72, v72
	v_exp_f32_e32 v73, v73
	s_waitcnt lgkmcnt(4)
	v_mfma_f32_32x32x16_bf16 v[0:15], v[148:151], v[108:111], v[0:15]
	v_exp_f32_e32 v74, v74
	v_exp_f32_e32 v75, v75
	s_waitcnt lgkmcnt(2)
	v_mfma_f32_32x32x16_bf16 v[16:31], v[144:147], v[190:193], v[16:31]
	v_exp_f32_e32 v76, v76
	v_exp_f32_e32 v77, v77
	s_waitcnt lgkmcnt(0)
	v_mfma_f32_32x32x16_bf16 v[0:15], v[144:147], v[84:87], v[0:15]
	v_exp_f32_e32 v78, v78
	v_exp_f32_e32 v79, v79
	s_waitcnt vmcnt(0) lgkmcnt(0)
	s_barrier
;   #define RESC() do{ if(!NOMAX&&resc){ asm volatile("s_waitcnt lgkmcnt(0)":::"memory"); \
;       _Pragma("unroll") for(int d_=0;d_<2*VM;++d_) _Pragma("unroll") for(int r=0;r<16;++r)o[d_][r]*=wsf[crow(r,hi)]; } }while(0)
; template<int THRL,int VM,bool NOMAX> __device__ __forceinline__ void attn_unit(const bf16*Qb,const bf16*__restrict__ Kh,const bf16*__restrict__ Vh,bf16*Ob,const int NT,const int sp,float*wscr,char*shm){
;     ...
;   STEP(pB0,pB1,pA0,pA1,NT-1,false,false,false); RESC();
	ds_read_b64_tr_b16 v[170:171], v168 offset:24576
	ds_read_b64_tr_b16 v[172:173], v168 offset:25088
	v_add_f32_e32 v88, v112, v113
	ds_read_b128 v[84:87], v188
	v_add_f32_e32 v88, v114, v88
	v_add_f32_e32 v88, v115, v88
	v_add_f32_e32 v88, v116, v88
	v_add_f32_e32 v104, v117, v88
	v_cvt_pk_bf16_f32 v156, v112, v113
	v_cvt_pk_bf16_f32 v157, v114, v115
	s_waitcnt lgkmcnt(0)
	v_mfma_f32_32x32x16_bf16 v[80:95], v[80:83], v[84:87], 0
	ds_read_b64_tr_b16 v[112:113], v168 offset:28672
	ds_read_b64_tr_b16 v[114:115], v168 offset:29184
	ds_read_b128 v[100:103], v188
	v_add_f32_e32 v104, v118, v104
	v_add_f32_e32 v104, v119, v104
	v_add_f32_e32 v104, v120, v104
	v_add_f32_e32 v144, v121, v104
	v_cvt_pk_bf16_f32 v158, v116, v117
	v_cvt_pk_bf16_f32 v159, v118, v119
	s_waitcnt lgkmcnt(0)
	v_mfma_f32_32x32x16_bf16 v[96:111], v[96:99], v[100:103], 0
	ds_read_b64_tr_b16 v[116:117], v168 offset:25600
	ds_read_b64_tr_b16 v[118:119], v168 offset:26112
	ds_read_b128 v[178:181], v188 offset:1024
	v_add_f32_e32 v144, v122, v144
	v_add_f32_e32 v144, v123, v144
	v_add_f32_e32 v144, v124, v144
	v_add_f32_e32 v144, v125, v144
	v_cvt_pk_bf16_f32 v152, v120, v121
	v_cvt_pk_bf16_f32 v153, v122, v123
	s_waitcnt lgkmcnt(0)
	v_mfma_f32_32x32x16_bf16 v[80:95], v[164:167], v[178:181], v[80:95]
	ds_read_b64_tr_b16 v[120:121], v168 offset:29696
	ds_read_b64_tr_b16 v[122:123], v168 offset:30208
	ds_read_b128 v[164:167], v188 offset:1024
	v_add_f32_e32 v144, v126, v144
	v_add_f32_e32 v144, v127, v144
	v_add_f32_e32 v144, v64, v144
	v_add_f32_e32 v144, v65, v144
	v_cvt_pk_bf16_f32 v154, v124, v125
	v_cvt_pk_bf16_f32 v155, v126, v127
	s_waitcnt lgkmcnt(0)
	v_mfma_f32_32x32x16_bf16 v[96:111], v[140:143], v[164:167], v[96:111]
	ds_read_b64_tr_b16 v[124:125], v168 offset:26624
	ds_read_b64_tr_b16 v[126:127], v168 offset:27136
	ds_read_b128 v[140:143], v188 offset:2048
	v_add_f32_e32 v144, v66, v144
	v_add_f32_e32 v144, v67, v144
	v_add_f32_e32 v144, v68, v144
	v_add_f32_e32 v144, v69, v144
	v_cvt_pk_bf16_f32 v148, v64, v65
	v_cvt_pk_bf16_f32 v149, v66, v67
	s_waitcnt lgkmcnt(0)
	v_mfma_f32_32x32x16_bf16 v[80:95], v[160:163], v[140:143], v[80:95]
	ds_read_b64_tr_b16 v[64:65], v168 offset:30720
	ds_read_b64_tr_b16 v[66:67], v168 offset:31232
	ds_read_b128 v[140:143], v188 offset:2048
	v_add_f32_e32 v144, v70, v144
	v_add_f32_e32 v144, v71, v144
	v_add_f32_e32 v144, v72, v144
	v_add_f32_e32 v144, v73, v144
	v_cvt_pk_bf16_f32 v150, v68, v69
	v_cvt_pk_bf16_f32 v151, v70, v71
	s_waitcnt lgkmcnt(0)
	v_mfma_f32_32x32x16_bf16 v[96:111], v[132:135], v[140:143], v[96:111]
	ds_read_b64_tr_b16 v[68:69], v168 offset:27648
	ds_read_b64_tr_b16 v[70:71], v168 offset:28160
	ds_read_b128 v[132:135], v188 offset:3072
	v_add_f32_e32 v140, v74, v144
	v_add_f32_e32 v140, v75, v140
	v_add_f32_e32 v140, v76, v140
	v_add_f32_e32 v140, v77, v140
	v_cvt_pk_bf16_f32 v144, v72, v73
	v_cvt_pk_bf16_f32 v145, v74, v75
	s_waitcnt lgkmcnt(0)
	v_mfma_f32_32x32x16_bf16 v[80:95], v[136:139], v[132:135], v[80:95]
	ds_read_b64_tr_b16 v[72:73], v168 offset:31744
	ds_read_b64_tr_b16 v[74:75], v168 offset:32256
	ds_read_b128 v[132:135], v188 offset:3072
	v_add_f32_e32 v136, v78, v140
	v_add_f32_e32 v136, v79, v136
	v_add_f32_e32 v136, 0, v136
	v_cvt_pk_bf16_f32 v146, v76, v77
	v_cvt_pk_bf16_f32 v147, v78, v79
	s_waitcnt lgkmcnt(0)
	v_mfma_f32_32x32x16_bf16 v[96:111], v[128:131], v[132:135], v[96:111]
	v_mfma_f32_32x32x16_bf16 v[48:63], v[156:159], v[170:173], v[48:63]
	ds_read_b64_tr_b16 v[76:77], v168 offset:32768
	ds_read_b64_tr_b16 v[78:79], v168 offset:33280
	v_exp_f32_e32 v80, v80
	v_exp_f32_e32 v81, v81
	v_mfma_f32_32x32x16_bf16 v[32:47], v[156:159], v[112:115], v[32:47]
	ds_read_b64_tr_b16 v[128:129], v168 offset:36864
	ds_read_b64_tr_b16 v[130:131], v168 offset:37376
	v_exp_f32_e32 v82, v82
	v_exp_f32_e32 v83, v83
	v_mfma_f32_32x32x16_bf16 v[48:63], v[152:155], v[116:119], v[48:63]
	ds_read_b64_tr_b16 v[112:113], v168 offset:33792
	ds_read_b64_tr_b16 v[114:115], v168 offset:34304
	v_exp_f32_e32 v84, v84
	v_exp_f32_e32 v85, v85
	v_mfma_f32_32x32x16_bf16 v[32:47], v[152:155], v[120:123], v[32:47]
	ds_read_b64_tr_b16 v[116:117], v168 offset:37888
	ds_read_b64_tr_b16 v[118:119], v168 offset:38400
	v_exp_f32_e32 v86, v86
	v_exp_f32_e32 v87, v87
	v_mfma_f32_32x32x16_bf16 v[48:63], v[148:151], v[124:127], v[48:63]
	ds_read_b64_tr_b16 v[120:121], v168 offset:34816
	ds_read_b64_tr_b16 v[122:123], v168 offset:35328
	v_exp_f32_e32 v88, v88
	v_exp_f32_e32 v89, v89
	v_mfma_f32_32x32x16_bf16 v[32:47], v[148:151], v[64:67], v[32:47]
	ds_read_b64_tr_b16 v[124:125], v168 offset:38912
	ds_read_b64_tr_b16 v[126:127], v168 offset:39424
	v_exp_f32_e32 v90, v90
	v_exp_f32_e32 v91, v91
	v_mfma_f32_32x32x16_bf16 v[48:63], v[144:147], v[68:71], v[48:63]
	ds_read_b64_tr_b16 v[64:65], v168 offset:35840
	ds_read_b64_tr_b16 v[66:67], v168 offset:36352
	v_exp_f32_e32 v92, v92
	v_exp_f32_e32 v93, v93
	v_mfma_f32_32x32x16_bf16 v[32:47], v[144:147], v[72:75], v[32:47]
	ds_read_b64_tr_b16 v[68:69], v168 offset:39936
	ds_read_b64_tr_b16 v[70:71], v168 offset:40448
	v_exp_f32_e32 v94, v94
	v_exp_f32_e32 v95, v95
	s_waitcnt lgkmcnt(14)
	v_mfma_f32_32x32x16_bf16 v[16:31], v[156:159], v[76:79], v[16:31]
	v_exp_f32_e32 v96, v96
	v_exp_f32_e32 v97, v97
	s_waitcnt lgkmcnt(12)
; #define SBAR() __builtin_amdgcn_sched_barrier(0)
;   #define RESC() do{ if(!NOMAX&&resc){ asm volatile("s_waitcnt lgkmcnt(0)":::"memory"); \
;       _Pragma("unroll") for(int d_=0;d_<2*VM;++d_) _Pragma("unroll") for(int r=0;r<16;++r)o[d_][r]*=wsf[crow(r,hi)]; } }while(0)
;   #define PKW(P,B) cvtpk_s(P[B],P[B+1])
; template<int THRL,int VM,bool NOMAX> __device__ __forceinline__ void attn_unit(const bf16*Qb,const bf16*__restrict__ Kh,const bf16*__restrict__ Vh,bf16*Ob,const int NT,const int sp,float*wscr,char*shm){
;     ...
;   STEP(pB0,pB1,pA0,pA1,NT-1,false,false,false); RESC();
;   { float sacc=pB0[0]+pB0[1]; _Pragma("unroll") for(int r=2;r<16;++r)sacc+=pB0[r]; _Pragma("unroll") for(int r=0;r<16;++r)sacc+=pB1[r]; l_reg+=sacc;
;     pw0=(u32x4){PKW(pB0,0),PKW(pB0,2),PKW(pB0,4),PKW(pB0,6)};pw1=(u32x4){PKW(pB0,8),PKW(pB0,10),PKW(pB0,12),PKW(pB0,14)};pw2=(u32x4){PKW(pB1,0),PKW(pB1,2),PKW(pB1,4),PKW(pB1,6)};pw3=(u32x4){PKW(pB1,8),PKW(pB1,10),PKW(pB1,12),PKW(pB1,14)};
;     SBAR(); pv(o,vb0+VM*sl_cur,PAF(0),PAF(1),PAF(2),PAF(3)); if constexpr(VM==2) pv(o+2,vb0+VM*sl_cur+8192,PAF(0),PAF(1),PAF(2),PAF(3)); }
;     ...
;   {auto rr=__builtin_amdgcn_permlane32_swap(__float_as_uint(l_reg),__float_as_uint(l_reg),false,false);l_reg=__uint_as_float(rr[0])+__uint_as_float(rr[1]);}
;   if(hi==0)wsf[32+r32]=l_reg;asm volatile("s_waitcnt lgkmcnt(0)":::"memory");
	v_mfma_f32_32x32x16_bf16 v[0:15], v[156:159], v[128:131], v[0:15]
	v_exp_f32_e32 v98, v98
	v_exp_f32_e32 v99, v99
	s_waitcnt lgkmcnt(10)
	v_mfma_f32_32x32x16_bf16 v[16:31], v[152:155], v[112:115], v[16:31]
	v_exp_f32_e32 v100, v100
	v_exp_f32_e32 v101, v101
	s_waitcnt lgkmcnt(8)
	v_mfma_f32_32x32x16_bf16 v[0:15], v[152:155], v[116:119], v[0:15]
	v_exp_f32_e32 v102, v102
	v_exp_f32_e32 v103, v103
	s_waitcnt lgkmcnt(6)
	v_mfma_f32_32x32x16_bf16 v[16:31], v[148:151], v[120:123], v[16:31]
	v_exp_f32_e32 v104, v104
	v_exp_f32_e32 v105, v105
	s_waitcnt lgkmcnt(4)
	v_mfma_f32_32x32x16_bf16 v[0:15], v[148:151], v[124:127], v[0:15]
	v_exp_f32_e32 v106, v106
	v_exp_f32_e32 v107, v107
	s_waitcnt lgkmcnt(2)
	v_mfma_f32_32x32x16_bf16 v[16:31], v[144:147], v[64:67], v[16:31]
	v_exp_f32_e32 v108, v108
	v_exp_f32_e32 v109, v109
	s_waitcnt lgkmcnt(0)
	v_mfma_f32_32x32x16_bf16 v[0:15], v[144:147], v[68:71], v[0:15]
	v_exp_f32_e32 v110, v110
	v_exp_f32_e32 v111, v111
	v_add_f32_e32 v64, v80, v81
	v_add_f32_e32 v64, v82, v64
	v_add_f32_e32 v64, v83, v64
	v_add_f32_e32 v64, v84, v64
	v_add_f32_e32 v64, v85, v64
	v_add_f32_e32 v64, v86, v64
	v_add_f32_e32 v64, v87, v64
	v_add_f32_e32 v64, v88, v64
	v_add_f32_e32 v64, v89, v64
	v_add_f32_e32 v64, v90, v64
	v_add_f32_e32 v64, v91, v64
	v_add_f32_e32 v64, v92, v64
	v_add_f32_e32 v64, v93, v64
	v_add_f32_e32 v64, v94, v64
	v_add_f32_e32 v64, v95, v64
	v_add_f32_e32 v64, v64, v96
	v_add_f32_e32 v64, v97, v64
	v_add_f32_e32 v64, v98, v64
	v_add_f32_e32 v64, v99, v64
	v_add_f32_e32 v64, v100, v64
	v_add_f32_e32 v64, v101, v64
	v_add_f32_e32 v64, v102, v64
	v_add_f32_e32 v64, v103, v64
	v_add_f32_e32 v64, v104, v64
	v_add_f32_e32 v64, v105, v64
	v_add_f32_e32 v64, v106, v64
	v_add_f32_e32 v64, v107, v64
	v_add_f32_e32 v64, v108, v64
	v_add_f32_e32 v64, v109, v64
	v_add_f32_e32 v64, v110, v64
	v_add_f32_e32 v64, v111, v64
	v_add_f32_e32 v65, v174, v136
	v_add_f32_e32 v64, v65, v64
	v_cvt_pk_bf16_f32 v66, v80, v81
	v_cvt_pk_bf16_f32 v67, v82, v83
	v_cvt_pk_bf16_f32 v68, v84, v85
	v_cvt_pk_bf16_f32 v69, v86, v87
	v_cvt_pk_bf16_f32 v70, v88, v89
	v_cvt_pk_bf16_f32 v71, v90, v91
	v_cvt_pk_bf16_f32 v72, v92, v93
	v_cvt_pk_bf16_f32 v73, v94, v95
	v_cvt_pk_bf16_f32 v74, v96, v97
	v_cvt_pk_bf16_f32 v75, v98, v99
	v_cvt_pk_bf16_f32 v76, v100, v101
	v_cvt_pk_bf16_f32 v77, v102, v103
	v_cvt_pk_bf16_f32 v78, v104, v105
	v_cvt_pk_bf16_f32 v79, v106, v107
	v_cvt_pk_bf16_f32 v80, v108, v109
	v_cvt_pk_bf16_f32 v81, v110, v111
	v_add_u32_e32 v65, 0x4000, v176
	ds_read_b64_tr_b16 v[82:83],v65 offset:0
	ds_read_b64_tr_b16 v[84:85],v65 offset:512
	ds_read_b64_tr_b16 v[86:87],v65 offset:1024
	ds_read_b64_tr_b16 v[88:89],v65 offset:1536
	ds_read_b64_tr_b16 v[90:91],v65 offset:2048
	ds_read_b64_tr_b16 v[92:93],v65 offset:2560
	ds_read_b64_tr_b16 v[94:95],v65 offset:3072
	ds_read_b64_tr_b16 v[96:97],v65 offset:3584
	s_waitcnt lgkmcnt(0)
	s_nop 0
	v_mfma_f32_32x32x16_bf16 v[48:63], v[66:69], v[82:85], v[48:63]
	ds_read_b64_tr_b16 v[82:83],v65 offset:4096
	ds_read_b64_tr_b16 v[84:85],v65 offset:4608
	v_mfma_f32_32x32x16_bf16 v[48:63], v[70:73], v[86:89], v[48:63]
	ds_read_b64_tr_b16 v[86:87],v65 offset:5120
	ds_read_b64_tr_b16 v[88:89],v65 offset:5632
	v_mfma_f32_32x32x16_bf16 v[48:63], v[74:77], v[90:93], v[48:63]
	ds_read_b64_tr_b16 v[90:91],v65 offset:6144
	ds_read_b64_tr_b16 v[92:93],v65 offset:6656
	ds_read_b64_tr_b16 v[98:99],v65 offset:7168
	ds_read_b64_tr_b16 v[100:101],v65 offset:7680
	s_waitcnt lgkmcnt(0)
	v_mfma_f32_32x32x16_bf16 v[48:63], v[78:81], v[94:97], v[48:63]
	v_mfma_f32_32x32x16_bf16 v[32:47], v[66:69], v[82:85], v[32:47]
	v_add_u32_e32 v65, 0x6000, v176
	ds_read_b64_tr_b16 v[82:83],v65 offset:0
	ds_read_b64_tr_b16 v[84:85],v65 offset:512
	v_mfma_f32_32x32x16_bf16 v[32:47], v[70:73], v[86:89], v[32:47]
	ds_read_b64_tr_b16 v[86:87],v65 offset:1024
	ds_read_b64_tr_b16 v[88:89],v65 offset:1536
	v_mfma_f32_32x32x16_bf16 v[32:47], v[74:77], v[90:93], v[32:47]
	ds_read_b64_tr_b16 v[90:91],v65 offset:2048
	ds_read_b64_tr_b16 v[92:93],v65 offset:2560
	ds_read_b64_tr_b16 v[94:95],v65 offset:3072
	ds_read_b64_tr_b16 v[96:97],v65 offset:3584
	s_waitcnt lgkmcnt(0)
	v_mfma_f32_32x32x16_bf16 v[32:47], v[78:81], v[98:101], v[32:47]
	v_mfma_f32_32x32x16_bf16 v[16:31], v[66:69], v[82:85], v[16:31]
	ds_read_b64_tr_b16 v[82:83],v65 offset:4096
	ds_read_b64_tr_b16 v[84:85],v65 offset:4608
	v_mfma_f32_32x32x16_bf16 v[16:31], v[70:73], v[86:89], v[16:31]
	ds_read_b64_tr_b16 v[86:87],v65 offset:5120
	ds_read_b64_tr_b16 v[88:89],v65 offset:5632
	v_mfma_f32_32x32x16_bf16 v[16:31], v[74:77], v[90:93], v[16:31]
	ds_read_b64_tr_b16 v[90:91],v65 offset:6144
	ds_read_b64_tr_b16 v[92:93],v65 offset:6656
	ds_read_b64_tr_b16 v[98:99],v65 offset:7168
	ds_read_b64_tr_b16 v[100:101],v65 offset:7680
	s_waitcnt lgkmcnt(0)
	v_mfma_f32_32x32x16_bf16 v[16:31], v[78:81], v[94:97], v[16:31]
	v_mfma_f32_32x32x16_bf16 v[0:15], v[66:69], v[82:85], v[0:15]
	v_mov_b32_e32 v65, v64
	s_nop 1
	v_permlane32_swap_b32_e32 v64, v65
	v_cmp_gt_u32_e32 vcc, 32, v187
	v_mfma_f32_32x32x16_bf16 v[0:15], v[70:73], v[86:89], v[0:15]
	v_mfma_f32_32x32x16_bf16 v[0:15], v[74:77], v[90:93], v[0:15]
	v_mfma_f32_32x32x16_bf16 v[0:15], v[78:81], v[98:101], v[0:15]
	s_and_saveexec_b64 s[16:17], vcc
	s_cbranch_execz .LBB0_859
	v_add_f32_e32 v64, v64, v65
	v_lshl_add_u32 v65, v186, 2, s34
	ds_write_b32 v65, v64 offset:128
	s_branch .LBB0_859

; #define WAIT_BAR(N) asm volatile("s_waitcnt vmcnt(" #N ") lgkmcnt(0)\n\ts_barrier":::"memory")
;   #define RESC() do{ if(!NOMAX&&resc){ asm volatile("s_waitcnt lgkmcnt(0)":::"memory"); \
;       _Pragma("unroll") for(int d_=0;d_<2*VM;++d_) _Pragma("unroll") for(int r=0;r<16;++r)o[d_][r]*=wsf[crow(r,hi)]; } }while(0)
;   #define ROT() do{sl_prev=sl_cur;sl_cur=sl_next;sl_next=(sl_next==(NSLOT-1)*SLOTB)?0:sl_next+SLOTB;}while(0)
; template<int THRL,int VM,bool NOMAX> __device__ __forceinline__ void attn_unit(const bf16*Qb,const bf16*__restrict__ Kh,const bf16*__restrict__ Vh,bf16*Ob,const int NT,const int sp,float*wscr,char*shm){
;     ...
;   int t=1;
;   for(;t+5<NT;t+=2){
;     STEP(pB0,pB1,pA0,pA1,t,true,true,true);     if constexpr(VM==2){WAIT_BAR(3);}else{WAIT_BAR(2);} RESC(); ROT();
.LBB0_874:
	v_mfma_f32_32x32x16_bf16 v[112:127], v[100:103], v[218:221], 0
	v_lshl_add_u32 v206, s89, 1, v188
	ds_read_b64_tr_b16 v[194:195], v206 offset:24576
	ds_read_b64_tr_b16 v[196:197], v206 offset:25088
	v_add_f32_e32 v108, v80, v81
	v_add_f32_e32 v108, v82, v108
	v_add_f32_e32 v108, v83, v108
	v_add_f32_e32 v108, v84, v108
	v_add_f32_e32 v108, v85, v108
	v_cvt_pk_bf16_f32 v156, v80, v81
	v_cvt_pk_bf16_f32 v157, v82, v83
	ds_read_b64_tr_b16 v[80:81], v206 offset:28672
	ds_read_b64_tr_b16 v[82:83], v206 offset:29184
	v_add_f32_e32 v104, v86, v108
	v_add_f32_e32 v104, v87, v104
	v_add_f32_e32 v104, v88, v104
	v_add_f32_e32 v144, v89, v104
	v_mfma_f32_32x32x16_bf16 v[96:111], v[96:99], v[218:221], 0
	v_cvt_pk_bf16_f32 v158, v84, v85
	v_cvt_pk_bf16_f32 v159, v86, v87
	ds_read_b64_tr_b16 v[84:85], v206 offset:25600
	ds_read_b64_tr_b16 v[86:87], v206 offset:26112
	v_add_f32_e32 v144, v90, v144
	v_add_f32_e32 v144, v91, v144
	v_add_f32_e32 v144, v92, v144
	v_add_f32_e32 v144, v93, v144
	v_cvt_pk_bf16_f32 v152, v88, v89
	v_cvt_pk_bf16_f32 v153, v90, v91
	v_mfma_f32_32x32x16_bf16 v[112:127], v[164:167], v[222:225], v[112:127]
	ds_read_b64_tr_b16 v[88:89], v206 offset:29696
	ds_read_b64_tr_b16 v[90:91], v206 offset:30208
	v_add_f32_e32 v144, v94, v144
	v_add_f32_e32 v144, v95, v144
	v_add_f32_e32 v144, v64, v144
	v_add_f32_e32 v144, v65, v144
	v_mfma_f32_32x32x16_bf16 v[96:111], v[160:163], v[222:225], v[96:111]
	v_cvt_pk_bf16_f32 v154, v92, v93
	v_cvt_pk_bf16_f32 v155, v94, v95
	ds_read_b64_tr_b16 v[92:93], v206 offset:26624
	ds_read_b64_tr_b16 v[94:95], v206 offset:27136
	v_add_f32_e32 v144, v66, v144
	v_add_f32_e32 v144, v67, v144
	v_add_f32_e32 v144, v68, v144
	v_add_f32_e32 v144, v69, v144
	v_cvt_pk_bf16_f32 v148, v64, v65
	v_cvt_pk_bf16_f32 v149, v66, v67
	v_mfma_f32_32x32x16_bf16 v[112:127], v[140:143], v[226:229], v[112:127]
	ds_read_b64_tr_b16 v[198:199], v206 offset:30720
	ds_read_b64_tr_b16 v[200:201], v206 offset:31232
	v_add_f32_e32 v140, v70, v144
	v_add_f32_e32 v140, v71, v140
	v_add_f32_e32 v140, v72, v140
	v_add_f32_e32 v140, v73, v140
	v_mfma_f32_32x32x16_bf16 v[96:111], v[136:139], v[226:229], v[96:111]
	v_cvt_pk_bf16_f32 v150, v68, v69
	v_cvt_pk_bf16_f32 v151, v70, v71
	ds_read_b64_tr_b16 v[202:203], v206 offset:27648
	ds_read_b64_tr_b16 v[204:205], v206 offset:28160
	v_add_f32_e32 v68, v74, v140
	v_add_f32_e32 v68, v75, v68
	v_add_f32_e32 v68, v76, v68
	v_add_f32_e32 v68, v77, v68
	v_cvt_pk_bf16_f32 v144, v72, v73
	v_cvt_pk_bf16_f32 v145, v74, v75
	v_mfma_f32_32x32x16_bf16 v[112:127], v[132:135], v[230:233], v[112:127]
	ds_read_b64_tr_b16 v[72:73], v206 offset:31744
	ds_read_b64_tr_b16 v[74:75], v206 offset:32256
	v_add_f32_e32 v68, v78, v68
	v_add_f32_e32 v68, v79, v68
	v_cvt_pk_bf16_f32 v146, v76, v77
	v_mfma_f32_32x32x16_bf16 v[96:111], v[128:131], v[230:233], v[96:111]
	v_cvt_pk_bf16_f32 v147, v78, v79
	s_add_i32 m0, s87, s17
	v_lshl_add_u64 v[64:65], v[180:181], 0, s[56:57]
	global_load_lds_dwordx4 v[64:65], off
	s_lshl_b32 s88, s86, 1
	s_add_i32 s88, s88, s16
	s_mov_b32 m0, s88
	v_lshl_add_u64 v[64:65], v[178:179], 0, s[56:57]
	global_load_lds_dwordx4 v[64:65], off
	s_addk_i32 m0, 0x2000
	v_lshl_add_u64 v[64:65], v[176:177], 0, s[56:57]
	global_load_lds_dwordx4 v[64:65], off
	v_add_f32_e32 v193, v193, v68
	v_add_u32_e32 v242, s86, v234
	v_add_u32_e32 v243, s86, v235
	v_add_u32_e32 v244, s86, v236
	v_add_u32_e32 v245, s86, v237
	s_waitcnt lgkmcnt(12)
	v_mfma_f32_32x32x16_bf16 v[48:63], v[156:159], v[194:197], v[48:63]
	ds_read_b64_tr_b16 v[76:77], v206 offset:32768
	ds_read_b64_tr_b16 v[78:79], v206 offset:33280
	v_exp_f32_e32 v112, v112
	v_exp_f32_e32 v113, v113
	ds_read_b128 v[68:71], v242
	v_mfma_f32_32x32x16_bf16 v[32:47], v[156:159], v[80:83], v[32:47]
	ds_read_b64_tr_b16 v[194:195], v206 offset:36864
	ds_read_b64_tr_b16 v[196:197], v206 offset:37376
	v_exp_f32_e32 v114, v114
	v_exp_f32_e32 v115, v115
	ds_read_b128 v[64:67], v242 offset:4096
	s_waitcnt lgkmcnt(14)
	v_mfma_f32_32x32x16_bf16 v[48:63], v[152:155], v[84:87], v[48:63]
	ds_read_b64_tr_b16 v[80:81], v206 offset:33792
	ds_read_b64_tr_b16 v[82:83], v206 offset:34304
	v_exp_f32_e32 v116, v116
	v_exp_f32_e32 v117, v117
	ds_read_b128 v[164:167], v243
	v_mfma_f32_32x32x16_bf16 v[32:47], v[152:155], v[88:91], v[32:47]
	ds_read_b64_tr_b16 v[84:85], v206 offset:37888
	ds_read_b64_tr_b16 v[86:87], v206 offset:38400
	v_exp_f32_e32 v118, v118
	v_exp_f32_e32 v119, v119
	ds_read_b128 v[140:143], v243 offset:4096
	s_waitcnt lgkmcnt(14)
	v_mfma_f32_32x32x16_bf16 v[48:63], v[148:151], v[92:95], v[48:63]
	ds_read_b64_tr_b16 v[88:89], v206 offset:34816
	ds_read_b64_tr_b16 v[90:91], v206 offset:35328
	v_exp_f32_e32 v120, v120
	v_exp_f32_e32 v121, v121
	ds_read_b128 v[160:163], v244
	v_mfma_f32_32x32x16_bf16 v[32:47], v[148:151], v[198:201], v[32:47]
	ds_read_b64_tr_b16 v[92:93], v206 offset:38912
	ds_read_b64_tr_b16 v[94:95], v206 offset:39424
	v_exp_f32_e32 v122, v122
	v_exp_f32_e32 v123, v123
	ds_read_b128 v[132:135], v244 offset:4096
	s_waitcnt lgkmcnt(14)
	v_mfma_f32_32x32x16_bf16 v[48:63], v[144:147], v[202:205], v[48:63]
	ds_read_b64_tr_b16 v[198:199], v206 offset:35840
	ds_read_b64_tr_b16 v[200:201], v206 offset:36352
	v_exp_f32_e32 v124, v124
	v_exp_f32_e32 v125, v125
	ds_read_b128 v[136:139], v245
	v_mfma_f32_32x32x16_bf16 v[32:47], v[144:147], v[72:75], v[32:47]
	ds_read_b64_tr_b16 v[202:203], v206 offset:39936
	ds_read_b64_tr_b16 v[204:205], v206 offset:40448
	v_exp_f32_e32 v126, v126
	v_exp_f32_e32 v127, v127
	ds_read_b128 v[128:131], v245 offset:4096
	s_waitcnt lgkmcnt(14)
	v_mfma_f32_32x32x16_bf16 v[16:31], v[156:159], v[76:79], v[16:31]
	v_exp_f32_e32 v96, v96
	v_exp_f32_e32 v97, v97
	v_mfma_f32_32x32x16_bf16 v[0:15], v[156:159], v[194:197], v[0:15]
	v_exp_f32_e32 v98, v98
	v_exp_f32_e32 v99, v99
	v_mfma_f32_32x32x16_bf16 v[16:31], v[152:155], v[80:83], v[16:31]
	v_exp_f32_e32 v100, v100
	v_exp_f32_e32 v101, v101
	s_waitcnt lgkmcnt(12)
	v_mfma_f32_32x32x16_bf16 v[0:15], v[152:155], v[84:87], v[0:15]
	v_exp_f32_e32 v102, v102
	v_exp_f32_e32 v103, v103
	s_waitcnt lgkmcnt(8)
	v_mfma_f32_32x32x16_bf16 v[16:31], v[148:151], v[88:91], v[16:31]
	v_exp_f32_e32 v104, v104
	v_exp_f32_e32 v105, v105
	s_waitcnt lgkmcnt(4)
	v_mfma_f32_32x32x16_bf16 v[0:15], v[148:151], v[92:95], v[0:15]
	v_exp_f32_e32 v106, v106
	v_exp_f32_e32 v107, v107
	s_waitcnt lgkmcnt(2)
	v_mfma_f32_32x32x16_bf16 v[16:31], v[144:147], v[198:201], v[16:31]
	v_exp_f32_e32 v108, v108
	v_exp_f32_e32 v109, v109
	s_waitcnt lgkmcnt(0)
	v_mfma_f32_32x32x16_bf16 v[0:15], v[144:147], v[202:205], v[0:15]
	v_exp_f32_e32 v110, v110
	v_exp_f32_e32 v111, v111
	s_waitcnt vmcnt(3) lgkmcnt(0)
	s_barrier
; #define WAIT_BAR(N) asm volatile("s_waitcnt vmcnt(" #N ") lgkmcnt(0)\n\ts_barrier":::"memory")
;   #define RESC() do{ if(!NOMAX&&resc){ asm volatile("s_waitcnt lgkmcnt(0)":::"memory"); \
;       _Pragma("unroll") for(int d_=0;d_<2*VM;++d_) _Pragma("unroll") for(int r=0;r<16;++r)o[d_][r]*=wsf[crow(r,hi)]; } }while(0)
;   #define ROT() do{sl_prev=sl_cur;sl_cur=sl_next;sl_next=(sl_next==(NSLOT-1)*SLOTB)?0:sl_next+SLOTB;}while(0)
; template<int THRL,int VM,bool NOMAX> __device__ __forceinline__ void attn_unit(const bf16*Qb,const bf16*__restrict__ Kh,const bf16*__restrict__ Vh,bf16*Ob,const int NT,const int sp,float*wscr,char*shm){
;     ...
;   int t=1;
;   for(;t+5<NT;t+=2){
;     STEP(pB0,pB1,pA0,pA1,t,true,true,true);     if constexpr(VM==2){WAIT_BAR(3);}else{WAIT_BAR(2);} RESC(); ROT();
;     STEP(pA0,pA1,pB0,pB1,t+1,true,true,true);   if constexpr(VM==2){WAIT_BAR(3);}else{WAIT_BAR(2);} RESC(); ROT();
	v_mfma_f32_32x32x16_bf16 v[80:95], v[68:71], v[218:221], 0
	s_add_i32 s88, s86, 0x2000
	s_cmpk_lg_i32 s86, 0x4000
	s_cselect_b32 s88, s88, 0
	v_lshl_add_u32 v206, s87, 1, v188
	ds_read_b64_tr_b16 v[194:195], v206 offset:24576
	ds_read_b64_tr_b16 v[196:197], v206 offset:25088
	v_add_f32_e32 v76, v112, v113
	v_add_f32_e32 v76, v114, v76
	v_add_f32_e32 v76, v115, v76
	v_add_f32_e32 v76, v116, v76
	v_add_f32_e32 v76, v117, v76
	v_cvt_pk_bf16_f32 v156, v112, v113
	v_cvt_pk_bf16_f32 v157, v114, v115
	ds_read_b64_tr_b16 v[112:113], v206 offset:28672
	ds_read_b64_tr_b16 v[114:115], v206 offset:29184
	v_add_f32_e32 v72, v118, v76
	v_add_f32_e32 v72, v119, v72
	v_add_f32_e32 v72, v120, v72
	v_add_f32_e32 v144, v121, v72
	v_mfma_f32_32x32x16_bf16 v[64:79], v[64:67], v[218:221], 0
	v_cvt_pk_bf16_f32 v158, v116, v117
	v_cvt_pk_bf16_f32 v159, v118, v119
	ds_read_b64_tr_b16 v[116:117], v206 offset:25600
	ds_read_b64_tr_b16 v[118:119], v206 offset:26112
	v_add_f32_e32 v144, v122, v144
	v_add_f32_e32 v144, v123, v144
	v_add_f32_e32 v144, v124, v144
	v_add_f32_e32 v144, v125, v144
	v_mfma_f32_32x32x16_bf16 v[80:95], v[164:167], v[222:225], v[80:95]
	v_cvt_pk_bf16_f32 v152, v120, v121
	v_cvt_pk_bf16_f32 v153, v122, v123
	ds_read_b64_tr_b16 v[120:121], v206 offset:29696
	ds_read_b64_tr_b16 v[122:123], v206 offset:30208
	v_add_f32_e32 v144, v126, v144
	v_add_f32_e32 v144, v127, v144
	v_add_f32_e32 v144, v96, v144
	v_add_f32_e32 v144, v97, v144
	v_mfma_f32_32x32x16_bf16 v[64:79], v[140:143], v[222:225], v[64:79]
	v_cvt_pk_bf16_f32 v154, v124, v125
	v_cvt_pk_bf16_f32 v155, v126, v127
	ds_read_b64_tr_b16 v[124:125], v206 offset:26624
	ds_read_b64_tr_b16 v[126:127], v206 offset:27136
	v_add_f32_e32 v144, v98, v144
	v_add_f32_e32 v144, v99, v144
	v_add_f32_e32 v144, v100, v144
	v_add_f32_e32 v144, v101, v144
	v_mfma_f32_32x32x16_bf16 v[80:95], v[160:163], v[226:229], v[80:95]
	v_cvt_pk_bf16_f32 v148, v96, v97
	v_cvt_pk_bf16_f32 v149, v98, v99
	ds_read_b64_tr_b16 v[198:199], v206 offset:30720
	ds_read_b64_tr_b16 v[200:201], v206 offset:31232
	v_add_f32_e32 v140, v102, v144
	v_add_f32_e32 v140, v103, v140
	v_add_f32_e32 v140, v104, v140
	v_add_f32_e32 v140, v105, v140
	v_mfma_f32_32x32x16_bf16 v[64:79], v[132:135], v[226:229], v[64:79]
	v_cvt_pk_bf16_f32 v150, v100, v101
	v_cvt_pk_bf16_f32 v151, v102, v103
	ds_read_b64_tr_b16 v[202:203], v206 offset:27648
	ds_read_b64_tr_b16 v[204:205], v206 offset:28160
	v_add_f32_e32 v100, v106, v140
	v_add_f32_e32 v100, v107, v100
	v_add_f32_e32 v100, v108, v100
	v_add_f32_e32 v100, v109, v100
	v_mfma_f32_32x32x16_bf16 v[80:95], v[136:139], v[230:233], v[80:95]
	v_cvt_pk_bf16_f32 v144, v104, v105
	v_cvt_pk_bf16_f32 v145, v106, v107
	ds_read_b64_tr_b16 v[104:105], v206 offset:31744
	ds_read_b64_tr_b16 v[106:107], v206 offset:32256
	v_add_f32_e32 v100, v110, v100
	v_add_f32_e32 v100, v111, v100
	v_cvt_pk_bf16_f32 v146, v108, v109
	v_mfma_f32_32x32x16_bf16 v[64:79], v[128:131], v[230:233], v[64:79]
	v_cvt_pk_bf16_f32 v147, v110, v111
	s_add_i32 m0, s86, s17
	s_nop 0
	global_load_lds_dwordx4 v[180:181], off
	s_lshl_b32 s87, s88, 1
	s_add_i32 s87, s87, s16
	s_mov_b32 m0, s87
	s_nop 0
	global_load_lds_dwordx4 v[178:179], off
	s_addk_i32 m0, 0x2000
	s_nop 0
	global_load_lds_dwordx4 v[176:177], off
	v_add_f32_e32 v193, v193, v100
	v_add_u32_e32 v242, s88, v234
	v_add_u32_e32 v243, s88, v235
	v_add_u32_e32 v244, s88, v236
	v_add_u32_e32 v245, s88, v237
	s_waitcnt lgkmcnt(12)
	v_mfma_f32_32x32x16_bf16 v[48:63], v[156:159], v[194:197], v[48:63]
	ds_read_b64_tr_b16 v[108:109], v206 offset:32768
	ds_read_b64_tr_b16 v[110:111], v206 offset:33280
	v_exp_f32_e32 v80, v80
	v_exp_f32_e32 v81, v81
	ds_read_b128 v[100:103], v242
	v_mfma_f32_32x32x16_bf16 v[32:47], v[156:159], v[112:115], v[32:47]
	ds_read_b64_tr_b16 v[194:195], v206 offset:36864
	ds_read_b64_tr_b16 v[196:197], v206 offset:37376
	v_exp_f32_e32 v82, v82
	v_exp_f32_e32 v83, v83
	ds_read_b128 v[96:99], v242 offset:4096
	s_waitcnt lgkmcnt(14)
	v_mfma_f32_32x32x16_bf16 v[48:63], v[152:155], v[116:119], v[48:63]
	ds_read_b64_tr_b16 v[112:113], v206 offset:33792
	ds_read_b64_tr_b16 v[114:115], v206 offset:34304
	v_exp_f32_e32 v84, v84
	v_exp_f32_e32 v85, v85
	ds_read_b128 v[164:167], v243
	v_mfma_f32_32x32x16_bf16 v[32:47], v[152:155], v[120:123], v[32:47]
	ds_read_b64_tr_b16 v[116:117], v206 offset:37888
	ds_read_b64_tr_b16 v[118:119], v206 offset:38400
	v_exp_f32_e32 v86, v86
	v_exp_f32_e32 v87, v87
	ds_read_b128 v[160:163], v243 offset:4096
	s_waitcnt lgkmcnt(14)
	v_mfma_f32_32x32x16_bf16 v[48:63], v[148:151], v[124:127], v[48:63]
	ds_read_b64_tr_b16 v[120:121], v206 offset:34816
	ds_read_b64_tr_b16 v[122:123], v206 offset:35328
	v_exp_f32_e32 v88, v88
	v_exp_f32_e32 v89, v89
	ds_read_b128 v[140:143], v244
	v_mfma_f32_32x32x16_bf16 v[32:47], v[148:151], v[198:201], v[32:47]
	ds_read_b64_tr_b16 v[124:125], v206 offset:38912
	ds_read_b64_tr_b16 v[126:127], v206 offset:39424
	v_exp_f32_e32 v90, v90
	v_exp_f32_e32 v91, v91
	ds_read_b128 v[136:139], v244 offset:4096
	s_waitcnt lgkmcnt(14)
	v_mfma_f32_32x32x16_bf16 v[48:63], v[144:147], v[202:205], v[48:63]
	ds_read_b64_tr_b16 v[198:199], v206 offset:35840
	ds_read_b64_tr_b16 v[200:201], v206 offset:36352
	v_exp_f32_e32 v92, v92
	v_exp_f32_e32 v93, v93
	ds_read_b128 v[132:135], v245
	v_mfma_f32_32x32x16_bf16 v[32:47], v[144:147], v[104:107], v[32:47]
	ds_read_b64_tr_b16 v[202:203], v206 offset:39936
	ds_read_b64_tr_b16 v[204:205], v206 offset:40448
	v_exp_f32_e32 v94, v94
	v_exp_f32_e32 v95, v95
	ds_read_b128 v[128:131], v245 offset:4096
	s_waitcnt lgkmcnt(14)
	v_mfma_f32_32x32x16_bf16 v[16:31], v[156:159], v[108:111], v[16:31]
	v_exp_f32_e32 v64, v64
	v_exp_f32_e32 v65, v65
	v_mfma_f32_32x32x16_bf16 v[0:15], v[156:159], v[194:197], v[0:15]
	v_exp_f32_e32 v66, v66
	v_exp_f32_e32 v67, v67
	v_mfma_f32_32x32x16_bf16 v[16:31], v[152:155], v[112:115], v[16:31]
	v_exp_f32_e32 v68, v68
	v_exp_f32_e32 v69, v69
	s_waitcnt lgkmcnt(12)
	v_mfma_f32_32x32x16_bf16 v[0:15], v[152:155], v[116:119], v[0:15]
	v_exp_f32_e32 v70, v70
	v_exp_f32_e32 v71, v71
	s_waitcnt lgkmcnt(8)
	v_mfma_f32_32x32x16_bf16 v[16:31], v[148:151], v[120:123], v[16:31]
	v_exp_f32_e32 v72, v72
	v_exp_f32_e32 v73, v73
	s_waitcnt lgkmcnt(4)
	v_mfma_f32_32x32x16_bf16 v[0:15], v[148:151], v[124:127], v[0:15]
	v_exp_f32_e32 v74, v74
	v_exp_f32_e32 v75, v75
	s_waitcnt lgkmcnt(2)
	v_mfma_f32_32x32x16_bf16 v[16:31], v[144:147], v[198:201], v[16:31]
	v_exp_f32_e32 v76, v76
	v_exp_f32_e32 v77, v77
	s_waitcnt lgkmcnt(0)
	v_mfma_f32_32x32x16_bf16 v[0:15], v[144:147], v[202:205], v[0:15]
	v_exp_f32_e32 v78, v78
	v_exp_f32_e32 v79, v79
	s_add_i32 s90, s88, 0x2000
	s_cmpk_lg_i32 s88, 0x4000
	s_mov_b32 s89, s86
	s_cselect_b32 s86, s90, 0
	s_add_i32 s85, s85, 2
	v_lshl_add_u64 v[176:177], v[176:177], 0, s[58:59]
	v_lshl_add_u64 v[178:179], v[178:179], 0, s[58:59]
	v_lshl_add_u64 v[180:181], v[180:181], 0, s[58:59]
	s_mov_b32 s87, s88
	s_cmp_lt_u32 s85, 57
	s_waitcnt vmcnt(3) lgkmcnt(0)
	s_barrier
; #define WAIT_BAR(N) asm volatile("s_waitcnt vmcnt(" #N ") lgkmcnt(0)\n\ts_barrier":::"memory")
;   #define RESC() do{ if(!NOMAX&&resc){ asm volatile("s_waitcnt lgkmcnt(0)":::"memory"); \
;       _Pragma("unroll") for(int d_=0;d_<2*VM;++d_) _Pragma("unroll") for(int r=0;r<16;++r)o[d_][r]*=wsf[crow(r,hi)]; } }while(0)
;   #define ROT() do{sl_prev=sl_cur;sl_cur=sl_next;sl_next=(sl_next==(NSLOT-1)*SLOTB)?0:sl_next+SLOTB;}while(0)
;   #define ENDW(tt) do{ if((tt)+3<NT){ if constexpr(VM==2){WAIT_BAR(3);}else{WAIT_BAR(2);} } else if((tt)+2<NT){ if constexpr(VM==2){WAIT_BAR(2);}else{WAIT_BAR(1);} } else {WAIT_BAR(0);} }while(0)
; template<int THRL,int VM,bool NOMAX> __device__ __forceinline__ void attn_unit(const bf16*Qb,const bf16*__restrict__ Kh,const bf16*__restrict__ Vh,bf16*Ob,const int NT,const int sp,float*wscr,char*shm){
;     ...
;   int t=1;
;   for(;t+5<NT;t+=2){
;     STEP(pB0,pB1,pA0,pA1,t,true,true,true);     if constexpr(VM==2){WAIT_BAR(3);}else{WAIT_BAR(2);} RESC(); ROT();
;     STEP(pA0,pA1,pB0,pB1,t+1,true,true,true);   if constexpr(VM==2){WAIT_BAR(3);}else{WAIT_BAR(2);} RESC(); ROT();
;   }
;     ...
;   for(;t+1<NT;t+=2){
;     STEP(pB0,pB1,pA0,pA1,t,(t+3<NT),(t+1<NT),(t+1<NT));       ENDW(t);   RESC(); ROT();
;     STEP(pA0,pA1,pB0,pB1,t+1,(t+4<NT),(t+2<NT),(t+2<NT));     ENDW(t+1); RESC(); ROT();
	s_cbranch_scc1 .LBB0_874
	s_and_b32 s34, s34, 0x3fffffc0
	s_lshl_b32 s34, s34, 2
	s_add_i32 s34, s34, 0
	s_add_i32 s34, s34, 0x12000
	s_cmp_lg_u32 0, -1
	s_cselect_b32 s85, 0, 0
	s_add_i32 s86, s85, 0x6000
	v_add_u32_e32 v104, s86, v191
	v_add3_u32 v176, v104, v190, v192
	v_add_u32_e32 v177, 0x6000, v188
	ds_read_b64_tr_b16 v[178:179], v188 offset:40960
	ds_read_b64_tr_b16 v[180:181], v188 offset:41472
	v_add_f32_e32 v108, v80, v81
	ds_read_b128 v[104:107], v168
	v_add_f32_e32 v108, v82, v108
	v_add_f32_e32 v108, v83, v108
	v_add_f32_e32 v108, v84, v108
	v_add_f32_e32 v108, v85, v108
	v_cvt_pk_bf16_f32 v156, v80, v81
	v_cvt_pk_bf16_f32 v157, v82, v83
	s_waitcnt lgkmcnt(0)
	v_mfma_f32_32x32x16_bf16 v[112:127], v[100:103], v[104:107], 0
	ds_read_b64_tr_b16 v[80:81], v188 offset:45056
	ds_read_b64_tr_b16 v[82:83], v188 offset:45568
	ds_read_b128 v[100:103], v168
	v_add_f32_e32 v104, v86, v108
	v_add_f32_e32 v104, v87, v104
	v_add_f32_e32 v104, v88, v104
	v_add_f32_e32 v144, v89, v104
	v_cvt_pk_bf16_f32 v158, v84, v85
	v_cvt_pk_bf16_f32 v159, v86, v87
	s_waitcnt lgkmcnt(0)
	v_mfma_f32_32x32x16_bf16 v[96:111], v[96:99], v[100:103], 0
	ds_read_b64_tr_b16 v[84:85], v188 offset:41984
	ds_read_b64_tr_b16 v[86:87], v188 offset:42496
	ds_read_b128 v[194:197], v168 offset:1024
	v_add_f32_e32 v144, v90, v144
	v_add_f32_e32 v144, v91, v144
	v_add_f32_e32 v144, v92, v144
	v_add_f32_e32 v144, v93, v144
	v_cvt_pk_bf16_f32 v152, v88, v89
	v_cvt_pk_bf16_f32 v153, v90, v91
	s_waitcnt lgkmcnt(0)
	v_mfma_f32_32x32x16_bf16 v[112:127], v[164:167], v[194:197], v[112:127]
	ds_read_b64_tr_b16 v[88:89], v188 offset:46080
	ds_read_b64_tr_b16 v[90:91], v188 offset:46592
	ds_read_b128 v[164:167], v168 offset:1024
	v_add_f32_e32 v144, v94, v144
	v_add_f32_e32 v144, v95, v144
	v_add_f32_e32 v144, v64, v144
	v_add_f32_e32 v144, v65, v144
	v_cvt_pk_bf16_f32 v154, v92, v93
	v_cvt_pk_bf16_f32 v155, v94, v95
	s_waitcnt lgkmcnt(0)
	v_mfma_f32_32x32x16_bf16 v[96:111], v[160:163], v[164:167], v[96:111]
	ds_read_b64_tr_b16 v[194:195], v188 offset:43008
	ds_read_b64_tr_b16 v[196:197], v188 offset:43520
	ds_read_b128 v[92:95], v168 offset:2048
	v_add_f32_e32 v144, v66, v144
	v_add_f32_e32 v144, v67, v144
	v_add_f32_e32 v144, v68, v144
	v_add_f32_e32 v144, v69, v144
	v_cvt_pk_bf16_f32 v148, v64, v65
	v_cvt_pk_bf16_f32 v149, v66, v67
	s_waitcnt lgkmcnt(0)
	v_mfma_f32_32x32x16_bf16 v[112:127], v[140:143], v[92:95], v[112:127]
	ds_read_b64_tr_b16 v[140:141], v188 offset:47104
	ds_read_b64_tr_b16 v[142:143], v188 offset:47616
	ds_read_b128 v[64:67], v168 offset:2048
	v_add_f32_e32 v92, v70, v144
	v_add_f32_e32 v92, v71, v92
	v_add_f32_e32 v92, v72, v92
	v_add_f32_e32 v92, v73, v92
	v_cvt_pk_bf16_f32 v150, v68, v69
	v_cvt_pk_bf16_f32 v151, v70, v71
	s_waitcnt lgkmcnt(0)
	v_mfma_f32_32x32x16_bf16 v[96:111], v[136:139], v[64:67], v[96:111]
	ds_read_b64_tr_b16 v[136:137], v188 offset:44032
	ds_read_b64_tr_b16 v[138:139], v188 offset:44544
	ds_read_b128 v[64:67], v168 offset:3072
	v_add_f32_e32 v68, v74, v92
	v_add_f32_e32 v68, v75, v68
	v_add_f32_e32 v68, v76, v68
	v_add_f32_e32 v68, v77, v68
	v_cvt_pk_bf16_f32 v144, v72, v73
	v_cvt_pk_bf16_f32 v145, v74, v75
	s_waitcnt lgkmcnt(0)
	v_mfma_f32_32x32x16_bf16 v[112:127], v[132:135], v[64:67], v[112:127]
	ds_read_b64_tr_b16 v[72:73], v188 offset:48128
	ds_read_b64_tr_b16 v[74:75], v188 offset:48640
	ds_read_b128 v[64:67], v168 offset:3072
	v_add_f32_e32 v68, v78, v68
	v_add_f32_e32 v68, v79, v68
	v_add_f32_e32 v68, 0, v68
	v_cvt_pk_bf16_f32 v146, v76, v77
	v_cvt_pk_bf16_f32 v147, v78, v79
	s_waitcnt lgkmcnt(0)
	v_mfma_f32_32x32x16_bf16 v[96:111], v[128:131], v[64:67], v[96:111]
	s_add_i32 s85, s85, s35
	v_lshl_add_u64 v[64:65], v[174:175], 0, s[60:61]
	s_add_i32 s35, s85, 0x4000
	s_mov_b32 s86, m0
	s_mov_b32 m0, s35
	s_nop 0
	global_load_lds_dwordx4 v[64:65], off
	s_mov_b32 m0, s86
	v_lshl_add_u64 v[64:65], v[170:171], 0, s[62:63]
	s_mov_b32 s35, m0
	s_mov_b32 m0, s16
	s_nop 0
	global_load_lds_dwordx4 v[64:65], off
	s_mov_b32 m0, s35
	v_lshl_add_u64 v[64:65], v[172:173], 0, s[62:63]
	s_add_i32 s35, s16, 0x2000
	s_mov_b32 s86, m0
	s_mov_b32 m0, s35
	s_nop 0
	global_load_lds_dwordx4 v[64:65], off
	s_mov_b32 m0, s86
	v_add_f32_e32 v198, v193, v68
	v_mfma_f32_32x32x16_bf16 v[48:63], v[156:159], v[178:181], v[48:63]
	ds_read_b64_tr_b16 v[76:77], v188 offset:49152
	ds_read_b64_tr_b16 v[78:79], v188 offset:49664
	v_exp_f32_e32 v112, v112
	v_exp_f32_e32 v113, v113
	v_mfma_f32_32x32x16_bf16 v[32:47], v[156:159], v[80:83], v[32:47]
	ds_read_b64_tr_b16 v[128:129], v188 offset:53248
	ds_read_b64_tr_b16 v[130:131], v188 offset:53760
	v_exp_f32_e32 v114, v114
	v_exp_f32_e32 v115, v115
	ds_read_b128 v[68:71], v234
	ds_read_b128 v[64:67], v234 offset:4096
	v_mfma_f32_32x32x16_bf16 v[48:63], v[152:155], v[84:87], v[48:63]
	ds_read_b64_tr_b16 v[132:133], v188 offset:50176
	ds_read_b64_tr_b16 v[134:135], v188 offset:50688
	v_exp_f32_e32 v116, v116
	v_exp_f32_e32 v117, v117
	ds_read_b128 v[164:167], v235
	ds_read_b128 v[92:95], v235 offset:4096
	v_mfma_f32_32x32x16_bf16 v[32:47], v[152:155], v[88:91], v[32:47]
	ds_read_b64_tr_b16 v[178:179], v188 offset:54272
	ds_read_b64_tr_b16 v[180:181], v188 offset:54784
	v_exp_f32_e32 v118, v118
	v_exp_f32_e32 v119, v119
	ds_read_b128 v[160:163], v236
	ds_read_b128 v[84:87], v236 offset:4096
	v_mfma_f32_32x32x16_bf16 v[48:63], v[148:151], v[194:197], v[48:63]
	ds_read_b64_tr_b16 v[190:191], v188 offset:51200
	ds_read_b64_tr_b16 v[192:193], v188 offset:51712
	v_exp_f32_e32 v120, v120
	v_exp_f32_e32 v121, v121
	ds_read_b128 v[88:91], v237
	ds_read_b128 v[80:83], v237 offset:4096
	v_mfma_f32_32x32x16_bf16 v[32:47], v[148:151], v[140:143], v[32:47]
	ds_read_b64_tr_b16 v[194:195], v188 offset:55296
	ds_read_b64_tr_b16 v[196:197], v188 offset:55808
	v_exp_f32_e32 v122, v122
	v_exp_f32_e32 v123, v123
	v_mfma_f32_32x32x16_bf16 v[48:63], v[144:147], v[136:139], v[48:63]
	ds_read_b64_tr_b16 v[140:141], v188 offset:52224
	ds_read_b64_tr_b16 v[142:143], v188 offset:52736
	v_exp_f32_e32 v124, v124
	v_exp_f32_e32 v125, v125
	v_mfma_f32_32x32x16_bf16 v[32:47], v[144:147], v[72:75], v[32:47]
	ds_read_b64_tr_b16 v[136:137], v188 offset:56320
	ds_read_b64_tr_b16 v[138:139], v188 offset:56832
	v_exp_f32_e32 v126, v126
	v_exp_f32_e32 v127, v127
	s_waitcnt lgkmcnt(14)
	v_mfma_f32_32x32x16_bf16 v[16:31], v[156:159], v[76:79], v[16:31]
	v_exp_f32_e32 v96, v96
	v_exp_f32_e32 v97, v97
	v_mfma_f32_32x32x16_bf16 v[0:15], v[156:159], v[128:131], v[0:15]
	v_exp_f32_e32 v98, v98
	v_exp_f32_e32 v99, v99
	v_mfma_f32_32x32x16_bf16 v[16:31], v[152:155], v[132:135], v[16:31]
	v_exp_f32_e32 v100, v100
	v_exp_f32_e32 v101, v101
	s_waitcnt lgkmcnt(12)
	v_mfma_f32_32x32x16_bf16 v[0:15], v[152:155], v[178:181], v[0:15]
	v_exp_f32_e32 v102, v102
	v_exp_f32_e32 v103, v103
	s_waitcnt lgkmcnt(8)
	v_mfma_f32_32x32x16_bf16 v[16:31], v[148:151], v[190:193], v[16:31]
	v_exp_f32_e32 v104, v104
	v_exp_f32_e32 v105, v105
	s_waitcnt lgkmcnt(4)
	v_mfma_f32_32x32x16_bf16 v[0:15], v[148:151], v[194:197], v[0:15]
	v_exp_f32_e32 v106, v106
	v_exp_f32_e32 v107, v107
	s_waitcnt lgkmcnt(2)
	v_mfma_f32_32x32x16_bf16 v[16:31], v[144:147], v[140:143], v[16:31]
	v_exp_f32_e32 v108, v108
	v_exp_f32_e32 v109, v109
	s_waitcnt lgkmcnt(0)
	v_mfma_f32_32x32x16_bf16 v[0:15], v[144:147], v[136:139], v[0:15]
	v_exp_f32_e32 v110, v110
	v_exp_f32_e32 v111, v111
	s_waitcnt vmcnt(3) lgkmcnt(0)
	s_barrier
	ds_read_b64_tr_b16 v[178:179], v188 offset:57344
	ds_read_b64_tr_b16 v[180:181], v188 offset:57856
	v_add_f32_e32 v76, v112, v113
	ds_read_b128 v[72:75], v168
	v_add_f32_e32 v76, v114, v76
	v_add_f32_e32 v76, v115, v76
	v_add_f32_e32 v76, v116, v76
	v_add_f32_e32 v76, v117, v76
	v_cvt_pk_bf16_f32 v156, v112, v113
	v_cvt_pk_bf16_f32 v157, v114, v115
	s_waitcnt lgkmcnt(0)
	v_mfma_f32_32x32x16_bf16 v[128:143], v[68:71], v[72:75], 0
	ds_read_b64_tr_b16 v[112:113], v188 offset:61440
	ds_read_b64_tr_b16 v[114:115], v188 offset:61952
	ds_read_b128 v[68:71], v168
	v_add_f32_e32 v72, v118, v76
	v_add_f32_e32 v72, v119, v72
	v_add_f32_e32 v72, v120, v72
	v_add_f32_e32 v144, v121, v72
	s_waitcnt lgkmcnt(0)
	v_mfma_f32_32x32x16_bf16 v[64:79], v[64:67], v[68:71], 0
	v_cvt_pk_bf16_f32 v158, v116, v117
	v_cvt_pk_bf16_f32 v159, v118, v119
	ds_read_b64_tr_b16 v[116:117], v188 offset:58368
	ds_read_b64_tr_b16 v[118:119], v188 offset:58880
	ds_read_b128 v[190:193], v168 offset:1024
	v_add_f32_e32 v144, v122, v144
	v_add_f32_e32 v144, v123, v144
	v_add_f32_e32 v144, v124, v144
	v_add_f32_e32 v144, v125, v144
	v_cvt_pk_bf16_f32 v152, v120, v121
	v_cvt_pk_bf16_f32 v153, v122, v123
	s_waitcnt lgkmcnt(0)
	v_mfma_f32_32x32x16_bf16 v[128:143], v[164:167], v[190:193], v[128:143]
	ds_read_b64_tr_b16 v[120:121], v188 offset:62464
	ds_read_b64_tr_b16 v[122:123], v188 offset:62976
	ds_read_b128 v[164:167], v168 offset:1024
	v_add_f32_e32 v144, v126, v144
	v_add_f32_e32 v144, v127, v144
	v_add_f32_e32 v144, v96, v144
	v_add_f32_e32 v144, v97, v144
	s_waitcnt lgkmcnt(0)
	v_mfma_f32_32x32x16_bf16 v[64:79], v[92:95], v[164:167], v[64:79]
	v_cvt_pk_bf16_f32 v154, v124, v125
	v_cvt_pk_bf16_f32 v155, v126, v127
	ds_read_b64_tr_b16 v[92:93], v188 offset:59392
	ds_read_b64_tr_b16 v[94:95], v188 offset:59904
	ds_read_b128 v[124:127], v168 offset:2048
	v_add_f32_e32 v144, v98, v144
	v_add_f32_e32 v144, v99, v144
	v_add_f32_e32 v144, v100, v144
	v_add_f32_e32 v144, v101, v144
	v_cvt_pk_bf16_f32 v148, v96, v97
	v_cvt_pk_bf16_f32 v149, v98, v99
	s_waitcnt lgkmcnt(0)
	v_mfma_f32_32x32x16_bf16 v[128:143], v[160:163], v[124:127], v[128:143]
	ds_read_b64_tr_b16 v[96:97], v188 offset:63488
	ds_read_b64_tr_b16 v[98:99], v188 offset:64000
	ds_read_b128 v[124:127], v168 offset:2048
	v_add_f32_e32 v144, v102, v144
	v_add_f32_e32 v144, v103, v144
	v_add_f32_e32 v144, v104, v144
	v_add_f32_e32 v144, v105, v144
	s_waitcnt lgkmcnt(0)
	v_mfma_f32_32x32x16_bf16 v[64:79], v[84:87], v[124:127], v[64:79]
	v_cvt_pk_bf16_f32 v150, v100, v101
	v_cvt_pk_bf16_f32 v151, v102, v103
	ds_read_b64_tr_b16 v[100:101], v188 offset:60416
	ds_read_b64_tr_b16 v[102:103], v188 offset:60928
	ds_read_b128 v[84:87], v168 offset:3072
	v_add_f32_e32 v124, v106, v144
	v_add_f32_e32 v124, v107, v124
	v_add_f32_e32 v124, v108, v124
	v_add_f32_e32 v124, v109, v124
	v_cvt_pk_bf16_f32 v144, v104, v105
	v_cvt_pk_bf16_f32 v145, v106, v107
	s_waitcnt lgkmcnt(0)
	v_mfma_f32_32x32x16_bf16 v[128:143], v[88:91], v[84:87], v[128:143]
	ds_read_b64_tr_b16 v[88:89], v188 offset:64512
	ds_read_b64_tr_b16 v[90:91], v188 offset:65024
	ds_read_b128 v[84:87], v168 offset:3072
	v_add_f32_e32 v104, v110, v124
	v_add_f32_e32 v104, v111, v104
	v_add_f32_e32 v104, 0, v104
	v_cvt_pk_bf16_f32 v146, v108, v109
	s_waitcnt lgkmcnt(0)
	v_mfma_f32_32x32x16_bf16 v[64:79], v[80:83], v[84:87], v[64:79]
	v_cvt_pk_bf16_f32 v147, v110, v111
	v_lshl_add_u64 v[80:81], v[174:175], 0, s[64:65]
	s_mov_b32 s86, m0
	s_mov_b32 m0, s17
	s_nop 0
	global_load_lds_dwordx4 v[80:81], off
	s_mov_b32 m0, s86
	v_lshl_add_u64 v[80:81], v[170:171], 0, s[66:67]
	s_add_i32 s17, s85, 0xa000
	s_mov_b32 s86, m0
	s_mov_b32 m0, s17
	s_nop 0
	global_load_lds_dwordx4 v[80:81], off
	s_mov_b32 m0, s86
	v_lshl_add_u64 v[80:81], v[172:173], 0, s[66:67]
	s_add_i32 s17, s85, 0xc000
	s_mov_b32 s86, m0
	s_mov_b32 m0, s17
	s_nop 0
	global_load_lds_dwordx4 v[80:81], off
	s_mov_b32 m0, s86
	v_add_f32_e32 v198, v198, v104
	v_mfma_f32_32x32x16_bf16 v[48:63], v[156:159], v[178:181], v[48:63]
	ds_read_b64_tr_b16 v[104:105], v177 offset:40960
	ds_read_b64_tr_b16 v[106:107], v177 offset:41472
	v_exp_f32_e32 v128, v128
	v_exp_f32_e32 v129, v129
	v_mfma_f32_32x32x16_bf16 v[32:47], v[156:159], v[112:115], v[32:47]
	ds_read_b64_tr_b16 v[108:109], v177 offset:45056
	ds_read_b64_tr_b16 v[110:111], v177 offset:45568
	v_exp_f32_e32 v130, v130
	v_exp_f32_e32 v131, v131
	ds_read_b128 v[84:87], v234 offset:8192
	ds_read_b128 v[80:83], v234 offset:12288
	v_mfma_f32_32x32x16_bf16 v[48:63], v[152:155], v[116:119], v[48:63]
	ds_read_b64_tr_b16 v[178:179], v177 offset:41984
	ds_read_b64_tr_b16 v[180:181], v177 offset:42496
	v_exp_f32_e32 v132, v132
	v_exp_f32_e32 v133, v133
	ds_read_b128 v[164:167], v235 offset:8192
	ds_read_b128 v[124:127], v235 offset:12288
	v_mfma_f32_32x32x16_bf16 v[32:47], v[152:155], v[120:123], v[32:47]
	ds_read_b64_tr_b16 v[190:191], v177 offset:46080
	ds_read_b64_tr_b16 v[192:193], v177 offset:46592
	v_exp_f32_e32 v134, v134
	v_exp_f32_e32 v135, v135
	ds_read_b128 v[160:163], v236 offset:8192
	ds_read_b128 v[116:119], v236 offset:12288
	v_mfma_f32_32x32x16_bf16 v[48:63], v[148:151], v[92:95], v[48:63]
	ds_read_b64_tr_b16 v[194:195], v177 offset:43008
	ds_read_b64_tr_b16 v[196:197], v177 offset:43520
	v_exp_f32_e32 v136, v136
	v_exp_f32_e32 v137, v137
	ds_read_b128 v[120:123], v237 offset:8192
	ds_read_b128 v[112:115], v237 offset:12288
	v_mfma_f32_32x32x16_bf16 v[32:47], v[148:151], v[96:99], v[32:47]
	ds_read_b64_tr_b16 v[92:93], v177 offset:47104
	ds_read_b64_tr_b16 v[94:95], v177 offset:47616
	v_exp_f32_e32 v138, v138
	v_exp_f32_e32 v139, v139
	v_mfma_f32_32x32x16_bf16 v[48:63], v[144:147], v[100:103], v[48:63]
	ds_read_b64_tr_b16 v[96:97], v177 offset:44032
	ds_read_b64_tr_b16 v[98:99], v177 offset:44544
	v_exp_f32_e32 v140, v140
	v_exp_f32_e32 v141, v141
	v_mfma_f32_32x32x16_bf16 v[32:47], v[144:147], v[88:91], v[32:47]
	ds_read_b64_tr_b16 v[100:101], v177 offset:48128
	ds_read_b64_tr_b16 v[102:103], v177 offset:48640
	v_exp_f32_e32 v142, v142
	v_exp_f32_e32 v143, v143
	s_waitcnt lgkmcnt(14)
	v_mfma_f32_32x32x16_bf16 v[16:31], v[156:159], v[104:107], v[16:31]
	v_exp_f32_e32 v64, v64
	v_exp_f32_e32 v65, v65
	v_mfma_f32_32x32x16_bf16 v[0:15], v[156:159], v[108:111], v[0:15]
	v_exp_f32_e32 v66, v66
	v_exp_f32_e32 v67, v67
	v_mfma_f32_32x32x16_bf16 v[16:31], v[152:155], v[178:181], v[16:31]
	v_exp_f32_e32 v68, v68
	v_exp_f32_e32 v69, v69
	s_waitcnt lgkmcnt(12)
	v_mfma_f32_32x32x16_bf16 v[0:15], v[152:155], v[190:193], v[0:15]
	v_exp_f32_e32 v70, v70
	v_exp_f32_e32 v71, v71
	s_waitcnt lgkmcnt(8)
	v_mfma_f32_32x32x16_bf16 v[16:31], v[148:151], v[194:197], v[16:31]
	v_exp_f32_e32 v72, v72
	v_exp_f32_e32 v73, v73
	s_waitcnt lgkmcnt(4)
	v_mfma_f32_32x32x16_bf16 v[0:15], v[148:151], v[92:95], v[0:15]
	v_exp_f32_e32 v74, v74
	v_exp_f32_e32 v75, v75
	s_waitcnt lgkmcnt(2)
	v_mfma_f32_32x32x16_bf16 v[16:31], v[144:147], v[96:99], v[16:31]
	v_exp_f32_e32 v76, v76
	v_exp_f32_e32 v77, v77
	s_waitcnt lgkmcnt(0)
	v_mfma_f32_32x32x16_bf16 v[0:15], v[144:147], v[100:103], v[0:15]
	v_exp_f32_e32 v78, v78
	v_exp_f32_e32 v79, v79
	s_waitcnt vmcnt(3) lgkmcnt(0)
	s_barrier
	ds_read_b64_tr_b16 v[178:179], v188 offset:24576
	ds_read_b64_tr_b16 v[180:181], v188 offset:25088
	v_add_f32_e32 v92, v128, v129
	ds_read_b128 v[88:91], v168
	v_add_f32_e32 v92, v130, v92
	v_add_f32_e32 v92, v131, v92
	v_add_f32_e32 v92, v132, v92
	v_add_f32_e32 v92, v133, v92
	v_cvt_pk_bf16_f32 v156, v128, v129
	v_cvt_pk_bf16_f32 v157, v130, v131
	s_waitcnt lgkmcnt(0)
	v_mfma_f32_32x32x16_bf16 v[96:111], v[84:87], v[88:91], 0
	ds_read_b64_tr_b16 v[128:129], v188 offset:28672
	ds_read_b64_tr_b16 v[130:131], v188 offset:29184
	ds_read_b128 v[84:87], v168
	v_add_f32_e32 v88, v134, v92
	v_add_f32_e32 v88, v135, v88
	v_add_f32_e32 v88, v136, v88
	v_add_f32_e32 v144, v137, v88
	v_cvt_pk_bf16_f32 v158, v132, v133
	v_cvt_pk_bf16_f32 v159, v134, v135
	s_waitcnt lgkmcnt(0)
	v_mfma_f32_32x32x16_bf16 v[80:95], v[80:83], v[84:87], 0
	ds_read_b64_tr_b16 v[132:133], v188 offset:25600
	ds_read_b64_tr_b16 v[134:135], v188 offset:26112
	ds_read_b128 v[190:193], v168 offset:1024
	v_add_f32_e32 v144, v138, v144
	v_add_f32_e32 v144, v139, v144
	v_add_f32_e32 v144, v140, v144
	v_add_f32_e32 v144, v141, v144
	v_cvt_pk_bf16_f32 v152, v136, v137
	v_cvt_pk_bf16_f32 v153, v138, v139
	s_waitcnt lgkmcnt(0)
	v_mfma_f32_32x32x16_bf16 v[96:111], v[164:167], v[190:193], v[96:111]
	ds_read_b64_tr_b16 v[136:137], v188 offset:29696
	ds_read_b64_tr_b16 v[138:139], v188 offset:30208
	ds_read_b128 v[164:167], v168 offset:1024
	v_add_f32_e32 v144, v142, v144
	v_add_f32_e32 v144, v143, v144
	v_add_f32_e32 v144, v64, v144
	v_add_f32_e32 v144, v65, v144
	v_cvt_pk_bf16_f32 v154, v140, v141
	v_cvt_pk_bf16_f32 v155, v142, v143
	s_waitcnt lgkmcnt(0)
; #define WAIT_BAR(N) asm volatile("s_waitcnt vmcnt(" #N ") lgkmcnt(0)\n\ts_barrier":::"memory")
;   #define RESC() do{ if(!NOMAX&&resc){ asm volatile("s_waitcnt lgkmcnt(0)":::"memory"); \
;       _Pragma("unroll") for(int d_=0;d_<2*VM;++d_) _Pragma("unroll") for(int r=0;r<16;++r)o[d_][r]*=wsf[crow(r,hi)]; } }while(0)
;   #define ROT() do{sl_prev=sl_cur;sl_cur=sl_next;sl_next=(sl_next==(NSLOT-1)*SLOTB)?0:sl_next+SLOTB;}while(0)
;   #define ENDW(tt) do{ if((tt)+3<NT){ if constexpr(VM==2){WAIT_BAR(3);}else{WAIT_BAR(2);} } else if((tt)+2<NT){ if constexpr(VM==2){WAIT_BAR(2);}else{WAIT_BAR(1);} } else {WAIT_BAR(0);} }while(0)
; template<int THRL,int VM,bool NOMAX> __device__ __forceinline__ void attn_unit(const bf16*Qb,const bf16*__restrict__ Kh,const bf16*__restrict__ Vh,bf16*Ob,const int NT,const int sp,float*wscr,char*shm){
;     ...
;   int t=1;
;   for(;t+5<NT;t+=2){
;     STEP(pB0,pB1,pA0,pA1,t,true,true,true);     if constexpr(VM==2){WAIT_BAR(3);}else{WAIT_BAR(2);} RESC(); ROT();
;     STEP(pA0,pA1,pB0,pB1,t+1,true,true,true);   if constexpr(VM==2){WAIT_BAR(3);}else{WAIT_BAR(2);} RESC(); ROT();
;   }
;     ...
;   for(;t+1<NT;t+=2){
;     STEP(pB0,pB1,pA0,pA1,t,(t+3<NT),(t+1<NT),(t+1<NT));       ENDW(t);   RESC(); ROT();
;     STEP(pA0,pA1,pB0,pB1,t+1,(t+4<NT),(t+2<NT),(t+2<NT));     ENDW(t+1); RESC(); ROT();
	v_mfma_f32_32x32x16_bf16 v[80:95], v[124:127], v[164:167], v[80:95]
	ds_read_b64_tr_b16 v[124:125], v188 offset:26624
	ds_read_b64_tr_b16 v[126:127], v188 offset:27136
	ds_read_b128 v[140:143], v168 offset:2048
	v_add_f32_e32 v144, v66, v144
	v_add_f32_e32 v144, v67, v144
	v_add_f32_e32 v144, v68, v144
	v_add_f32_e32 v144, v69, v144
	v_cvt_pk_bf16_f32 v148, v64, v65
	v_cvt_pk_bf16_f32 v149, v66, v67
	s_waitcnt lgkmcnt(0)
	v_mfma_f32_32x32x16_bf16 v[96:111], v[160:163], v[140:143], v[96:111]
	ds_read_b64_tr_b16 v[190:191], v188 offset:30720
	ds_read_b64_tr_b16 v[192:193], v188 offset:31232
	ds_read_b128 v[64:67], v168 offset:2048
	v_add_f32_e32 v140, v70, v144
	v_add_f32_e32 v140, v71, v140
	v_add_f32_e32 v140, v72, v140
	v_add_f32_e32 v140, v73, v140
	v_cvt_pk_bf16_f32 v150, v68, v69
	v_cvt_pk_bf16_f32 v151, v70, v71
	s_waitcnt lgkmcnt(0)
	v_mfma_f32_32x32x16_bf16 v[80:95], v[116:119], v[64:67], v[80:95]
	ds_read_b64_tr_b16 v[116:117], v188 offset:27648
	ds_read_b64_tr_b16 v[118:119], v188 offset:28160
	ds_read_b128 v[64:67], v168 offset:3072
	v_add_f32_e32 v68, v74, v140
	v_add_f32_e32 v68, v75, v68
	v_add_f32_e32 v68, v76, v68
	v_add_f32_e32 v68, v77, v68
	v_cvt_pk_bf16_f32 v144, v72, v73
	v_cvt_pk_bf16_f32 v145, v74, v75
	s_waitcnt lgkmcnt(0)
	v_mfma_f32_32x32x16_bf16 v[96:111], v[120:123], v[64:67], v[96:111]
	ds_read_b64_tr_b16 v[72:73], v188 offset:31744
	ds_read_b64_tr_b16 v[74:75], v188 offset:32256
	ds_read_b128 v[64:67], v168 offset:3072
	v_add_f32_e32 v68, v78, v68
	v_add_f32_e32 v68, v79, v68
	v_add_f32_e32 v68, 0, v68
	v_cvt_pk_bf16_f32 v146, v76, v77
	v_cvt_pk_bf16_f32 v147, v78, v79
	s_waitcnt lgkmcnt(0)
	v_mfma_f32_32x32x16_bf16 v[80:95], v[112:115], v[64:67], v[80:95]
	v_lshl_add_u64 v[64:65], v[170:171], 0, s[60:61]
	s_add_i32 s17, s85, 0xe000
	s_mov_b32 s86, m0
	s_mov_b32 m0, s17
	s_nop 0
	global_load_lds_dwordx4 v[64:65], off
	s_mov_b32 m0, s86
	v_lshl_add_u64 v[64:65], v[172:173], 0, s[60:61]
	s_add_i32 s85, s85, 0x10000
	s_mov_b32 s17, m0
	s_mov_b32 m0, s85
	s_nop 0
	global_load_lds_dwordx4 v[64:65], off
	s_mov_b32 m0, s17
	v_add_f32_e32 v174, v198, v68
	v_mfma_f32_32x32x16_bf16 v[48:63], v[156:159], v[178:181], v[48:63]
	ds_read_b64_tr_b16 v[76:77], v188 offset:32768
	ds_read_b64_tr_b16 v[78:79], v188 offset:33280
	v_exp_f32_e32 v96, v96
	v_exp_f32_e32 v97, v97
	v_mfma_f32_32x32x16_bf16 v[32:47], v[156:159], v[128:131], v[32:47]
	ds_read_b64_tr_b16 v[112:113], v188 offset:36864
	ds_read_b64_tr_b16 v[114:115], v188 offset:37376
	v_exp_f32_e32 v98, v98
	v_exp_f32_e32 v99, v99
	ds_read_b128 v[68:71], v234 offset:16384
	ds_read_b128 v[64:67], v234 offset:20480
	v_mfma_f32_32x32x16_bf16 v[48:63], v[152:155], v[132:135], v[48:63]
	ds_read_b64_tr_b16 v[120:121], v188 offset:33792
	ds_read_b64_tr_b16 v[122:123], v188 offset:34304
	v_exp_f32_e32 v100, v100
	v_exp_f32_e32 v101, v101
	ds_read_b128 v[164:167], v235 offset:16384
	ds_read_b128 v[140:143], v235 offset:20480
	v_mfma_f32_32x32x16_bf16 v[32:47], v[152:155], v[136:139], v[32:47]
	ds_read_b64_tr_b16 v[178:179], v188 offset:37888
	ds_read_b64_tr_b16 v[180:181], v188 offset:38400
	v_exp_f32_e32 v102, v102
	v_exp_f32_e32 v103, v103
	ds_read_b128 v[160:163], v236 offset:16384
	ds_read_b128 v[132:135], v236 offset:20480
	v_mfma_f32_32x32x16_bf16 v[48:63], v[148:151], v[124:127], v[48:63]
	ds_read_b64_tr_b16 v[194:195], v188 offset:34816
	ds_read_b64_tr_b16 v[196:197], v188 offset:35328
	v_exp_f32_e32 v104, v104
	v_exp_f32_e32 v105, v105
	ds_read_b128 v[136:139], v237 offset:16384
	ds_read_b128 v[128:131], v237 offset:20480
	v_mfma_f32_32x32x16_bf16 v[32:47], v[148:151], v[190:193], v[32:47]
	ds_read_b64_tr_b16 v[124:125], v188 offset:38912
	ds_read_b64_tr_b16 v[126:127], v188 offset:39424
	v_exp_f32_e32 v106, v106
	v_exp_f32_e32 v107, v107
	v_mfma_f32_32x32x16_bf16 v[48:63], v[144:147], v[116:119], v[48:63]
	ds_read_b64_tr_b16 v[190:191], v188 offset:35840
	ds_read_b64_tr_b16 v[192:193], v188 offset:36352
	v_exp_f32_e32 v108, v108
	v_exp_f32_e32 v109, v109
	v_mfma_f32_32x32x16_bf16 v[32:47], v[144:147], v[72:75], v[32:47]
	ds_read_b64_tr_b16 v[116:117], v188 offset:39936
	ds_read_b64_tr_b16 v[118:119], v188 offset:40448
	v_exp_f32_e32 v110, v110
	v_exp_f32_e32 v111, v111
	s_waitcnt lgkmcnt(14)
	v_mfma_f32_32x32x16_bf16 v[16:31], v[156:159], v[76:79], v[16:31]
	v_exp_f32_e32 v80, v80
	v_exp_f32_e32 v81, v81
	v_mfma_f32_32x32x16_bf16 v[0:15], v[156:159], v[112:115], v[0:15]
	v_exp_f32_e32 v82, v82
	v_exp_f32_e32 v83, v83
	v_mfma_f32_32x32x16_bf16 v[16:31], v[152:155], v[120:123], v[16:31]
	v_exp_f32_e32 v84, v84
	v_exp_f32_e32 v85, v85
	s_waitcnt lgkmcnt(12)
	v_mfma_f32_32x32x16_bf16 v[0:15], v[152:155], v[178:181], v[0:15]
	v_exp_f32_e32 v86, v86
	v_exp_f32_e32 v87, v87
	s_waitcnt lgkmcnt(8)
	v_mfma_f32_32x32x16_bf16 v[16:31], v[148:151], v[194:197], v[16:31]
	v_exp_f32_e32 v88, v88
	v_exp_f32_e32 v89, v89
	s_waitcnt lgkmcnt(4)
	v_mfma_f32_32x32x16_bf16 v[0:15], v[148:151], v[124:127], v[0:15]
	v_exp_f32_e32 v90, v90
	v_exp_f32_e32 v91, v91
	s_waitcnt lgkmcnt(2)
	v_mfma_f32_32x32x16_bf16 v[16:31], v[144:147], v[190:193], v[16:31]
	v_exp_f32_e32 v92, v92
	v_exp_f32_e32 v93, v93
	s_waitcnt lgkmcnt(0)
	v_mfma_f32_32x32x16_bf16 v[0:15], v[144:147], v[116:119], v[0:15]
	v_exp_f32_e32 v94, v94
	v_exp_f32_e32 v95, v95
	s_waitcnt vmcnt(2) lgkmcnt(0)
	s_barrier
; #define WAIT_BAR(N) asm volatile("s_waitcnt vmcnt(" #N ") lgkmcnt(0)\n\ts_barrier":::"memory")
;   #define RESC() do{ if(!NOMAX&&resc){ asm volatile("s_waitcnt lgkmcnt(0)":::"memory"); \
;       _Pragma("unroll") for(int d_=0;d_<2*VM;++d_) _Pragma("unroll") for(int r=0;r<16;++r)o[d_][r]*=wsf[crow(r,hi)]; } }while(0)
;   #define ROT() do{sl_prev=sl_cur;sl_cur=sl_next;sl_next=(sl_next==(NSLOT-1)*SLOTB)?0:sl_next+SLOTB;}while(0)
;   #define ENDW(tt) do{ if((tt)+3<NT){ if constexpr(VM==2){WAIT_BAR(3);}else{WAIT_BAR(2);} } else if((tt)+2<NT){ if constexpr(VM==2){WAIT_BAR(2);}else{WAIT_BAR(1);} } else {WAIT_BAR(0);} }while(0)
; template<int THRL,int VM,bool NOMAX> __device__ __forceinline__ void attn_unit(const bf16*Qb,const bf16*__restrict__ Kh,const bf16*__restrict__ Vh,bf16*Ob,const int NT,const int sp,float*wscr,char*shm){
;     ...
;   int t=1;
;   for(;t+5<NT;t+=2){
;     STEP(pB0,pB1,pA0,pA1,t,true,true,true);     if constexpr(VM==2){WAIT_BAR(3);}else{WAIT_BAR(2);} RESC(); ROT();
;     STEP(pA0,pA1,pB0,pB1,t+1,true,true,true);   if constexpr(VM==2){WAIT_BAR(3);}else{WAIT_BAR(2);} RESC(); ROT();
;   }
;     ...
;   for(;t+1<NT;t+=2){
;     STEP(pB0,pB1,pA0,pA1,t,(t+3<NT),(t+1<NT),(t+1<NT));       ENDW(t);   RESC(); ROT();
;     STEP(pA0,pA1,pB0,pB1,t+1,(t+4<NT),(t+2<NT),(t+2<NT));     ENDW(t+1); RESC(); ROT();
	ds_read_b64_tr_b16 v[178:179], v188 offset:40960
	ds_read_b64_tr_b16 v[180:181], v188 offset:41472
	v_add_f32_e32 v76, v96, v97
	ds_read_b128 v[72:75], v168
	v_add_f32_e32 v76, v98, v76
	v_add_f32_e32 v76, v99, v76
	v_add_f32_e32 v76, v100, v76
	v_add_f32_e32 v76, v101, v76
	v_cvt_pk_bf16_f32 v156, v96, v97
	v_cvt_pk_bf16_f32 v157, v98, v99
	s_waitcnt lgkmcnt(0)
	v_mfma_f32_32x32x16_bf16 v[112:127], v[68:71], v[72:75], 0
	ds_read_b64_tr_b16 v[96:97], v188 offset:45056
	ds_read_b64_tr_b16 v[98:99], v188 offset:45568
	ds_read_b128 v[68:71], v168
	v_add_f32_e32 v72, v102, v76
	v_add_f32_e32 v72, v103, v72
	v_add_f32_e32 v72, v104, v72
	v_add_f32_e32 v144, v105, v72
	s_waitcnt lgkmcnt(0)
	v_mfma_f32_32x32x16_bf16 v[64:79], v[64:67], v[68:71], 0
	v_cvt_pk_bf16_f32 v158, v100, v101
	v_cvt_pk_bf16_f32 v159, v102, v103
	ds_read_b64_tr_b16 v[100:101], v188 offset:41984
	ds_read_b64_tr_b16 v[102:103], v188 offset:42496
	ds_read_b128 v[190:193], v168 offset:1024
	v_add_f32_e32 v144, v106, v144
	v_add_f32_e32 v144, v107, v144
	v_add_f32_e32 v144, v108, v144
	v_add_f32_e32 v144, v109, v144
	v_cvt_pk_bf16_f32 v152, v104, v105
	v_cvt_pk_bf16_f32 v153, v106, v107
	s_waitcnt lgkmcnt(0)
	v_mfma_f32_32x32x16_bf16 v[112:127], v[164:167], v[190:193], v[112:127]
	ds_read_b64_tr_b16 v[104:105], v188 offset:46080
	ds_read_b64_tr_b16 v[106:107], v188 offset:46592
	ds_read_b128 v[164:167], v168 offset:1024
	v_add_f32_e32 v144, v110, v144
	v_add_f32_e32 v144, v111, v144
	v_add_f32_e32 v144, v80, v144
	v_add_f32_e32 v144, v81, v144
	s_waitcnt lgkmcnt(0)
	v_mfma_f32_32x32x16_bf16 v[64:79], v[140:143], v[164:167], v[64:79]
	v_cvt_pk_bf16_f32 v154, v108, v109
	v_cvt_pk_bf16_f32 v155, v110, v111
	ds_read_b64_tr_b16 v[108:109], v188 offset:43008
	ds_read_b64_tr_b16 v[110:111], v188 offset:43520
	ds_read_b128 v[140:143], v168 offset:2048
	v_add_f32_e32 v144, v82, v144
	v_add_f32_e32 v144, v83, v144
	v_add_f32_e32 v144, v84, v144
	v_add_f32_e32 v144, v85, v144
	v_cvt_pk_bf16_f32 v148, v80, v81
	v_cvt_pk_bf16_f32 v149, v82, v83
	s_waitcnt lgkmcnt(0)
	v_mfma_f32_32x32x16_bf16 v[112:127], v[160:163], v[140:143], v[112:127]
	ds_read_b64_tr_b16 v[190:191], v188 offset:47104
	ds_read_b64_tr_b16 v[192:193], v188 offset:47616
	ds_read_b128 v[80:83], v168 offset:2048
	v_add_f32_e32 v140, v86, v144
	v_add_f32_e32 v140, v87, v140
	v_add_f32_e32 v140, v88, v140
	v_add_f32_e32 v140, v89, v140
	s_waitcnt lgkmcnt(0)
	v_mfma_f32_32x32x16_bf16 v[64:79], v[132:135], v[80:83], v[64:79]
	v_cvt_pk_bf16_f32 v150, v84, v85
	v_cvt_pk_bf16_f32 v151, v86, v87
	ds_read_b64_tr_b16 v[84:85], v188 offset:44032
	ds_read_b64_tr_b16 v[86:87], v188 offset:44544
	ds_read_b128 v[80:83], v168 offset:3072
	v_add_f32_e32 v132, v90, v140
	v_add_f32_e32 v132, v91, v132
	v_add_f32_e32 v132, v92, v132
	v_add_f32_e32 v132, v93, v132
	v_cvt_pk_bf16_f32 v144, v88, v89
	v_cvt_pk_bf16_f32 v145, v90, v91
	s_waitcnt lgkmcnt(0)
	v_mfma_f32_32x32x16_bf16 v[112:127], v[136:139], v[80:83], v[112:127]
	ds_read_b64_tr_b16 v[88:89], v188 offset:48128
	ds_read_b64_tr_b16 v[90:91], v188 offset:48640
	ds_read_b128 v[80:83], v168 offset:3072
	v_add_f32_e32 v132, v94, v132
	v_add_f32_e32 v132, v95, v132
	v_add_f32_e32 v132, 0, v132
	v_cvt_pk_bf16_f32 v146, v92, v93
	s_waitcnt lgkmcnt(0)
	v_mfma_f32_32x32x16_bf16 v[64:79], v[128:131], v[80:83], v[64:79]
	v_cvt_pk_bf16_f32 v147, v94, v95
	v_lshl_add_u64 v[80:81], v[170:171], 0, s[64:65]
	s_mov_b32 s17, m0
	s_mov_b32 m0, s16
	s_nop 0
	global_load_lds_dwordx4 v[80:81], off
	s_mov_b32 m0, s17
	v_lshl_add_u64 v[80:81], v[172:173], 0, s[64:65]
	s_mov_b32 s16, m0
	s_mov_b32 m0, s35
	s_nop 0
	global_load_lds_dwordx4 v[80:81], off
	s_mov_b32 m0, s16
	v_add_f32_e32 v174, v174, v132
	v_mfma_f32_32x32x16_bf16 v[48:63], v[156:159], v[178:181], v[48:63]
	ds_read_b64_tr_b16 v[92:93], v188 offset:49152
	ds_read_b64_tr_b16 v[94:95], v188 offset:49664
	v_exp_f32_e32 v112, v112
	v_exp_f32_e32 v113, v113
	v_mfma_f32_32x32x16_bf16 v[32:47], v[156:159], v[96:99], v[32:47]
	ds_read_b64_tr_b16 v[170:171], v188 offset:53248
	ds_read_b64_tr_b16 v[172:173], v188 offset:53760
	v_exp_f32_e32 v114, v114
	v_exp_f32_e32 v115, v115
	ds_read_b128 v[80:83], v234
	ds_read_b128 v[96:99], v234 offset:4096
	v_mfma_f32_32x32x16_bf16 v[48:63], v[152:155], v[100:103], v[48:63]
	ds_read_b64_tr_b16 v[178:179], v188 offset:50176
	ds_read_b64_tr_b16 v[180:181], v188 offset:50688
	v_exp_f32_e32 v116, v116
	v_exp_f32_e32 v117, v117
	ds_read_b128 v[164:167], v235
	ds_read_b128 v[140:143], v235 offset:4096
	v_mfma_f32_32x32x16_bf16 v[32:47], v[152:155], v[104:107], v[32:47]
	ds_read_b64_tr_b16 v[100:101], v188 offset:54272
	ds_read_b64_tr_b16 v[102:103], v188 offset:54784
	v_exp_f32_e32 v118, v118
	v_exp_f32_e32 v119, v119
	ds_read_b128 v[160:163], v236
	ds_read_b128 v[132:135], v236 offset:4096
	v_mfma_f32_32x32x16_bf16 v[48:63], v[148:151], v[108:111], v[48:63]
	ds_read_b64_tr_b16 v[104:105], v188 offset:51200
	ds_read_b64_tr_b16 v[106:107], v188 offset:51712
	v_exp_f32_e32 v120, v120
	v_exp_f32_e32 v121, v121
	ds_read_b128 v[136:139], v237
	ds_read_b128 v[128:131], v237 offset:4096
	v_mfma_f32_32x32x16_bf16 v[32:47], v[148:151], v[190:193], v[32:47]
	ds_read_b64_tr_b16 v[108:109], v188 offset:55296
	ds_read_b64_tr_b16 v[110:111], v188 offset:55808
	v_exp_f32_e32 v122, v122
	v_exp_f32_e32 v123, v123
	v_mfma_f32_32x32x16_bf16 v[48:63], v[144:147], v[84:87], v[48:63]
	ds_read_b64_tr_b16 v[190:191], v188 offset:52224
	ds_read_b64_tr_b16 v[192:193], v188 offset:52736
	v_exp_f32_e32 v124, v124
	v_exp_f32_e32 v125, v125
	v_mfma_f32_32x32x16_bf16 v[32:47], v[144:147], v[88:91], v[32:47]
	ds_read_b64_tr_b16 v[84:85], v188 offset:56320
	ds_read_b64_tr_b16 v[86:87], v188 offset:56832
	v_exp_f32_e32 v126, v126
	v_exp_f32_e32 v127, v127
	s_waitcnt lgkmcnt(14)
	v_mfma_f32_32x32x16_bf16 v[16:31], v[156:159], v[92:95], v[16:31]
	v_exp_f32_e32 v64, v64
	v_exp_f32_e32 v65, v65
	v_mfma_f32_32x32x16_bf16 v[0:15], v[156:159], v[170:173], v[0:15]
	v_exp_f32_e32 v66, v66
	v_exp_f32_e32 v67, v67
	v_mfma_f32_32x32x16_bf16 v[16:31], v[152:155], v[178:181], v[16:31]
	v_exp_f32_e32 v68, v68
	v_exp_f32_e32 v69, v69
	s_waitcnt lgkmcnt(12)
	v_mfma_f32_32x32x16_bf16 v[0:15], v[152:155], v[100:103], v[0:15]
	v_exp_f32_e32 v70, v70
	v_exp_f32_e32 v71, v71
	s_waitcnt lgkmcnt(8)
	v_mfma_f32_32x32x16_bf16 v[16:31], v[148:151], v[104:107], v[16:31]
	v_exp_f32_e32 v72, v72
	v_exp_f32_e32 v73, v73
	s_waitcnt lgkmcnt(4)
	v_mfma_f32_32x32x16_bf16 v[0:15], v[148:151], v[108:111], v[0:15]
	v_exp_f32_e32 v74, v74
	v_exp_f32_e32 v75, v75
	s_waitcnt lgkmcnt(2)
	v_mfma_f32_32x32x16_bf16 v[16:31], v[144:147], v[190:193], v[16:31]
	v_exp_f32_e32 v76, v76
	v_exp_f32_e32 v77, v77
	s_waitcnt lgkmcnt(0)
	v_mfma_f32_32x32x16_bf16 v[0:15], v[144:147], v[84:87], v[0:15]
	v_exp_f32_e32 v78, v78
	v_exp_f32_e32 v79, v79
	s_waitcnt vmcnt(0) lgkmcnt(0)
	s_barrier
;   #define RESC() do{ if(!NOMAX&&resc){ asm volatile("s_waitcnt lgkmcnt(0)":::"memory"); \
;       _Pragma("unroll") for(int d_=0;d_<2*VM;++d_) _Pragma("unroll") for(int r=0;r<16;++r)o[d_][r]*=wsf[crow(r,hi)]; } }while(0)
; template<int THRL,int VM,bool NOMAX> __device__ __forceinline__ void attn_unit(const bf16*Qb,const bf16*__restrict__ Kh,const bf16*__restrict__ Vh,bf16*Ob,const int NT,const int sp,float*wscr,char*shm){
;     ...
;   STEP(pB0,pB1,pA0,pA1,NT-1,false,false,false); RESC();
	ds_read_b64_tr_b16 v[170:171], v188 offset:57344
	ds_read_b64_tr_b16 v[172:173], v188 offset:57856
	v_add_f32_e32 v88, v112, v113
	ds_read_b128 v[84:87], v168
	v_add_f32_e32 v88, v114, v88
	v_add_f32_e32 v88, v115, v88
	v_add_f32_e32 v88, v116, v88
	v_add_f32_e32 v104, v117, v88
	v_cvt_pk_bf16_f32 v156, v112, v113
	v_cvt_pk_bf16_f32 v157, v114, v115
	s_waitcnt lgkmcnt(0)
	v_mfma_f32_32x32x16_bf16 v[80:95], v[80:83], v[84:87], 0
	ds_read_b64_tr_b16 v[112:113], v188 offset:61440
	ds_read_b64_tr_b16 v[114:115], v188 offset:61952
	ds_read_b128 v[100:103], v168
	v_add_f32_e32 v104, v118, v104
	v_add_f32_e32 v104, v119, v104
	v_add_f32_e32 v104, v120, v104
	v_add_f32_e32 v144, v121, v104
	v_cvt_pk_bf16_f32 v158, v116, v117
	v_cvt_pk_bf16_f32 v159, v118, v119
	s_waitcnt lgkmcnt(0)
	v_mfma_f32_32x32x16_bf16 v[96:111], v[96:99], v[100:103], 0
	ds_read_b64_tr_b16 v[116:117], v188 offset:58368
	ds_read_b64_tr_b16 v[118:119], v188 offset:58880
	ds_read_b128 v[178:181], v168 offset:1024
	v_add_f32_e32 v144, v122, v144
	v_add_f32_e32 v144, v123, v144
	v_add_f32_e32 v144, v124, v144
	v_add_f32_e32 v144, v125, v144
	v_cvt_pk_bf16_f32 v152, v120, v121
	v_cvt_pk_bf16_f32 v153, v122, v123
	s_waitcnt lgkmcnt(0)
	v_mfma_f32_32x32x16_bf16 v[80:95], v[164:167], v[178:181], v[80:95]
	ds_read_b64_tr_b16 v[120:121], v188 offset:62464
	ds_read_b64_tr_b16 v[122:123], v188 offset:62976
	ds_read_b128 v[164:167], v168 offset:1024
	v_add_f32_e32 v144, v126, v144
	v_add_f32_e32 v144, v127, v144
	v_add_f32_e32 v144, v64, v144
	v_add_f32_e32 v144, v65, v144
	v_cvt_pk_bf16_f32 v154, v124, v125
	v_cvt_pk_bf16_f32 v155, v126, v127
	s_waitcnt lgkmcnt(0)
	v_mfma_f32_32x32x16_bf16 v[96:111], v[140:143], v[164:167], v[96:111]
	ds_read_b64_tr_b16 v[124:125], v188 offset:59392
	ds_read_b64_tr_b16 v[126:127], v188 offset:59904
	ds_read_b128 v[140:143], v168 offset:2048
	v_add_f32_e32 v144, v66, v144
	v_add_f32_e32 v144, v67, v144
	v_add_f32_e32 v144, v68, v144
	v_add_f32_e32 v144, v69, v144
	v_cvt_pk_bf16_f32 v148, v64, v65
	v_cvt_pk_bf16_f32 v149, v66, v67
	s_waitcnt lgkmcnt(0)
	v_mfma_f32_32x32x16_bf16 v[80:95], v[160:163], v[140:143], v[80:95]
	ds_read_b64_tr_b16 v[64:65], v188 offset:63488
	ds_read_b64_tr_b16 v[66:67], v188 offset:64000
	ds_read_b128 v[140:143], v168 offset:2048
	v_add_f32_e32 v144, v70, v144
	v_add_f32_e32 v144, v71, v144
	v_add_f32_e32 v144, v72, v144
	v_add_f32_e32 v144, v73, v144
	v_cvt_pk_bf16_f32 v150, v68, v69
	v_cvt_pk_bf16_f32 v151, v70, v71
	s_waitcnt lgkmcnt(0)
	v_mfma_f32_32x32x16_bf16 v[96:111], v[132:135], v[140:143], v[96:111]
	ds_read_b64_tr_b16 v[68:69], v188 offset:60416
	ds_read_b64_tr_b16 v[70:71], v188 offset:60928
	ds_read_b128 v[132:135], v168 offset:3072
	v_add_f32_e32 v140, v74, v144
	v_add_f32_e32 v140, v75, v140
	v_add_f32_e32 v140, v76, v140
	v_add_f32_e32 v140, v77, v140
	v_cvt_pk_bf16_f32 v144, v72, v73
	v_cvt_pk_bf16_f32 v145, v74, v75
	s_waitcnt lgkmcnt(0)
	v_mfma_f32_32x32x16_bf16 v[80:95], v[136:139], v[132:135], v[80:95]
	ds_read_b64_tr_b16 v[72:73], v188 offset:64512
	ds_read_b64_tr_b16 v[74:75], v188 offset:65024
	ds_read_b128 v[132:135], v168 offset:3072
	v_add_f32_e32 v136, v78, v140
	v_add_f32_e32 v136, v79, v136
	v_add_f32_e32 v136, 0, v136
	v_cvt_pk_bf16_f32 v146, v76, v77
	v_cvt_pk_bf16_f32 v147, v78, v79
	s_waitcnt lgkmcnt(0)
	v_mfma_f32_32x32x16_bf16 v[96:111], v[128:131], v[132:135], v[96:111]
	v_mfma_f32_32x32x16_bf16 v[48:63], v[156:159], v[170:173], v[48:63]
	ds_read_b64_tr_b16 v[76:77], v177 offset:40960
	ds_read_b64_tr_b16 v[78:79], v177 offset:41472
	v_exp_f32_e32 v80, v80
	v_exp_f32_e32 v81, v81
	v_mfma_f32_32x32x16_bf16 v[32:47], v[156:159], v[112:115], v[32:47]
	ds_read_b64_tr_b16 v[128:129], v177 offset:45056
	ds_read_b64_tr_b16 v[130:131], v177 offset:45568
	v_exp_f32_e32 v82, v82
	v_exp_f32_e32 v83, v83
	v_mfma_f32_32x32x16_bf16 v[48:63], v[152:155], v[116:119], v[48:63]
	ds_read_b64_tr_b16 v[112:113], v177 offset:41984
	ds_read_b64_tr_b16 v[114:115], v177 offset:42496
	v_exp_f32_e32 v84, v84
	v_exp_f32_e32 v85, v85
	v_mfma_f32_32x32x16_bf16 v[32:47], v[152:155], v[120:123], v[32:47]
	ds_read_b64_tr_b16 v[116:117], v177 offset:46080
	ds_read_b64_tr_b16 v[118:119], v177 offset:46592
	v_exp_f32_e32 v86, v86
	v_exp_f32_e32 v87, v87
	v_mfma_f32_32x32x16_bf16 v[48:63], v[148:151], v[124:127], v[48:63]
	ds_read_b64_tr_b16 v[120:121], v177 offset:43008
	ds_read_b64_tr_b16 v[122:123], v177 offset:43520
	v_exp_f32_e32 v88, v88
	v_exp_f32_e32 v89, v89
	v_mfma_f32_32x32x16_bf16 v[32:47], v[148:151], v[64:67], v[32:47]
	ds_read_b64_tr_b16 v[124:125], v177 offset:47104
	ds_read_b64_tr_b16 v[126:127], v177 offset:47616
	v_exp_f32_e32 v90, v90
	v_exp_f32_e32 v91, v91
	v_mfma_f32_32x32x16_bf16 v[48:63], v[144:147], v[68:71], v[48:63]
	ds_read_b64_tr_b16 v[64:65], v177 offset:44032
	ds_read_b64_tr_b16 v[66:67], v177 offset:44544
	v_exp_f32_e32 v92, v92
	v_exp_f32_e32 v93, v93
	v_mfma_f32_32x32x16_bf16 v[32:47], v[144:147], v[72:75], v[32:47]
	ds_read_b64_tr_b16 v[68:69], v177 offset:48128
	ds_read_b64_tr_b16 v[70:71], v177 offset:48640
	v_exp_f32_e32 v94, v94
	v_exp_f32_e32 v95, v95
	s_waitcnt lgkmcnt(14)
	v_mfma_f32_32x32x16_bf16 v[16:31], v[156:159], v[76:79], v[16:31]
	v_exp_f32_e32 v96, v96
	v_exp_f32_e32 v97, v97
	s_waitcnt lgkmcnt(12)
; #define SBAR() __builtin_amdgcn_sched_barrier(0)
;   #define RESC() do{ if(!NOMAX&&resc){ asm volatile("s_waitcnt lgkmcnt(0)":::"memory"); \
;       _Pragma("unroll") for(int d_=0;d_<2*VM;++d_) _Pragma("unroll") for(int r=0;r<16;++r)o[d_][r]*=wsf[crow(r,hi)]; } }while(0)
;   #define PKW(P,B) cvtpk_s(P[B],P[B+1])
; template<int THRL,int VM,bool NOMAX> __device__ __forceinline__ void attn_unit(const bf16*Qb,const bf16*__restrict__ Kh,const bf16*__restrict__ Vh,bf16*Ob,const int NT,const int sp,float*wscr,char*shm){
;     ...
;   STEP(pB0,pB1,pA0,pA1,NT-1,false,false,false); RESC();
;   { float sacc=pB0[0]+pB0[1]; _Pragma("unroll") for(int r=2;r<16;++r)sacc+=pB0[r]; _Pragma("unroll") for(int r=0;r<16;++r)sacc+=pB1[r]; l_reg+=sacc;
;     pw0=(u32x4){PKW(pB0,0),PKW(pB0,2),PKW(pB0,4),PKW(pB0,6)};pw1=(u32x4){PKW(pB0,8),PKW(pB0,10),PKW(pB0,12),PKW(pB0,14)};pw2=(u32x4){PKW(pB1,0),PKW(pB1,2),PKW(pB1,4),PKW(pB1,6)};pw3=(u32x4){PKW(pB1,8),PKW(pB1,10),PKW(pB1,12),PKW(pB1,14)};
;     SBAR(); pv(o,vb0+VM*sl_cur,PAF(0),PAF(1),PAF(2),PAF(3)); if constexpr(VM==2) pv(o+2,vb0+VM*sl_cur+8192,PAF(0),PAF(1),PAF(2),PAF(3)); }
;     ...
;   {auto rr=__builtin_amdgcn_permlane32_swap(__float_as_uint(l_reg),__float_as_uint(l_reg),false,false);l_reg=__uint_as_float(rr[0])+__uint_as_float(rr[1]);}
;   if(hi==0)wsf[32+r32]=l_reg;asm volatile("s_waitcnt lgkmcnt(0)":::"memory");
	v_mfma_f32_32x32x16_bf16 v[0:15], v[156:159], v[128:131], v[0:15]
	v_exp_f32_e32 v98, v98
	v_exp_f32_e32 v99, v99
	s_waitcnt lgkmcnt(10)
	v_mfma_f32_32x32x16_bf16 v[16:31], v[152:155], v[112:115], v[16:31]
	v_exp_f32_e32 v100, v100
	v_exp_f32_e32 v101, v101
	s_waitcnt lgkmcnt(8)
	v_mfma_f32_32x32x16_bf16 v[0:15], v[152:155], v[116:119], v[0:15]
	v_exp_f32_e32 v102, v102
	v_exp_f32_e32 v103, v103
	s_waitcnt lgkmcnt(6)
	v_mfma_f32_32x32x16_bf16 v[16:31], v[148:151], v[120:123], v[16:31]
	v_exp_f32_e32 v104, v104
	v_exp_f32_e32 v105, v105
	s_waitcnt lgkmcnt(4)
	v_mfma_f32_32x32x16_bf16 v[0:15], v[148:151], v[124:127], v[0:15]
	v_exp_f32_e32 v106, v106
	v_exp_f32_e32 v107, v107
	s_waitcnt lgkmcnt(2)
	v_mfma_f32_32x32x16_bf16 v[16:31], v[144:147], v[64:67], v[16:31]
	v_exp_f32_e32 v108, v108
	v_exp_f32_e32 v109, v109
	s_waitcnt lgkmcnt(0)
	v_mfma_f32_32x32x16_bf16 v[0:15], v[144:147], v[68:71], v[0:15]
	v_exp_f32_e32 v110, v110
	v_exp_f32_e32 v111, v111
	v_add_f32_e32 v64, v80, v81
	v_add_f32_e32 v64, v82, v64
	v_add_f32_e32 v64, v83, v64
	v_add_f32_e32 v64, v84, v64
	v_add_f32_e32 v64, v85, v64
	v_add_f32_e32 v64, v86, v64
	v_add_f32_e32 v64, v87, v64
	v_add_f32_e32 v64, v88, v64
	v_add_f32_e32 v64, v89, v64
	v_add_f32_e32 v64, v90, v64
	v_add_f32_e32 v64, v91, v64
	v_add_f32_e32 v64, v92, v64
	v_add_f32_e32 v64, v93, v64
	v_add_f32_e32 v64, v94, v64
	v_add_f32_e32 v64, v95, v64
	v_add_f32_e32 v64, v64, v96
	v_add_f32_e32 v64, v97, v64
	v_add_f32_e32 v64, v98, v64
	v_add_f32_e32 v64, v99, v64
	v_add_f32_e32 v64, v100, v64
	v_add_f32_e32 v64, v101, v64
	v_add_f32_e32 v64, v102, v64
	v_add_f32_e32 v64, v103, v64
	v_add_f32_e32 v64, v104, v64
	v_add_f32_e32 v64, v105, v64
	v_add_f32_e32 v64, v106, v64
	v_add_f32_e32 v64, v107, v64
	v_add_f32_e32 v64, v108, v64
	v_add_f32_e32 v64, v109, v64
	v_add_f32_e32 v64, v110, v64
	v_add_f32_e32 v64, v111, v64
	v_add_f32_e32 v65, v174, v136
	v_add_f32_e32 v64, v65, v64
	v_cvt_pk_bf16_f32 v66, v80, v81
	v_cvt_pk_bf16_f32 v67, v82, v83
	v_cvt_pk_bf16_f32 v68, v84, v85
	v_cvt_pk_bf16_f32 v69, v86, v87
	v_cvt_pk_bf16_f32 v70, v88, v89
	v_cvt_pk_bf16_f32 v71, v90, v91
	v_cvt_pk_bf16_f32 v72, v92, v93
	v_cvt_pk_bf16_f32 v73, v94, v95
	v_cvt_pk_bf16_f32 v74, v96, v97
	v_cvt_pk_bf16_f32 v75, v98, v99
	v_cvt_pk_bf16_f32 v76, v100, v101
	v_cvt_pk_bf16_f32 v77, v102, v103
	v_cvt_pk_bf16_f32 v78, v104, v105
	v_cvt_pk_bf16_f32 v79, v106, v107
	v_cvt_pk_bf16_f32 v80, v108, v109
	v_cvt_pk_bf16_f32 v81, v110, v111
	ds_read_b64_tr_b16 v[82:83],v176 offset:0
	ds_read_b64_tr_b16 v[84:85],v176 offset:512
	ds_read_b64_tr_b16 v[86:87],v176 offset:1024
	ds_read_b64_tr_b16 v[88:89],v176 offset:1536
	ds_read_b64_tr_b16 v[90:91],v176 offset:2048
	ds_read_b64_tr_b16 v[92:93],v176 offset:2560
	ds_read_b64_tr_b16 v[94:95],v176 offset:3072
	ds_read_b64_tr_b16 v[96:97],v176 offset:3584
	s_waitcnt lgkmcnt(0)
	s_nop 0
	v_mfma_f32_32x32x16_bf16 v[48:63], v[66:69], v[82:85], v[48:63]
	ds_read_b64_tr_b16 v[82:83],v176 offset:4096
	ds_read_b64_tr_b16 v[84:85],v176 offset:4608
	v_mfma_f32_32x32x16_bf16 v[48:63], v[70:73], v[86:89], v[48:63]
	ds_read_b64_tr_b16 v[86:87],v176 offset:5120
	ds_read_b64_tr_b16 v[88:89],v176 offset:5632
	v_mfma_f32_32x32x16_bf16 v[48:63], v[74:77], v[90:93], v[48:63]
	ds_read_b64_tr_b16 v[90:91],v176 offset:6144
	ds_read_b64_tr_b16 v[92:93],v176 offset:6656
	ds_read_b64_tr_b16 v[98:99],v176 offset:7168
	ds_read_b64_tr_b16 v[100:101],v176 offset:7680
	s_waitcnt lgkmcnt(0)
	v_mfma_f32_32x32x16_bf16 v[48:63], v[78:81], v[94:97], v[48:63]
	v_mfma_f32_32x32x16_bf16 v[32:47], v[66:69], v[82:85], v[32:47]
	v_add_u32_e32 v65, 0x2000, v176
	ds_read_b64_tr_b16 v[82:83],v65 offset:0
	ds_read_b64_tr_b16 v[84:85],v65 offset:512
	v_mfma_f32_32x32x16_bf16 v[32:47], v[70:73], v[86:89], v[32:47]
	ds_read_b64_tr_b16 v[86:87],v65 offset:1024
	ds_read_b64_tr_b16 v[88:89],v65 offset:1536
	v_mfma_f32_32x32x16_bf16 v[32:47], v[74:77], v[90:93], v[32:47]
	ds_read_b64_tr_b16 v[90:91],v65 offset:2048
	ds_read_b64_tr_b16 v[92:93],v65 offset:2560
	ds_read_b64_tr_b16 v[94:95],v65 offset:3072
	ds_read_b64_tr_b16 v[96:97],v65 offset:3584
	s_waitcnt lgkmcnt(0)
	v_mfma_f32_32x32x16_bf16 v[32:47], v[78:81], v[98:101], v[32:47]
	v_mfma_f32_32x32x16_bf16 v[16:31], v[66:69], v[82:85], v[16:31]
	ds_read_b64_tr_b16 v[82:83],v65 offset:4096
	ds_read_b64_tr_b16 v[84:85],v65 offset:4608
	v_mfma_f32_32x32x16_bf16 v[16:31], v[70:73], v[86:89], v[16:31]
	ds_read_b64_tr_b16 v[86:87],v65 offset:5120
	ds_read_b64_tr_b16 v[88:89],v65 offset:5632
	v_mfma_f32_32x32x16_bf16 v[16:31], v[74:77], v[90:93], v[16:31]
	ds_read_b64_tr_b16 v[90:91],v65 offset:6144
	ds_read_b64_tr_b16 v[92:93],v65 offset:6656
	ds_read_b64_tr_b16 v[98:99],v65 offset:7168
	ds_read_b64_tr_b16 v[100:101],v65 offset:7680
	s_waitcnt lgkmcnt(0)
	v_mfma_f32_32x32x16_bf16 v[16:31], v[78:81], v[94:97], v[16:31]
	v_mfma_f32_32x32x16_bf16 v[0:15], v[66:69], v[82:85], v[0:15]
	v_mov_b32_e32 v65, v64
	s_nop 1
	v_permlane32_swap_b32_e32 v64, v65
	v_cmp_gt_u32_e32 vcc, 32, v187
	v_mfma_f32_32x32x16_bf16 v[0:15], v[70:73], v[86:89], v[0:15]
	v_mfma_f32_32x32x16_bf16 v[0:15], v[74:77], v[90:93], v[0:15]
	v_mfma_f32_32x32x16_bf16 v[0:15], v[78:81], v[98:101], v[0:15]
	s_and_saveexec_b64 s[16:17], vcc
	s_cbranch_execz .LBB0_870
	v_add_f32_e32 v64, v64, v65
	v_lshl_add_u32 v65, v186, 2, s34
	ds_write_b32 v65, v64 offset:128
	s_branch .LBB0_870

; #define WAIT_BAR(N) asm volatile("s_waitcnt vmcnt(" #N ") lgkmcnt(0)\n\ts_barrier":::"memory")
;   #define RESC() do{ if(!NOMAX&&resc){ asm volatile("s_waitcnt lgkmcnt(0)":::"memory"); \
;       _Pragma("unroll") for(int d_=0;d_<2*VM;++d_) _Pragma("unroll") for(int r=0;r<16;++r)o[d_][r]*=wsf[crow(r,hi)]; } }while(0)
;   #define ROT() do{sl_prev=sl_cur;sl_cur=sl_next;sl_next=(sl_next==(NSLOT-1)*SLOTB)?0:sl_next+SLOTB;}while(0)
; template<int THRL,int VM,bool NOMAX> __device__ __forceinline__ void attn_unit(const bf16*Qb,const bf16*__restrict__ Kh,const bf16*__restrict__ Vh,bf16*Ob,const int NT,const int sp,float*wscr,char*shm){
;     ...
;   int t=1;
;   for(;t+5<NT;t+=2){
;     STEP(pB0,pB1,pA0,pA1,t,true,true,true);     if constexpr(VM==2){WAIT_BAR(3);}else{WAIT_BAR(2);} RESC(); ROT();
.LBB0_882:
	v_mfma_f32_32x32x16_bf16 v[96:111], v[84:87], v[156:159], 0
	v_add_u32_e32 v187, s54, v182
	ds_read_b64_tr_b16 v[188:189], v187 offset:24576
	ds_read_b64_tr_b16 v[190:191], v187 offset:25088
	v_add_f32_e32 v88, v64, v65
	v_add_f32_e32 v88, v66, v88
	v_add_f32_e32 v88, v67, v88
	v_add_f32_e32 v88, v68, v88
	v_add_f32_e32 v88, v69, v88
	v_cvt_pk_bf16_f32 v140, v64, v65
	v_cvt_pk_bf16_f32 v141, v66, v67
	ds_read_b64_tr_b16 v[64:65], v187 offset:28672
	ds_read_b64_tr_b16 v[66:67], v187 offset:29184
	v_add_f32_e32 v84, v70, v88
	v_add_f32_e32 v84, v71, v84
	v_add_f32_e32 v84, v72, v84
	v_add_f32_e32 v128, v73, v84
	v_mfma_f32_32x32x16_bf16 v[80:95], v[80:83], v[156:159], 0
	v_cvt_pk_bf16_f32 v142, v68, v69
	v_cvt_pk_bf16_f32 v143, v70, v71
	ds_read_b64_tr_b16 v[68:69], v187 offset:25600
	ds_read_b64_tr_b16 v[70:71], v187 offset:26112
	v_add_f32_e32 v128, v74, v128
	v_add_f32_e32 v128, v75, v128
	v_add_f32_e32 v128, v76, v128
	v_add_f32_e32 v128, v77, v128
	v_cvt_pk_bf16_f32 v136, v72, v73
	v_cvt_pk_bf16_f32 v137, v74, v75
	v_mfma_f32_32x32x16_bf16 v[96:111], v[164:167], v[152:155], v[96:111]
	ds_read_b64_tr_b16 v[72:73], v187 offset:29696
	ds_read_b64_tr_b16 v[74:75], v187 offset:30208
	v_mfma_f32_32x32x16_bf16 v[80:95], v[160:163], v[152:155], v[80:95]
	v_add_f32_e32 v128, v78, v128
	v_add_f32_e32 v128, v79, v128
	v_add_f32_e32 v128, v48, v128
	v_add_f32_e32 v128, v49, v128
	v_cvt_pk_bf16_f32 v138, v76, v77
	v_cvt_pk_bf16_f32 v139, v78, v79
	ds_read_b64_tr_b16 v[76:77], v187 offset:26624
	ds_read_b64_tr_b16 v[78:79], v187 offset:27136
	v_add_f32_e32 v128, v50, v128
	v_add_f32_e32 v128, v51, v128
	v_add_f32_e32 v128, v52, v128
	v_add_f32_e32 v128, v53, v128
	v_cvt_pk_bf16_f32 v132, v48, v49
	v_cvt_pk_bf16_f32 v133, v50, v51
	v_mfma_f32_32x32x16_bf16 v[96:111], v[124:127], v[148:151], v[96:111]
	ds_read_b64_tr_b16 v[48:49], v187 offset:30720
	ds_read_b64_tr_b16 v[50:51], v187 offset:31232
	v_mfma_f32_32x32x16_bf16 v[80:95], v[120:123], v[148:151], v[80:95]
	v_add_f32_e32 v124, v54, v128
	v_add_f32_e32 v124, v55, v124
	v_add_f32_e32 v124, v56, v124
	v_add_f32_e32 v124, v57, v124
	v_cvt_pk_bf16_f32 v134, v52, v53
	v_cvt_pk_bf16_f32 v135, v54, v55
	ds_read_b64_tr_b16 v[52:53], v187 offset:27648
	ds_read_b64_tr_b16 v[54:55], v187 offset:28160
	v_add_f32_e32 v120, v58, v124
	v_add_f32_e32 v120, v59, v120
	v_add_f32_e32 v120, v60, v120
	v_add_f32_e32 v120, v61, v120
	v_cvt_pk_bf16_f32 v128, v56, v57
	v_cvt_pk_bf16_f32 v129, v58, v59
	v_mfma_f32_32x32x16_bf16 v[96:111], v[116:119], v[144:147], v[96:111]
	ds_read_b64_tr_b16 v[56:57], v187 offset:31744
	ds_read_b64_tr_b16 v[58:59], v187 offset:32256
	v_mfma_f32_32x32x16_bf16 v[80:95], v[112:115], v[144:147], v[80:95]
	v_add_f32_e32 v116, v62, v120
	v_add_f32_e32 v116, v63, v116
	v_cvt_pk_bf16_f32 v130, v60, v61
	v_cvt_pk_bf16_f32 v131, v62, v63
	s_add_i32 m0, s52, s33
	v_lshl_add_u64 v[60:61], v[176:177], 0, s[38:39]
	global_load_lds_dwordx4 v[60:61], off
	s_add_i32 m0, s35, s16
	v_lshl_add_u64 v[60:61], v[174:175], 0, s[38:39]
	global_load_lds_dwordx4 v[60:61], off
	v_add_f32_e32 v202, v186, v116
	s_waitcnt lgkmcnt(12)
	v_mfma_f32_32x32x16_bf16 v[16:31], v[140:143], v[188:191], v[16:31]
	v_exp_f32_e32 v96, v96
	v_exp_f32_e32 v97, v97
	v_exp_f32_e32 v98, v98
	v_exp_f32_e32 v99, v99
	v_mfma_f32_32x32x16_bf16 v[32:47], v[140:143], v[64:67], v[32:47]
	v_exp_f32_e32 v100, v100
	v_exp_f32_e32 v101, v101
	v_exp_f32_e32 v102, v102
	v_exp_f32_e32 v103, v103
	v_add_u32_e32 v242, s35, v234
	v_add_u32_e32 v243, s35, v235
	v_add_u32_e32 v244, s35, v236
	v_add_u32_e32 v245, s35, v237
	ds_read_b128 v[60:63], v242
	ds_read_b128 v[112:115], v242 offset:4096
	s_waitcnt lgkmcnt(10)
	v_mfma_f32_32x32x16_bf16 v[16:31], v[136:139], v[68:71], v[16:31]
	v_exp_f32_e32 v104, v104
	v_exp_f32_e32 v105, v105
	v_exp_f32_e32 v106, v106
	v_exp_f32_e32 v107, v107
	ds_read_b128 v[116:119], v243
	ds_read_b128 v[120:123], v243 offset:4096
	v_mfma_f32_32x32x16_bf16 v[32:47], v[136:139], v[72:75], v[32:47]
	v_exp_f32_e32 v108, v108
	v_exp_f32_e32 v109, v109
	v_exp_f32_e32 v110, v110
	v_exp_f32_e32 v111, v111
	ds_read_b128 v[124:127], v244
	ds_read_b128 v[160:163], v244 offset:4096
	s_waitcnt lgkmcnt(10)
	v_mfma_f32_32x32x16_bf16 v[16:31], v[132:135], v[76:79], v[16:31]
	v_exp_f32_e32 v80, v80
	v_exp_f32_e32 v81, v81
	v_exp_f32_e32 v82, v82
	v_exp_f32_e32 v83, v83
	ds_read_b128 v[164:167], v245
	ds_read_b128 v[186:189], v245 offset:4096
	v_mfma_f32_32x32x16_bf16 v[32:47], v[132:135], v[48:51], v[32:47]
	v_exp_f32_e32 v84, v84
	v_exp_f32_e32 v85, v85
	v_exp_f32_e32 v86, v86
	v_exp_f32_e32 v87, v87
	s_waitcnt lgkmcnt(8)
	v_mfma_f32_32x32x16_bf16 v[16:31], v[128:131], v[52:55], v[16:31]
	v_exp_f32_e32 v88, v88
	v_exp_f32_e32 v89, v89
	v_exp_f32_e32 v90, v90
	v_exp_f32_e32 v91, v91
	v_mfma_f32_32x32x16_bf16 v[32:47], v[128:131], v[56:59], v[32:47]
	v_exp_f32_e32 v92, v92
	v_exp_f32_e32 v93, v93
	v_exp_f32_e32 v94, v94
	v_exp_f32_e32 v95, v95
	s_waitcnt vmcnt(2) lgkmcnt(0)
	s_barrier
; #define WAIT_BAR(N) asm volatile("s_waitcnt vmcnt(" #N ") lgkmcnt(0)\n\ts_barrier":::"memory")
;   #define RESC() do{ if(!NOMAX&&resc){ asm volatile("s_waitcnt lgkmcnt(0)":::"memory"); \
;       _Pragma("unroll") for(int d_=0;d_<2*VM;++d_) _Pragma("unroll") for(int r=0;r<16;++r)o[d_][r]*=wsf[crow(r,hi)]; } }while(0)
;   #define ROT() do{sl_prev=sl_cur;sl_cur=sl_next;sl_next=(sl_next==(NSLOT-1)*SLOTB)?0:sl_next+SLOTB;}while(0)
; template<int THRL,int VM,bool NOMAX> __device__ __forceinline__ void attn_unit(const bf16*Qb,const bf16*__restrict__ Kh,const bf16*__restrict__ Vh,bf16*Ob,const int NT,const int sp,float*wscr,char*shm){
;     ...
;   int t=1;
;   for(;t+5<NT;t+=2){
;     STEP(pB0,pB1,pA0,pA1,t,true,true,true);     if constexpr(VM==2){WAIT_BAR(3);}else{WAIT_BAR(2);} RESC(); ROT();
;     STEP(pA0,pA1,pB0,pB1,t+1,true,true,true);   if constexpr(VM==2){WAIT_BAR(3);}else{WAIT_BAR(2);} RESC(); ROT();
	v_mfma_f32_32x32x16_bf16 v[64:79], v[60:63], v[156:159], 0
	s_add_i32 s53, s35, 0x2000
	s_cmpk_lg_i32 s35, 0x4000
	s_cselect_b32 s53, s53, 0
	v_add_u32_e32 v203, s52, v182
	ds_read_b64_tr_b16 v[190:191], v203 offset:24576
	ds_read_b64_tr_b16 v[192:193], v203 offset:25088
	v_add_f32_e32 v48, v96, v97
	v_add_f32_e32 v48, v98, v48
	v_add_f32_e32 v48, v99, v48
	v_add_f32_e32 v48, v100, v48
	v_add_f32_e32 v48, v101, v48
	v_cvt_pk_bf16_f32 v140, v96, v97
	v_cvt_pk_bf16_f32 v141, v98, v99
	ds_read_b64_tr_b16 v[96:97], v203 offset:28672
	ds_read_b64_tr_b16 v[98:99], v203 offset:29184
	v_add_f32_e32 v48, v102, v48
	v_add_f32_e32 v48, v103, v48
	v_add_f32_e32 v48, v104, v48
	v_add_f32_e32 v128, v105, v48
	v_mfma_f32_32x32x16_bf16 v[48:63], v[112:115], v[156:159], 0
	v_cvt_pk_bf16_f32 v142, v100, v101
	v_cvt_pk_bf16_f32 v143, v102, v103
	ds_read_b64_tr_b16 v[100:101], v203 offset:25600
	ds_read_b64_tr_b16 v[102:103], v203 offset:26112
	v_mfma_f32_32x32x16_bf16 v[64:79], v[116:119], v[152:155], v[64:79]
	v_add_f32_e32 v112, v106, v128
	v_add_f32_e32 v112, v107, v112
	v_add_f32_e32 v112, v108, v112
	v_add_f32_e32 v112, v109, v112
	v_cvt_pk_bf16_f32 v136, v104, v105
	v_cvt_pk_bf16_f32 v137, v106, v107
	ds_read_b64_tr_b16 v[104:105], v203 offset:29696
	ds_read_b64_tr_b16 v[106:107], v203 offset:30208
	v_mfma_f32_32x32x16_bf16 v[48:63], v[120:123], v[152:155], v[48:63]
	v_add_f32_e32 v112, v110, v112
	v_add_f32_e32 v112, v111, v112
	v_add_f32_e32 v112, v80, v112
	v_add_f32_e32 v112, v81, v112
	v_cvt_pk_bf16_f32 v138, v108, v109
	v_cvt_pk_bf16_f32 v139, v110, v111
	ds_read_b64_tr_b16 v[108:109], v203 offset:26624
	ds_read_b64_tr_b16 v[110:111], v203 offset:27136
	v_mfma_f32_32x32x16_bf16 v[64:79], v[124:127], v[148:151], v[64:79]
	v_add_f32_e32 v112, v82, v112
	v_add_f32_e32 v112, v83, v112
	v_add_f32_e32 v112, v84, v112
	v_add_f32_e32 v112, v85, v112
	v_cvt_pk_bf16_f32 v132, v80, v81
	v_cvt_pk_bf16_f32 v133, v82, v83
	ds_read_b64_tr_b16 v[194:195], v203 offset:30720
	ds_read_b64_tr_b16 v[196:197], v203 offset:31232
	v_mfma_f32_32x32x16_bf16 v[48:63], v[160:163], v[148:151], v[48:63]
	v_add_f32_e32 v80, v86, v112
	v_add_f32_e32 v80, v87, v80
	v_add_f32_e32 v80, v88, v80
	v_add_f32_e32 v80, v89, v80
	v_cvt_pk_bf16_f32 v134, v84, v85
	v_cvt_pk_bf16_f32 v135, v86, v87
	ds_read_b64_tr_b16 v[198:199], v203 offset:27648
	ds_read_b64_tr_b16 v[200:201], v203 offset:28160
	v_mfma_f32_32x32x16_bf16 v[64:79], v[164:167], v[144:147], v[64:79]
	v_add_f32_e32 v80, v90, v80
	v_add_f32_e32 v80, v91, v80
	v_add_f32_e32 v80, v92, v80
	v_add_f32_e32 v80, v93, v80
	v_cvt_pk_bf16_f32 v128, v88, v89
	v_cvt_pk_bf16_f32 v129, v90, v91
	ds_read_b64_tr_b16 v[88:89], v203 offset:31744
	ds_read_b64_tr_b16 v[90:91], v203 offset:32256
	v_mfma_f32_32x32x16_bf16 v[48:63], v[186:189], v[144:147], v[48:63]
	v_add_f32_e32 v80, v94, v80
	v_add_f32_e32 v80, v95, v80
	v_cvt_pk_bf16_f32 v130, v92, v93
	v_cvt_pk_bf16_f32 v131, v94, v95
	s_add_i32 m0, s35, s33
	s_nop 0
	global_load_lds_dwordx4 v[176:177], off
	s_add_i32 m0, s53, s16
	s_nop 0
	global_load_lds_dwordx4 v[174:175], off
	v_add_f32_e32 v186, v202, v80
	s_waitcnt lgkmcnt(12)
	v_mfma_f32_32x32x16_bf16 v[16:31], v[140:143], v[190:193], v[16:31]
	v_exp_f32_e32 v64, v64
	v_exp_f32_e32 v65, v65
	v_exp_f32_e32 v66, v66
	v_exp_f32_e32 v67, v67
	v_mfma_f32_32x32x16_bf16 v[32:47], v[140:143], v[96:99], v[32:47]
	v_exp_f32_e32 v68, v68
	v_exp_f32_e32 v69, v69
	v_exp_f32_e32 v70, v70
	v_exp_f32_e32 v71, v71
	v_add_u32_e32 v242, s53, v234
	v_add_u32_e32 v243, s53, v235
	v_add_u32_e32 v244, s53, v236
	v_add_u32_e32 v245, s53, v237
	ds_read_b128 v[84:87], v242
	ds_read_b128 v[80:83], v242 offset:4096
	s_waitcnt lgkmcnt(10)
	v_mfma_f32_32x32x16_bf16 v[16:31], v[136:139], v[100:103], v[16:31]
	v_exp_f32_e32 v72, v72
	v_exp_f32_e32 v73, v73
	v_exp_f32_e32 v74, v74
	v_exp_f32_e32 v75, v75
	ds_read_b128 v[164:167], v243
	ds_read_b128 v[160:163], v243 offset:4096
	v_mfma_f32_32x32x16_bf16 v[32:47], v[136:139], v[104:107], v[32:47]
	v_exp_f32_e32 v76, v76
	v_exp_f32_e32 v77, v77
	v_exp_f32_e32 v78, v78
	v_exp_f32_e32 v79, v79
	ds_read_b128 v[124:127], v244
	ds_read_b128 v[120:123], v244 offset:4096
	s_waitcnt lgkmcnt(10)
	v_mfma_f32_32x32x16_bf16 v[16:31], v[132:135], v[108:111], v[16:31]
	v_exp_f32_e32 v48, v48
	v_exp_f32_e32 v49, v49
	v_exp_f32_e32 v50, v50
	v_exp_f32_e32 v51, v51
	ds_read_b128 v[116:119], v245
	ds_read_b128 v[112:115], v245 offset:4096
	v_mfma_f32_32x32x16_bf16 v[32:47], v[132:135], v[194:197], v[32:47]
	v_exp_f32_e32 v52, v52
	v_exp_f32_e32 v53, v53
	v_exp_f32_e32 v54, v54
	v_exp_f32_e32 v55, v55
	s_waitcnt lgkmcnt(8)
	v_mfma_f32_32x32x16_bf16 v[16:31], v[128:131], v[198:201], v[16:31]
	v_exp_f32_e32 v56, v56
	v_exp_f32_e32 v57, v57
	v_exp_f32_e32 v58, v58
	v_exp_f32_e32 v59, v59
	v_mfma_f32_32x32x16_bf16 v[32:47], v[128:131], v[88:91], v[32:47]
	v_exp_f32_e32 v60, v60
	v_exp_f32_e32 v61, v61
	v_exp_f32_e32 v62, v62
	v_exp_f32_e32 v63, v63
	s_add_i32 s55, s53, 0x2000
	s_cmpk_lg_i32 s53, 0x4000
	s_mov_b32 s54, s35
	s_cselect_b32 s35, s55, 0
	s_add_i32 s34, s34, 2
	v_lshl_add_u64 v[174:175], v[174:175], 0, s[8:9]
	v_lshl_add_u64 v[176:177], v[176:177], 0, s[8:9]
	s_mov_b32 s52, s53
	s_cmpk_lt_u32 s34, 0x79
	s_waitcnt vmcnt(2) lgkmcnt(0)
	s_barrier
	s_cbranch_scc1 .LBB0_882
; #define WAIT_BAR(N) asm volatile("s_waitcnt vmcnt(" #N ") lgkmcnt(0)\n\ts_barrier":::"memory")
;   #define RESC() do{ if(!NOMAX&&resc){ asm volatile("s_waitcnt lgkmcnt(0)":::"memory"); \
;       _Pragma("unroll") for(int d_=0;d_<2*VM;++d_) _Pragma("unroll") for(int r=0;r<16;++r)o[d_][r]*=wsf[crow(r,hi)]; } }while(0)
;   #define ROT() do{sl_prev=sl_cur;sl_cur=sl_next;sl_next=(sl_next==(NSLOT-1)*SLOTB)?0:sl_next+SLOTB;}while(0)
;   #define ENDW(tt) do{ if((tt)+3<NT){ if constexpr(VM==2){WAIT_BAR(3);}else{WAIT_BAR(2);} } else if((tt)+2<NT){ if constexpr(VM==2){WAIT_BAR(2);}else{WAIT_BAR(1);} } else {WAIT_BAR(0);} }while(0)
; template<int THRL,int VM,bool NOMAX> __device__ __forceinline__ void attn_unit(const bf16*Qb,const bf16*__restrict__ Kh,const bf16*__restrict__ Vh,bf16*Ob,const int NT,const int sp,float*wscr,char*shm){
;     ...
;   int t=1;
;   for(;t+5<NT;t+=2){
;     STEP(pB0,pB1,pA0,pA1,t,true,true,true);     if constexpr(VM==2){WAIT_BAR(3);}else{WAIT_BAR(2);} RESC(); ROT();
;     STEP(pA0,pA1,pB0,pB1,t+1,true,true,true);   if constexpr(VM==2){WAIT_BAR(3);}else{WAIT_BAR(2);} RESC(); ROT();
;   }
;     ...
;   for(;t+1<NT;t+=2){
;     STEP(pB0,pB1,pA0,pA1,t,(t+3<NT),(t+1<NT),(t+1<NT));       ENDW(t);   RESC(); ROT();
;     STEP(pA0,pA1,pB0,pB1,t+1,(t+4<NT),(t+2<NT),(t+2<NT));     ENDW(t+1); RESC(); ROT();
	s_and_b32 s29, s29, 0x3fffffc0
	s_lshl_b32 s29, s29, 2
	s_add_i32 s29, s29, 0
	s_cmp_lg_u32 0, -1
	s_cselect_b32 s34, 0, 0
	s_add_i32 s35, s34, 0x6000
	v_add3_u32 v174, v185, s35, v184
	ds_read_b64_tr_b16 v[188:189], v182 offset:40960
	ds_read_b64_tr_b16 v[190:191], v182 offset:41472
	v_add_f32_e32 v88, v64, v65
	v_add_f32_e32 v88, v66, v88
	v_add_f32_e32 v88, v67, v88
	v_add_f32_e32 v88, v68, v88
	v_add_f32_e32 v88, v69, v88
	v_cvt_pk_bf16_f32 v140, v64, v65
	v_cvt_pk_bf16_f32 v141, v66, v67
	s_waitcnt lgkmcnt(9)
	v_mfma_f32_32x32x16_bf16 v[96:111], v[84:87], v[156:159], 0
	ds_read_b64_tr_b16 v[64:65], v182 offset:45056
	ds_read_b64_tr_b16 v[66:67], v182 offset:45568
	v_add_f32_e32 v84, v70, v88
	v_add_f32_e32 v84, v71, v84
	v_add_f32_e32 v84, v72, v84
	v_add_f32_e32 v128, v73, v84
	v_cvt_pk_bf16_f32 v142, v68, v69
	v_cvt_pk_bf16_f32 v143, v70, v71
	s_waitcnt lgkmcnt(10)
	v_mfma_f32_32x32x16_bf16 v[80:95], v[80:83], v[156:159], 0
	ds_read_b64_tr_b16 v[68:69], v182 offset:41984
	ds_read_b64_tr_b16 v[70:71], v182 offset:42496
	v_add_f32_e32 v128, v74, v128
	v_add_f32_e32 v128, v75, v128
	v_add_f32_e32 v128, v76, v128
	v_add_f32_e32 v128, v77, v128
	v_cvt_pk_bf16_f32 v136, v72, v73
	v_cvt_pk_bf16_f32 v137, v74, v75
	s_waitcnt lgkmcnt(11)
	v_mfma_f32_32x32x16_bf16 v[96:111], v[164:167], v[152:155], v[96:111]
	ds_read_b64_tr_b16 v[72:73], v182 offset:46080
	ds_read_b64_tr_b16 v[74:75], v182 offset:46592
	v_add_f32_e32 v128, v78, v128
	v_add_f32_e32 v128, v79, v128
	v_add_f32_e32 v128, v48, v128
	v_add_f32_e32 v128, v49, v128
	v_cvt_pk_bf16_f32 v138, v76, v77
	v_cvt_pk_bf16_f32 v139, v78, v79
	s_waitcnt lgkmcnt(12)
	v_mfma_f32_32x32x16_bf16 v[80:95], v[160:163], v[152:155], v[80:95]
	ds_read_b64_tr_b16 v[76:77], v182 offset:43008
	ds_read_b64_tr_b16 v[78:79], v182 offset:43520
	v_add_f32_e32 v128, v50, v128
	v_add_f32_e32 v128, v51, v128
	v_add_f32_e32 v128, v52, v128
	v_add_f32_e32 v128, v53, v128
	v_cvt_pk_bf16_f32 v132, v48, v49
	v_cvt_pk_bf16_f32 v133, v50, v51
	s_waitcnt lgkmcnt(13)
	v_mfma_f32_32x32x16_bf16 v[96:111], v[124:127], v[148:151], v[96:111]
	ds_read_b64_tr_b16 v[48:49], v182 offset:47104
	ds_read_b64_tr_b16 v[50:51], v182 offset:47616
	v_add_f32_e32 v124, v54, v128
	v_add_f32_e32 v124, v55, v124
	v_add_f32_e32 v124, v56, v124
	v_add_f32_e32 v124, v57, v124
	v_cvt_pk_bf16_f32 v134, v52, v53
	v_cvt_pk_bf16_f32 v135, v54, v55
	s_waitcnt lgkmcnt(14)
	v_mfma_f32_32x32x16_bf16 v[80:95], v[120:123], v[148:151], v[80:95]
	ds_read_b64_tr_b16 v[52:53], v182 offset:44032
	ds_read_b64_tr_b16 v[54:55], v182 offset:44544
	v_add_f32_e32 v120, v58, v124
	v_add_f32_e32 v120, v59, v120
	v_add_f32_e32 v120, v60, v120
	v_add_f32_e32 v120, v61, v120
	v_cvt_pk_bf16_f32 v128, v56, v57
	v_cvt_pk_bf16_f32 v129, v58, v59
	s_waitcnt lgkmcnt(14)
	v_mfma_f32_32x32x16_bf16 v[96:111], v[116:119], v[144:147], v[96:111]
	ds_read_b64_tr_b16 v[56:57], v182 offset:48128
	ds_read_b64_tr_b16 v[58:59], v182 offset:48640
	v_add_f32_e32 v116, v62, v120
	v_add_f32_e32 v116, v63, v116
	v_add_f32_e32 v116, 0, v116
	v_cvt_pk_bf16_f32 v130, v60, v61
	v_cvt_pk_bf16_f32 v131, v62, v63
	v_mfma_f32_32x32x16_bf16 v[80:95], v[112:115], v[144:147], v[80:95]
	v_lshl_add_u64 v[60:61], v[172:173], 0, s[40:41]
	s_mov_b32 s35, m0
	s_mov_b32 m0, s33
	s_nop 0
	global_load_lds_dwordx4 v[60:61], off
	s_mov_b32 m0, s35
	s_add_i32 s33, s34, s17
	v_lshl_add_u64 v[60:61], v[170:171], 0, s[42:43]
	s_add_i32 s17, s33, 0x8000
	s_mov_b32 s34, m0
	s_mov_b32 m0, s17
	s_nop 0
	global_load_lds_dwordx4 v[60:61], off
	s_mov_b32 m0, s34
	v_add_f32_e32 v175, v186, v116
	s_waitcnt lgkmcnt(14)
	v_mfma_f32_32x32x16_bf16 v[16:31], v[140:143], v[188:191], v[16:31]
	v_exp_f32_e32 v96, v96
	v_exp_f32_e32 v97, v97
	v_exp_f32_e32 v98, v98
	v_exp_f32_e32 v99, v99
	s_waitcnt lgkmcnt(12)
	v_mfma_f32_32x32x16_bf16 v[32:47], v[140:143], v[64:67], v[32:47]
	v_exp_f32_e32 v100, v100
	v_exp_f32_e32 v101, v101
	v_exp_f32_e32 v102, v102
	v_exp_f32_e32 v103, v103
	ds_read_b128 v[60:63], v234 offset:8192
	ds_read_b128 v[64:67], v234 offset:12288
	s_waitcnt lgkmcnt(12)
	v_mfma_f32_32x32x16_bf16 v[16:31], v[136:139], v[68:71], v[16:31]
	v_exp_f32_e32 v104, v104
	v_exp_f32_e32 v105, v105
	v_exp_f32_e32 v106, v106
	v_exp_f32_e32 v107, v107
	ds_read_b128 v[68:71], v235 offset:8192
	ds_read_b128 v[160:163], v235 offset:12288
	s_waitcnt lgkmcnt(12)
	v_mfma_f32_32x32x16_bf16 v[32:47], v[136:139], v[72:75], v[32:47]
	v_exp_f32_e32 v108, v108
	v_exp_f32_e32 v109, v109
	v_exp_f32_e32 v110, v110
	v_exp_f32_e32 v111, v111
	ds_read_b128 v[72:75], v236 offset:8192
	ds_read_b128 v[164:167], v236 offset:12288
	s_waitcnt lgkmcnt(12)
	v_mfma_f32_32x32x16_bf16 v[16:31], v[132:135], v[76:79], v[16:31]
	v_exp_f32_e32 v80, v80
	v_exp_f32_e32 v81, v81
	v_exp_f32_e32 v82, v82
	v_exp_f32_e32 v83, v83
	ds_read_b128 v[76:79], v237 offset:8192
	ds_read_b128 v[184:187], v237 offset:12288
	s_waitcnt lgkmcnt(12)
	v_mfma_f32_32x32x16_bf16 v[32:47], v[132:135], v[48:51], v[32:47]
	v_exp_f32_e32 v84, v84
	v_exp_f32_e32 v85, v85
	v_exp_f32_e32 v86, v86
	v_exp_f32_e32 v87, v87
	s_waitcnt lgkmcnt(10)
	v_mfma_f32_32x32x16_bf16 v[16:31], v[128:131], v[52:55], v[16:31]
	v_exp_f32_e32 v88, v88
	v_exp_f32_e32 v89, v89
	v_exp_f32_e32 v90, v90
	v_exp_f32_e32 v91, v91
	s_waitcnt lgkmcnt(8)
	v_mfma_f32_32x32x16_bf16 v[32:47], v[128:131], v[56:59], v[32:47]
	v_exp_f32_e32 v92, v92
	v_exp_f32_e32 v93, v93
	v_exp_f32_e32 v94, v94
	v_exp_f32_e32 v95, v95
	s_waitcnt vmcnt(2) lgkmcnt(0)
	s_barrier
; #define WAIT_BAR(N) asm volatile("s_waitcnt vmcnt(" #N ") lgkmcnt(0)\n\ts_barrier":::"memory")
;   #define RESC() do{ if(!NOMAX&&resc){ asm volatile("s_waitcnt lgkmcnt(0)":::"memory"); \
;       _Pragma("unroll") for(int d_=0;d_<2*VM;++d_) _Pragma("unroll") for(int r=0;r<16;++r)o[d_][r]*=wsf[crow(r,hi)]; } }while(0)
;   #define ROT() do{sl_prev=sl_cur;sl_cur=sl_next;sl_next=(sl_next==(NSLOT-1)*SLOTB)?0:sl_next+SLOTB;}while(0)
;   #define ENDW(tt) do{ if((tt)+3<NT){ if constexpr(VM==2){WAIT_BAR(3);}else{WAIT_BAR(2);} } else if((tt)+2<NT){ if constexpr(VM==2){WAIT_BAR(2);}else{WAIT_BAR(1);} } else {WAIT_BAR(0);} }while(0)
; template<int THRL,int VM,bool NOMAX> __device__ __forceinline__ void attn_unit(const bf16*Qb,const bf16*__restrict__ Kh,const bf16*__restrict__ Vh,bf16*Ob,const int NT,const int sp,float*wscr,char*shm){
;     ...
;   int t=1;
;   for(;t+5<NT;t+=2){
;     STEP(pB0,pB1,pA0,pA1,t,true,true,true);     if constexpr(VM==2){WAIT_BAR(3);}else{WAIT_BAR(2);} RESC(); ROT();
;     STEP(pA0,pA1,pB0,pB1,t+1,true,true,true);   if constexpr(VM==2){WAIT_BAR(3);}else{WAIT_BAR(2);} RESC(); ROT();
;   }
;     ...
;   for(;t+1<NT;t+=2){
;     STEP(pB0,pB1,pA0,pA1,t,(t+3<NT),(t+1<NT),(t+1<NT));       ENDW(t);   RESC(); ROT();
;     STEP(pA0,pA1,pB0,pB1,t+1,(t+4<NT),(t+2<NT),(t+2<NT));     ENDW(t+1); RESC(); ROT();
	ds_read_b64_tr_b16 v[188:189], v182 offset:24576
	ds_read_b64_tr_b16 v[190:191], v182 offset:25088
	v_add_f32_e32 v48, v96, v97
	v_add_f32_e32 v48, v98, v48
	v_add_f32_e32 v48, v99, v48
	v_add_f32_e32 v48, v100, v48
	v_add_f32_e32 v48, v101, v48
	v_cvt_pk_bf16_f32 v140, v96, v97
	v_cvt_pk_bf16_f32 v141, v98, v99
	s_waitcnt lgkmcnt(9)
	v_mfma_f32_32x32x16_bf16 v[112:127], v[60:63], v[156:159], 0
	ds_read_b64_tr_b16 v[96:97], v182 offset:28672
	ds_read_b64_tr_b16 v[98:99], v182 offset:29184
	v_add_f32_e32 v48, v102, v48
	v_add_f32_e32 v48, v103, v48
	v_add_f32_e32 v48, v104, v48
	v_add_f32_e32 v128, v105, v48
	s_waitcnt lgkmcnt(10)
	v_mfma_f32_32x32x16_bf16 v[48:63], v[64:67], v[156:159], 0
	v_cvt_pk_bf16_f32 v142, v100, v101
	v_cvt_pk_bf16_f32 v143, v102, v103
	ds_read_b64_tr_b16 v[64:65], v182 offset:25600
	ds_read_b64_tr_b16 v[66:67], v182 offset:26112
	v_add_f32_e32 v100, v106, v128
	v_add_f32_e32 v100, v107, v100
	v_add_f32_e32 v100, v108, v100
	v_add_f32_e32 v100, v109, v100
	v_cvt_pk_bf16_f32 v136, v104, v105
	v_cvt_pk_bf16_f32 v137, v106, v107
	s_waitcnt lgkmcnt(11)
	v_mfma_f32_32x32x16_bf16 v[112:127], v[68:71], v[152:155], v[112:127]
	ds_read_b64_tr_b16 v[68:69], v182 offset:29696
	ds_read_b64_tr_b16 v[70:71], v182 offset:30208
	s_waitcnt lgkmcnt(12)
	v_mfma_f32_32x32x16_bf16 v[48:63], v[160:163], v[152:155], v[48:63]
	v_add_f32_e32 v100, v110, v100
	v_add_f32_e32 v100, v111, v100
	v_add_f32_e32 v100, v80, v100
	v_add_f32_e32 v104, v81, v100
	v_cvt_pk_bf16_f32 v138, v108, v109
	v_cvt_pk_bf16_f32 v139, v110, v111
	ds_read_b64_tr_b16 v[100:101], v182 offset:26624
	ds_read_b64_tr_b16 v[102:103], v182 offset:27136
	v_add_f32_e32 v104, v82, v104
	v_add_f32_e32 v104, v83, v104
	v_add_f32_e32 v104, v84, v104
	v_add_f32_e32 v104, v85, v104
	v_cvt_pk_bf16_f32 v132, v80, v81
	v_cvt_pk_bf16_f32 v133, v82, v83
	s_waitcnt lgkmcnt(13)
	v_mfma_f32_32x32x16_bf16 v[112:127], v[72:75], v[148:151], v[112:127]
	ds_read_b64_tr_b16 v[72:73], v182 offset:30720
	ds_read_b64_tr_b16 v[74:75], v182 offset:31232
	s_waitcnt lgkmcnt(14)
	v_mfma_f32_32x32x16_bf16 v[48:63], v[164:167], v[148:151], v[48:63]
	v_add_f32_e32 v80, v86, v104
	v_add_f32_e32 v80, v87, v80
	v_add_f32_e32 v80, v88, v80
	v_add_f32_e32 v104, v89, v80
	v_cvt_pk_bf16_f32 v134, v84, v85
	v_cvt_pk_bf16_f32 v135, v86, v87
	ds_read_b64_tr_b16 v[80:81], v182 offset:27648
	ds_read_b64_tr_b16 v[82:83], v182 offset:28160
	v_add_f32_e32 v84, v90, v104
	v_add_f32_e32 v84, v91, v84
	v_add_f32_e32 v84, v92, v84
	v_add_f32_e32 v84, v93, v84
	v_cvt_pk_bf16_f32 v128, v88, v89
	v_cvt_pk_bf16_f32 v129, v90, v91
	s_waitcnt lgkmcnt(14)
	v_mfma_f32_32x32x16_bf16 v[112:127], v[76:79], v[144:147], v[112:127]
	ds_read_b64_tr_b16 v[76:77], v182 offset:31744
	ds_read_b64_tr_b16 v[78:79], v182 offset:32256
	v_mfma_f32_32x32x16_bf16 v[48:63], v[184:187], v[144:147], v[48:63]
	v_add_f32_e32 v84, v94, v84
	v_add_f32_e32 v84, v95, v84
	v_add_f32_e32 v84, 0, v84
	v_cvt_pk_bf16_f32 v130, v92, v93
	v_cvt_pk_bf16_f32 v131, v94, v95
	s_nop 0
	v_add_f32_e32 v175, v175, v84
	v_lshl_add_u64 v[84:85], v[172:173], 0, s[44:45]
	s_add_i32 s34, s33, 0x2000
	s_mov_b32 s35, m0
	s_mov_b32 m0, s34
	s_nop 0
	global_load_lds_dwordx4 v[84:85], off
	s_mov_b32 m0, s35
	v_lshl_add_u64 v[84:85], v[170:171], 0, s[48:49]
	s_add_i32 s33, s33, 0xa000
	s_mov_b32 s34, m0
	s_mov_b32 m0, s33
	s_nop 0
	global_load_lds_dwordx4 v[84:85], off
	s_mov_b32 m0, s34
	s_waitcnt lgkmcnt(14)
	v_mfma_f32_32x32x16_bf16 v[16:31], v[140:143], v[188:191], v[16:31]
	v_exp_f32_e32 v112, v112
	v_exp_f32_e32 v113, v113
	v_exp_f32_e32 v114, v114
	v_exp_f32_e32 v115, v115
	s_waitcnt lgkmcnt(12)
	v_mfma_f32_32x32x16_bf16 v[32:47], v[140:143], v[96:99], v[32:47]
	v_exp_f32_e32 v116, v116
	v_exp_f32_e32 v117, v117
	v_exp_f32_e32 v118, v118
	v_exp_f32_e32 v119, v119
	ds_read_b128 v[84:87], v234 offset:16384
	ds_read_b128 v[96:99], v234 offset:20480
	s_waitcnt lgkmcnt(12)
	v_mfma_f32_32x32x16_bf16 v[16:31], v[136:139], v[64:67], v[16:31]
	v_exp_f32_e32 v120, v120
	v_exp_f32_e32 v121, v121
	v_exp_f32_e32 v122, v122
	v_exp_f32_e32 v123, v123
	ds_read_b128 v[104:107], v235 offset:16384
	ds_read_b128 v[108:111], v235 offset:20480
	s_waitcnt lgkmcnt(12)
	v_mfma_f32_32x32x16_bf16 v[32:47], v[136:139], v[68:71], v[32:47]
	v_exp_f32_e32 v124, v124
	v_exp_f32_e32 v125, v125
	v_exp_f32_e32 v126, v126
	v_exp_f32_e32 v127, v127
	ds_read_b128 v[160:163], v236 offset:16384
	ds_read_b128 v[164:167], v236 offset:20480
	s_waitcnt lgkmcnt(12)
	v_mfma_f32_32x32x16_bf16 v[16:31], v[132:135], v[100:103], v[16:31]
	v_exp_f32_e32 v48, v48
	v_exp_f32_e32 v49, v49
	v_exp_f32_e32 v50, v50
	v_exp_f32_e32 v51, v51
	ds_read_b128 v[100:103], v237 offset:16384
	ds_read_b128 v[184:187], v237 offset:20480
	s_waitcnt lgkmcnt(12)
	v_mfma_f32_32x32x16_bf16 v[32:47], v[132:135], v[72:75], v[32:47]
	v_exp_f32_e32 v52, v52
	v_exp_f32_e32 v53, v53
	v_exp_f32_e32 v54, v54
	v_exp_f32_e32 v55, v55
	s_waitcnt lgkmcnt(10)
	v_mfma_f32_32x32x16_bf16 v[16:31], v[128:131], v[80:83], v[16:31]
	v_exp_f32_e32 v56, v56
	v_exp_f32_e32 v57, v57
	v_exp_f32_e32 v58, v58
	v_exp_f32_e32 v59, v59
	s_waitcnt lgkmcnt(8)
	v_mfma_f32_32x32x16_bf16 v[32:47], v[128:131], v[76:79], v[32:47]
	v_exp_f32_e32 v60, v60
	v_exp_f32_e32 v61, v61
	v_exp_f32_e32 v62, v62
	v_exp_f32_e32 v63, v63
	s_waitcnt vmcnt(2) lgkmcnt(0)
	s_barrier
; #define WAIT_BAR(N) asm volatile("s_waitcnt vmcnt(" #N ") lgkmcnt(0)\n\ts_barrier":::"memory")
;   #define RESC() do{ if(!NOMAX&&resc){ asm volatile("s_waitcnt lgkmcnt(0)":::"memory"); \
;       _Pragma("unroll") for(int d_=0;d_<2*VM;++d_) _Pragma("unroll") for(int r=0;r<16;++r)o[d_][r]*=wsf[crow(r,hi)]; } }while(0)
;   #define ROT() do{sl_prev=sl_cur;sl_cur=sl_next;sl_next=(sl_next==(NSLOT-1)*SLOTB)?0:sl_next+SLOTB;}while(0)
;   #define ENDW(tt) do{ if((tt)+3<NT){ if constexpr(VM==2){WAIT_BAR(3);}else{WAIT_BAR(2);} } else if((tt)+2<NT){ if constexpr(VM==2){WAIT_BAR(2);}else{WAIT_BAR(1);} } else {WAIT_BAR(0);} }while(0)
; template<int THRL,int VM,bool NOMAX> __device__ __forceinline__ void attn_unit(const bf16*Qb,const bf16*__restrict__ Kh,const bf16*__restrict__ Vh,bf16*Ob,const int NT,const int sp,float*wscr,char*shm){
;     ...
;   int t=1;
;   for(;t+5<NT;t+=2){
;     STEP(pB0,pB1,pA0,pA1,t,true,true,true);     if constexpr(VM==2){WAIT_BAR(3);}else{WAIT_BAR(2);} RESC(); ROT();
;     STEP(pA0,pA1,pB0,pB1,t+1,true,true,true);   if constexpr(VM==2){WAIT_BAR(3);}else{WAIT_BAR(2);} RESC(); ROT();
;   }
;     ...
;   for(;t+1<NT;t+=2){
;     STEP(pB0,pB1,pA0,pA1,t,(t+3<NT),(t+1<NT),(t+1<NT));       ENDW(t);   RESC(); ROT();
;     STEP(pA0,pA1,pB0,pB1,t+1,(t+4<NT),(t+2<NT),(t+2<NT));     ENDW(t+1); RESC(); ROT();
	ds_read_b64_tr_b16 v[188:189], v182 offset:32768
	ds_read_b64_tr_b16 v[190:191], v182 offset:33280
	v_add_f32_e32 v64, v112, v113
	v_add_f32_e32 v64, v114, v64
	v_add_f32_e32 v64, v115, v64
	v_add_f32_e32 v64, v116, v64
	v_add_f32_e32 v64, v117, v64
	v_cvt_pk_bf16_f32 v140, v112, v113
	v_cvt_pk_bf16_f32 v141, v114, v115
	s_waitcnt lgkmcnt(9)
	v_mfma_f32_32x32x16_bf16 v[80:95], v[84:87], v[156:159], 0
	ds_read_b64_tr_b16 v[112:113], v182 offset:36864
	ds_read_b64_tr_b16 v[114:115], v182 offset:37376
	v_add_f32_e32 v64, v118, v64
	v_add_f32_e32 v64, v119, v64
	v_add_f32_e32 v64, v120, v64
	v_add_f32_e32 v128, v121, v64
	v_cvt_pk_bf16_f32 v142, v116, v117
	v_cvt_pk_bf16_f32 v143, v118, v119
	s_waitcnt lgkmcnt(10)
	v_mfma_f32_32x32x16_bf16 v[64:79], v[96:99], v[156:159], 0
	ds_read_b64_tr_b16 v[96:97], v182 offset:33792
	ds_read_b64_tr_b16 v[98:99], v182 offset:34304
	v_add_f32_e32 v116, v122, v128
	v_add_f32_e32 v116, v123, v116
	v_add_f32_e32 v116, v124, v116
	v_add_f32_e32 v116, v125, v116
	v_cvt_pk_bf16_f32 v136, v120, v121
	v_cvt_pk_bf16_f32 v137, v122, v123
	s_waitcnt lgkmcnt(11)
	v_mfma_f32_32x32x16_bf16 v[80:95], v[104:107], v[152:155], v[80:95]
	ds_read_b64_tr_b16 v[104:105], v182 offset:37888
	ds_read_b64_tr_b16 v[106:107], v182 offset:38400
	v_add_f32_e32 v116, v126, v116
	v_add_f32_e32 v116, v127, v116
	v_add_f32_e32 v116, v48, v116
	v_add_f32_e32 v116, v49, v116
	v_cvt_pk_bf16_f32 v138, v124, v125
	v_cvt_pk_bf16_f32 v139, v126, v127
	s_waitcnt lgkmcnt(12)
	v_mfma_f32_32x32x16_bf16 v[64:79], v[108:111], v[152:155], v[64:79]
	ds_read_b64_tr_b16 v[108:109], v182 offset:34816
	ds_read_b64_tr_b16 v[110:111], v182 offset:35328
	v_add_f32_e32 v116, v50, v116
	v_add_f32_e32 v116, v51, v116
	v_add_f32_e32 v116, v52, v116
	v_add_f32_e32 v116, v53, v116
	v_cvt_pk_bf16_f32 v132, v48, v49
	v_cvt_pk_bf16_f32 v133, v50, v51
	s_waitcnt lgkmcnt(13)
	v_mfma_f32_32x32x16_bf16 v[80:95], v[160:163], v[148:151], v[80:95]
	ds_read_b64_tr_b16 v[48:49], v182 offset:38912
	ds_read_b64_tr_b16 v[50:51], v182 offset:39424
	v_add_f32_e32 v116, v54, v116
	v_add_f32_e32 v116, v55, v116
	v_add_f32_e32 v116, v56, v116
	v_add_f32_e32 v116, v57, v116
	v_cvt_pk_bf16_f32 v134, v52, v53
	v_cvt_pk_bf16_f32 v135, v54, v55
	s_waitcnt lgkmcnt(14)
	v_mfma_f32_32x32x16_bf16 v[64:79], v[164:167], v[148:151], v[64:79]
	ds_read_b64_tr_b16 v[52:53], v182 offset:35840
	ds_read_b64_tr_b16 v[54:55], v182 offset:36352
	v_add_f32_e32 v116, v58, v116
	v_add_f32_e32 v116, v59, v116
	v_add_f32_e32 v116, v60, v116
	v_add_f32_e32 v116, v61, v116
	v_cvt_pk_bf16_f32 v128, v56, v57
	v_cvt_pk_bf16_f32 v129, v58, v59
	s_waitcnt lgkmcnt(14)
	v_mfma_f32_32x32x16_bf16 v[80:95], v[100:103], v[144:147], v[80:95]
	ds_read_b64_tr_b16 v[56:57], v182 offset:39936
	ds_read_b64_tr_b16 v[58:59], v182 offset:40448
	v_add_f32_e32 v100, v62, v116
	v_add_f32_e32 v100, v63, v100
	v_add_f32_e32 v100, 0, v100
	v_cvt_pk_bf16_f32 v130, v60, v61
	v_cvt_pk_bf16_f32 v131, v62, v63
	v_mfma_f32_32x32x16_bf16 v[64:79], v[184:187], v[144:147], v[64:79]
	v_lshl_add_u64 v[60:61], v[170:171], 0, s[40:41]
	s_mov_b32 s33, m0
	s_mov_b32 m0, s16
	s_nop 0
	global_load_lds_dwordx4 v[60:61], off
	s_mov_b32 m0, s33
	v_add_f32_e32 v172, v175, v100
	s_waitcnt lgkmcnt(14)
	v_mfma_f32_32x32x16_bf16 v[16:31], v[140:143], v[188:191], v[16:31]
	v_exp_f32_e32 v80, v80
	v_exp_f32_e32 v81, v81
	v_exp_f32_e32 v82, v82
	v_exp_f32_e32 v83, v83
	s_waitcnt lgkmcnt(12)
	v_mfma_f32_32x32x16_bf16 v[32:47], v[140:143], v[112:115], v[32:47]
	v_exp_f32_e32 v84, v84
	v_exp_f32_e32 v85, v85
	v_exp_f32_e32 v86, v86
	v_exp_f32_e32 v87, v87
	ds_read_b128 v[60:63], v234
	ds_read_b128 v[112:115], v234 offset:4096
	s_waitcnt lgkmcnt(12)
	v_mfma_f32_32x32x16_bf16 v[16:31], v[136:139], v[96:99], v[16:31]
	v_exp_f32_e32 v88, v88
	v_exp_f32_e32 v89, v89
	v_exp_f32_e32 v90, v90
	v_exp_f32_e32 v91, v91
	ds_read_b128 v[116:119], v235
	ds_read_b128 v[120:123], v235 offset:4096
	s_waitcnt lgkmcnt(12)
	v_mfma_f32_32x32x16_bf16 v[32:47], v[136:139], v[104:107], v[32:47]
	v_exp_f32_e32 v92, v92
	v_exp_f32_e32 v93, v93
	v_exp_f32_e32 v94, v94
	v_exp_f32_e32 v95, v95
	ds_read_b128 v[124:127], v236
	ds_read_b128 v[160:163], v236 offset:4096
	s_waitcnt lgkmcnt(12)
	v_mfma_f32_32x32x16_bf16 v[16:31], v[132:135], v[108:111], v[16:31]
	v_exp_f32_e32 v64, v64
	v_exp_f32_e32 v65, v65
	v_exp_f32_e32 v66, v66
	v_exp_f32_e32 v67, v67
	ds_read_b128 v[164:167], v237
	ds_read_b128 v[184:187], v237 offset:4096
	s_waitcnt lgkmcnt(12)
	v_mfma_f32_32x32x16_bf16 v[32:47], v[132:135], v[48:51], v[32:47]
	v_exp_f32_e32 v68, v68
	v_exp_f32_e32 v69, v69
	v_exp_f32_e32 v70, v70
	v_exp_f32_e32 v71, v71
	s_waitcnt lgkmcnt(10)
	v_mfma_f32_32x32x16_bf16 v[16:31], v[128:131], v[52:55], v[16:31]
	v_exp_f32_e32 v72, v72
	v_exp_f32_e32 v73, v73
	v_exp_f32_e32 v74, v74
	v_exp_f32_e32 v75, v75
	s_waitcnt lgkmcnt(8)
	v_mfma_f32_32x32x16_bf16 v[32:47], v[128:131], v[56:59], v[32:47]
	v_exp_f32_e32 v76, v76
	v_exp_f32_e32 v77, v77
	v_exp_f32_e32 v78, v78
	v_exp_f32_e32 v79, v79
	s_waitcnt vmcnt(1) lgkmcnt(0)
	s_barrier
; #define WAIT_BAR(N) asm volatile("s_waitcnt vmcnt(" #N ") lgkmcnt(0)\n\ts_barrier":::"memory")
;   #define RESC() do{ if(!NOMAX&&resc){ asm volatile("s_waitcnt lgkmcnt(0)":::"memory"); \
;       _Pragma("unroll") for(int d_=0;d_<2*VM;++d_) _Pragma("unroll") for(int r=0;r<16;++r)o[d_][r]*=wsf[crow(r,hi)]; } }while(0)
;   #define ROT() do{sl_prev=sl_cur;sl_cur=sl_next;sl_next=(sl_next==(NSLOT-1)*SLOTB)?0:sl_next+SLOTB;}while(0)
;   #define ENDW(tt) do{ if((tt)+3<NT){ if constexpr(VM==2){WAIT_BAR(3);}else{WAIT_BAR(2);} } else if((tt)+2<NT){ if constexpr(VM==2){WAIT_BAR(2);}else{WAIT_BAR(1);} } else {WAIT_BAR(0);} }while(0)
; template<int THRL,int VM,bool NOMAX> __device__ __forceinline__ void attn_unit(const bf16*Qb,const bf16*__restrict__ Kh,const bf16*__restrict__ Vh,bf16*Ob,const int NT,const int sp,float*wscr,char*shm){
;     ...
;   int t=1;
;   for(;t+5<NT;t+=2){
;     STEP(pB0,pB1,pA0,pA1,t,true,true,true);     if constexpr(VM==2){WAIT_BAR(3);}else{WAIT_BAR(2);} RESC(); ROT();
;     STEP(pA0,pA1,pB0,pB1,t+1,true,true,true);   if constexpr(VM==2){WAIT_BAR(3);}else{WAIT_BAR(2);} RESC(); ROT();
;   }
;     ...
;   for(;t+1<NT;t+=2){
;     STEP(pB0,pB1,pA0,pA1,t,(t+3<NT),(t+1<NT),(t+1<NT));       ENDW(t);   RESC(); ROT();
;     STEP(pA0,pA1,pB0,pB1,t+1,(t+4<NT),(t+2<NT),(t+2<NT));     ENDW(t+1); RESC(); ROT();
	ds_read_b64_tr_b16 v[188:189], v182 offset:40960
	ds_read_b64_tr_b16 v[190:191], v182 offset:41472
	v_add_f32_e32 v48, v80, v81
	v_add_f32_e32 v48, v82, v48
	v_add_f32_e32 v48, v83, v48
	v_add_f32_e32 v48, v84, v48
	v_add_f32_e32 v48, v85, v48
	v_cvt_pk_bf16_f32 v140, v80, v81
	v_cvt_pk_bf16_f32 v141, v82, v83
	s_waitcnt lgkmcnt(9)
	v_mfma_f32_32x32x16_bf16 v[96:111], v[60:63], v[156:159], 0
	ds_read_b64_tr_b16 v[80:81], v182 offset:45056
	ds_read_b64_tr_b16 v[82:83], v182 offset:45568
	v_add_f32_e32 v48, v86, v48
	v_add_f32_e32 v48, v87, v48
	v_add_f32_e32 v48, v88, v48
	v_add_f32_e32 v128, v89, v48
	s_waitcnt lgkmcnt(10)
	v_mfma_f32_32x32x16_bf16 v[48:63], v[112:115], v[156:159], 0
	v_cvt_pk_bf16_f32 v142, v84, v85
	v_cvt_pk_bf16_f32 v143, v86, v87
	ds_read_b64_tr_b16 v[84:85], v182 offset:41984
	ds_read_b64_tr_b16 v[86:87], v182 offset:42496
	v_add_f32_e32 v112, v90, v128
	v_add_f32_e32 v112, v91, v112
	v_add_f32_e32 v112, v92, v112
	v_add_f32_e32 v112, v93, v112
	v_cvt_pk_bf16_f32 v136, v88, v89
	v_cvt_pk_bf16_f32 v137, v90, v91
	s_waitcnt lgkmcnt(11)
	v_mfma_f32_32x32x16_bf16 v[96:111], v[116:119], v[152:155], v[96:111]
	ds_read_b64_tr_b16 v[88:89], v182 offset:46080
	ds_read_b64_tr_b16 v[90:91], v182 offset:46592
	s_waitcnt lgkmcnt(12)
	v_mfma_f32_32x32x16_bf16 v[48:63], v[120:123], v[152:155], v[48:63]
	v_add_f32_e32 v112, v94, v112
	v_add_f32_e32 v112, v95, v112
	v_add_f32_e32 v112, v64, v112
	v_add_f32_e32 v112, v65, v112
	v_cvt_pk_bf16_f32 v138, v92, v93
	v_cvt_pk_bf16_f32 v139, v94, v95
	ds_read_b64_tr_b16 v[92:93], v182 offset:43008
	ds_read_b64_tr_b16 v[94:95], v182 offset:43520
	v_add_f32_e32 v112, v66, v112
	v_add_f32_e32 v112, v67, v112
	v_add_f32_e32 v112, v68, v112
	v_add_f32_e32 v112, v69, v112
	v_cvt_pk_bf16_f32 v132, v64, v65
	v_cvt_pk_bf16_f32 v133, v66, v67
	s_waitcnt lgkmcnt(13)
	v_mfma_f32_32x32x16_bf16 v[96:111], v[124:127], v[148:151], v[96:111]
	ds_read_b64_tr_b16 v[64:65], v182 offset:47104
	ds_read_b64_tr_b16 v[66:67], v182 offset:47616
	s_waitcnt lgkmcnt(14)
	v_mfma_f32_32x32x16_bf16 v[48:63], v[160:163], v[148:151], v[48:63]
	v_add_f32_e32 v112, v70, v112
	v_add_f32_e32 v112, v71, v112
	v_add_f32_e32 v112, v72, v112
	v_add_f32_e32 v112, v73, v112
	v_cvt_pk_bf16_f32 v134, v68, v69
	v_cvt_pk_bf16_f32 v135, v70, v71
	ds_read_b64_tr_b16 v[68:69], v182 offset:44032
	ds_read_b64_tr_b16 v[70:71], v182 offset:44544
	v_add_f32_e32 v112, v74, v112
	v_add_f32_e32 v112, v75, v112
	v_add_f32_e32 v112, v76, v112
	v_add_f32_e32 v112, v77, v112
	v_cvt_pk_bf16_f32 v128, v72, v73
	v_cvt_pk_bf16_f32 v129, v74, v75
	s_waitcnt lgkmcnt(14)
	v_mfma_f32_32x32x16_bf16 v[96:111], v[164:167], v[144:147], v[96:111]
	ds_read_b64_tr_b16 v[72:73], v182 offset:48128
	ds_read_b64_tr_b16 v[74:75], v182 offset:48640
	v_mfma_f32_32x32x16_bf16 v[48:63], v[184:187], v[144:147], v[48:63]
	v_add_f32_e32 v112, v78, v112
	v_add_f32_e32 v112, v79, v112
	v_add_f32_e32 v112, 0, v112
	v_cvt_pk_bf16_f32 v130, v76, v77
	v_cvt_pk_bf16_f32 v131, v78, v79
	v_lshl_add_u64 v[76:77], v[170:171], 0, s[44:45]
	s_mov_b32 s16, m0
	s_mov_b32 m0, s17
	s_nop 0
	global_load_lds_dwordx4 v[76:77], off
	s_mov_b32 m0, s16
	v_add_f32_e32 v120, v172, v112
	s_waitcnt lgkmcnt(14)
	v_mfma_f32_32x32x16_bf16 v[16:31], v[140:143], v[188:191], v[16:31]
	v_exp_f32_e32 v96, v96
	v_exp_f32_e32 v97, v97
	v_exp_f32_e32 v98, v98
	v_exp_f32_e32 v99, v99
	s_waitcnt lgkmcnt(12)
	v_mfma_f32_32x32x16_bf16 v[32:47], v[140:143], v[80:83], v[32:47]
	v_exp_f32_e32 v100, v100
	v_exp_f32_e32 v101, v101
	v_exp_f32_e32 v102, v102
	v_exp_f32_e32 v103, v103
	ds_read_b128 v[76:79], v234 offset:8192
	ds_read_b128 v[80:83], v234 offset:12288
	s_waitcnt lgkmcnt(12)
	v_mfma_f32_32x32x16_bf16 v[16:31], v[136:139], v[84:87], v[16:31]
	v_exp_f32_e32 v104, v104
	v_exp_f32_e32 v105, v105
	v_exp_f32_e32 v106, v106
	v_exp_f32_e32 v107, v107
	ds_read_b128 v[122:125], v235 offset:8192
	ds_read_b128 v[160:163], v235 offset:12288
	s_waitcnt lgkmcnt(12)
	v_mfma_f32_32x32x16_bf16 v[32:47], v[136:139], v[88:91], v[32:47]
	v_exp_f32_e32 v108, v108
	v_exp_f32_e32 v109, v109
	v_exp_f32_e32 v110, v110
	v_exp_f32_e32 v111, v111
	ds_read_b128 v[164:167], v236 offset:8192
	ds_read_b128 v[170:173], v236 offset:12288
	s_waitcnt lgkmcnt(12)
	v_mfma_f32_32x32x16_bf16 v[16:31], v[132:135], v[92:95], v[16:31]
	v_exp_f32_e32 v48, v48
	v_exp_f32_e32 v49, v49
	v_exp_f32_e32 v50, v50
	v_exp_f32_e32 v51, v51
	ds_read_b128 v[184:187], v237 offset:8192
	ds_read_b128 v[188:191], v237 offset:12288
	s_waitcnt lgkmcnt(12)
	v_mfma_f32_32x32x16_bf16 v[32:47], v[132:135], v[64:67], v[32:47]
	v_exp_f32_e32 v52, v52
	v_exp_f32_e32 v53, v53
	v_exp_f32_e32 v54, v54
	v_exp_f32_e32 v55, v55
	s_waitcnt lgkmcnt(10)
	v_mfma_f32_32x32x16_bf16 v[16:31], v[128:131], v[68:71], v[16:31]
	v_exp_f32_e32 v56, v56
	v_exp_f32_e32 v57, v57
	v_exp_f32_e32 v58, v58
	v_exp_f32_e32 v59, v59
	s_waitcnt lgkmcnt(8)
	v_mfma_f32_32x32x16_bf16 v[32:47], v[128:131], v[72:75], v[32:47]
	v_exp_f32_e32 v60, v60
	v_exp_f32_e32 v61, v61
	v_exp_f32_e32 v62, v62
	v_exp_f32_e32 v63, v63
	s_waitcnt vmcnt(0) lgkmcnt(0)
	s_barrier
	ds_read_b64_tr_b16 v[112:113], v182 offset:24576
	ds_read_b64_tr_b16 v[114:115], v182 offset:25088
	v_add_f32_e32 v64, v96, v97
	v_add_f32_e32 v64, v98, v64
	v_add_f32_e32 v64, v99, v64
	v_add_f32_e32 v64, v100, v64
	v_add_f32_e32 v84, v101, v64
	v_cvt_pk_bf16_f32 v140, v96, v97
	v_cvt_pk_bf16_f32 v141, v98, v99
	s_waitcnt lgkmcnt(9)
	v_mfma_f32_32x32x16_bf16 v[64:79], v[76:79], v[156:159], 0
	ds_read_b64_tr_b16 v[96:97], v182 offset:28672
	ds_read_b64_tr_b16 v[98:99], v182 offset:29184
	v_add_f32_e32 v84, v102, v84
	v_add_f32_e32 v84, v103, v84
	v_add_f32_e32 v84, v104, v84
	v_add_f32_e32 v121, v105, v84
	v_cvt_pk_bf16_f32 v142, v100, v101
	v_cvt_pk_bf16_f32 v143, v102, v103
	s_waitcnt lgkmcnt(10)
	v_mfma_f32_32x32x16_bf16 v[80:95], v[80:83], v[156:159], 0
	ds_read_b64_tr_b16 v[116:117], v182 offset:25600
	ds_read_b64_tr_b16 v[118:119], v182 offset:26112
	v_add_f32_e32 v100, v106, v121
	v_add_f32_e32 v100, v107, v100
	v_add_f32_e32 v100, v108, v100
	v_add_f32_e32 v121, v109, v100
	v_cvt_pk_bf16_f32 v136, v104, v105
	v_cvt_pk_bf16_f32 v137, v106, v107
	s_waitcnt lgkmcnt(11)
	v_mfma_f32_32x32x16_bf16 v[64:79], v[122:125], v[152:155], v[64:79]
	ds_read_b64_tr_b16 v[100:101], v182 offset:29696
	ds_read_b64_tr_b16 v[102:103], v182 offset:30208
	v_add_f32_e32 v104, v110, v121
	v_add_f32_e32 v104, v111, v104
	v_add_f32_e32 v104, v48, v104
	v_add_f32_e32 v121, v49, v104
	v_cvt_pk_bf16_f32 v138, v108, v109
	v_cvt_pk_bf16_f32 v139, v110, v111
	s_waitcnt lgkmcnt(12)
	v_mfma_f32_32x32x16_bf16 v[80:95], v[160:163], v[152:155], v[80:95]
	ds_read_b64_tr_b16 v[104:105], v182 offset:26624
	ds_read_b64_tr_b16 v[106:107], v182 offset:27136
	v_add_f32_e32 v108, v50, v121
	v_add_f32_e32 v108, v51, v108
	v_add_f32_e32 v108, v52, v108
	v_add_f32_e32 v108, v53, v108
	v_cvt_pk_bf16_f32 v132, v48, v49
	v_cvt_pk_bf16_f32 v133, v50, v51
	s_waitcnt lgkmcnt(13)
	v_mfma_f32_32x32x16_bf16 v[64:79], v[164:167], v[148:151], v[64:79]
	ds_read_b64_tr_b16 v[48:49], v182 offset:30720
	ds_read_b64_tr_b16 v[50:51], v182 offset:31232
	v_add_f32_e32 v108, v54, v108
	v_add_f32_e32 v108, v55, v108
	v_add_f32_e32 v108, v56, v108
	v_add_f32_e32 v121, v57, v108
	v_cvt_pk_bf16_f32 v134, v52, v53
	v_cvt_pk_bf16_f32 v135, v54, v55
	s_waitcnt lgkmcnt(14)
	v_mfma_f32_32x32x16_bf16 v[80:95], v[170:173], v[148:151], v[80:95]
	ds_read_b64_tr_b16 v[108:109], v182 offset:27648
	ds_read_b64_tr_b16 v[110:111], v182 offset:28160
	v_add_f32_e32 v52, v58, v121
	v_add_f32_e32 v52, v59, v52
	v_add_f32_e32 v52, v60, v52
	v_add_f32_e32 v121, v61, v52
	v_cvt_pk_bf16_f32 v128, v56, v57
	v_cvt_pk_bf16_f32 v129, v58, v59
	s_waitcnt lgkmcnt(14)
	v_mfma_f32_32x32x16_bf16 v[64:79], v[184:187], v[144:147], v[64:79]
	ds_read_b64_tr_b16 v[52:53], v182 offset:31744
	ds_read_b64_tr_b16 v[54:55], v182 offset:32256
	v_add_f32_e32 v56, v62, v121
	v_add_f32_e32 v56, v63, v56
	v_add_f32_e32 v56, 0, v56
	v_cvt_pk_bf16_f32 v130, v60, v61
	v_cvt_pk_bf16_f32 v131, v62, v63
	v_mfma_f32_32x32x16_bf16 v[80:95], v[188:191], v[144:147], v[80:95]
	s_nop 3
	v_exp_f32_e32 v64, v64
	v_exp_f32_e32 v65, v65
	v_exp_f32_e32 v66, v66
	v_exp_f32_e32 v67, v67
	s_nop 0
	v_exp_f32_e32 v68, v68
	v_exp_f32_e32 v69, v69
	v_exp_f32_e32 v70, v70
	v_exp_f32_e32 v71, v71
	s_nop 0
	v_exp_f32_e32 v72, v72
	v_exp_f32_e32 v73, v73
	v_exp_f32_e32 v74, v74
	v_exp_f32_e32 v75, v75
	s_nop 0
	v_exp_f32_e32 v76, v76
	v_exp_f32_e32 v77, v77
	v_exp_f32_e32 v78, v78
	v_exp_f32_e32 v79, v79
	v_exp_f32_e32 v80, v80
	v_exp_f32_e32 v81, v81
	v_exp_f32_e32 v82, v82
	v_exp_f32_e32 v83, v83
	s_nop 0
	v_exp_f32_e32 v84, v84
	v_exp_f32_e32 v85, v85
	v_exp_f32_e32 v86, v86
	v_exp_f32_e32 v87, v87
	s_nop 0
	v_exp_f32_e32 v88, v88
	v_exp_f32_e32 v89, v89
	v_exp_f32_e32 v90, v90
	v_exp_f32_e32 v91, v91
	s_nop 0
	v_exp_f32_e32 v92, v92
	v_exp_f32_e32 v93, v93
	v_exp_f32_e32 v94, v94
	v_exp_f32_e32 v95, v95
	s_waitcnt lgkmcnt(14)
; #define SBAR() __builtin_amdgcn_sched_barrier(0)
;   #define PKW(P,B) cvtpk_s(P[B],P[B+1])
; template<int THRL,int VM,bool NOMAX> __device__ __forceinline__ void attn_unit(const bf16*Qb,const bf16*__restrict__ Kh,const bf16*__restrict__ Vh,bf16*Ob,const int NT,const int sp,float*wscr,char*shm){
;     ...
;   { float sacc=pB0[0]+pB0[1]; _Pragma("unroll") for(int r=2;r<16;++r)sacc+=pB0[r]; _Pragma("unroll") for(int r=0;r<16;++r)sacc+=pB1[r]; l_reg+=sacc;
;     pw0=(u32x4){PKW(pB0,0),PKW(pB0,2),PKW(pB0,4),PKW(pB0,6)};pw1=(u32x4){PKW(pB0,8),PKW(pB0,10),PKW(pB0,12),PKW(pB0,14)};pw2=(u32x4){PKW(pB1,0),PKW(pB1,2),PKW(pB1,4),PKW(pB1,6)};pw3=(u32x4){PKW(pB1,8),PKW(pB1,10),PKW(pB1,12),PKW(pB1,14)};
;     SBAR(); pv(o,vb0+VM*sl_cur,PAF(0),PAF(1),PAF(2),PAF(3)); if constexpr(VM==2) pv(o+2,vb0+VM*sl_cur+8192,PAF(0),PAF(1),PAF(2),PAF(3)); }
;     ...
;   {auto rr=__builtin_amdgcn_permlane32_swap(__float_as_uint(l_reg),__float_as_uint(l_reg),false,false);l_reg=__uint_as_float(rr[0])+__uint_as_float(rr[1]);}
;   if(hi==0)wsf[32+r32]=l_reg;asm volatile("s_waitcnt lgkmcnt(0)":::"memory");
	v_mfma_f32_32x32x16_bf16 v[16:31], v[140:143], v[112:115], v[16:31]
	v_add_f32_e32 v57, v64, v65
	v_add_f32_e32 v57, v66, v57
	v_add_f32_e32 v57, v67, v57
	v_add_f32_e32 v57, v68, v57
	v_add_f32_e32 v57, v69, v57
	v_add_f32_e32 v57, v70, v57
	v_add_f32_e32 v57, v71, v57
	s_waitcnt lgkmcnt(12)
	v_mfma_f32_32x32x16_bf16 v[32:47], v[140:143], v[96:99], v[32:47]
	v_add_f32_e32 v57, v72, v57
	v_add_f32_e32 v57, v73, v57
	v_add_f32_e32 v57, v74, v57
	v_add_f32_e32 v57, v75, v57
	v_add_f32_e32 v57, v76, v57
	v_add_f32_e32 v57, v77, v57
	v_add_f32_e32 v57, v78, v57
	s_waitcnt lgkmcnt(10)
	v_mfma_f32_32x32x16_bf16 v[16:31], v[136:139], v[116:119], v[16:31]
	v_add_f32_e32 v57, v79, v57
	v_add_f32_e32 v57, v80, v57
	v_add_f32_e32 v57, v81, v57
	v_add_f32_e32 v57, v82, v57
	v_add_f32_e32 v57, v83, v57
	v_add_f32_e32 v57, v84, v57
	v_add_f32_e32 v57, v85, v57
	s_waitcnt lgkmcnt(8)
	v_mfma_f32_32x32x16_bf16 v[32:47], v[136:139], v[100:103], v[32:47]
	v_add_f32_e32 v57, v86, v57
	v_add_f32_e32 v57, v87, v57
	v_add_f32_e32 v57, v88, v57
	v_add_f32_e32 v57, v89, v57
	v_add_f32_e32 v57, v90, v57
	v_add_f32_e32 v57, v91, v57
	v_add_f32_e32 v57, v92, v57
	s_waitcnt lgkmcnt(6)
	v_mfma_f32_32x32x16_bf16 v[16:31], v[132:135], v[104:107], v[16:31]
	v_add_f32_e32 v57, v93, v57
	v_add_f32_e32 v57, v94, v57
	v_add_f32_e32 v57, v95, v57
	v_add_f32_e32 v56, v120, v56
	v_add_f32_e32 v56, v56, v57
	v_cvt_pk_bf16_f32 v58, v64, v65
	v_cvt_pk_bf16_f32 v59, v66, v67
	s_waitcnt lgkmcnt(4)
	v_mfma_f32_32x32x16_bf16 v[32:47], v[132:135], v[48:51], v[32:47]
	v_cvt_pk_bf16_f32 v48, v80, v81
	v_cvt_pk_bf16_f32 v60, v68, v69
	v_cvt_pk_bf16_f32 v61, v70, v71
	v_cvt_pk_bf16_f32 v62, v72, v73
	v_cvt_pk_bf16_f32 v63, v74, v75
	v_cvt_pk_bf16_f32 v64, v76, v77
	v_cvt_pk_bf16_f32 v65, v78, v79
	s_waitcnt lgkmcnt(2)
	v_mfma_f32_32x32x16_bf16 v[16:31], v[128:131], v[108:111], v[16:31]
	v_cvt_pk_bf16_f32 v49, v82, v83
	v_cvt_pk_bf16_f32 v50, v84, v85
	v_cvt_pk_bf16_f32 v51, v86, v87
	v_cvt_pk_bf16_f32 v66, v88, v89
	v_cvt_pk_bf16_f32 v67, v90, v91
	v_cvt_pk_bf16_f32 v68, v92, v93
	v_cvt_pk_bf16_f32 v69, v94, v95
	s_waitcnt lgkmcnt(0)
	v_mfma_f32_32x32x16_bf16 v[32:47], v[128:131], v[52:55], v[32:47]
	v_add3_u32 v57, v174, v168, s18
	ds_read_b64_tr_b16 v[52:53],v57 offset:0
	ds_read_b64_tr_b16 v[54:55],v57 offset:512
	ds_read_b64_tr_b16 v[70:71],v57 offset:1024
	ds_read_b64_tr_b16 v[72:73],v57 offset:1536
	ds_read_b64_tr_b16 v[74:75],v57 offset:2048
	ds_read_b64_tr_b16 v[76:77],v57 offset:2560
	ds_read_b64_tr_b16 v[78:79],v57 offset:3072
	ds_read_b64_tr_b16 v[80:81],v57 offset:3584
	s_waitcnt lgkmcnt(0)
	s_nop 0
	v_mfma_f32_32x32x16_bf16 v[16:31], v[58:61], v[52:55], v[16:31]
	ds_read_b64_tr_b16 v[52:53],v57 offset:4096
	ds_read_b64_tr_b16 v[54:55],v57 offset:4608
	v_mfma_f32_32x32x16_bf16 v[16:31], v[62:65], v[70:73], v[16:31]
	ds_read_b64_tr_b16 v[70:71],v57 offset:5120
	ds_read_b64_tr_b16 v[72:73],v57 offset:5632
	v_mfma_f32_32x32x16_bf16 v[16:31], v[48:51], v[74:77], v[16:31]
	ds_read_b64_tr_b16 v[74:75],v57 offset:6144
	ds_read_b64_tr_b16 v[76:77],v57 offset:6656
	ds_read_b64_tr_b16 v[82:83],v57 offset:7168
	ds_read_b64_tr_b16 v[84:85],v57 offset:7680
	s_waitcnt lgkmcnt(0)
	v_mfma_f32_32x32x16_bf16 v[16:31], v[66:69], v[78:81], v[16:31]
	v_mfma_f32_32x32x16_bf16 v[32:47], v[58:61], v[52:55], v[32:47]
	v_cmp_gt_u32_e32 vcc, 32, v178
	v_mfma_f32_32x32x16_bf16 v[32:47], v[62:65], v[70:73], v[32:47]
	v_mfma_f32_32x32x16_bf16 v[32:47], v[48:51], v[74:77], v[32:47]
	v_mov_b32_e32 v48, v56
	s_nop 1
	v_permlane32_swap_b32_e32 v56, v48
	v_mfma_f32_32x32x16_bf16 v[32:47], v[66:69], v[82:85], v[32:47]
	s_and_saveexec_b64 s[16:17], vcc
	s_cbranch_execz .LBB0_878
	v_add_f32_e32 v48, v56, v48
	v_lshl_add_u32 v49, v180, 2, s29
	ds_write_b32 v49, v48 offset:49280
	s_branch .LBB0_878

; #define WAIT_BAR(N) asm volatile("s_waitcnt vmcnt(" #N ") lgkmcnt(0)\n\ts_barrier":::"memory")
;   #define RESC() do{ if(!NOMAX&&resc){ asm volatile("s_waitcnt lgkmcnt(0)":::"memory"); \
;       _Pragma("unroll") for(int d_=0;d_<2*VM;++d_) _Pragma("unroll") for(int r=0;r<16;++r)o[d_][r]*=wsf[crow(r,hi)]; } }while(0)
;   #define ROT() do{sl_prev=sl_cur;sl_cur=sl_next;sl_next=(sl_next==(NSLOT-1)*SLOTB)?0:sl_next+SLOTB;}while(0)
; template<int THRL,int VM,bool NOMAX> __device__ __forceinline__ void attn_unit(const bf16*Qb,const bf16*__restrict__ Kh,const bf16*__restrict__ Vh,bf16*Ob,const int NT,const int sp,float*wscr,char*shm){
;     ...
;   for(;t+5<NT;t+=2){
;     STEP(pB0,pB1,pA0,pA1,t,true,true,true);     if constexpr(VM==2){WAIT_BAR(3);}else{WAIT_BAR(2);} RESC(); ROT();
;     STEP(pA0,pA1,pB0,pB1,t+1,true,true,true);   if constexpr(VM==2){WAIT_BAR(3);}else{WAIT_BAR(2);} RESC(); ROT();
.LBB0_891:
	v_mfma_f32_32x32x16_bf16 v[96:111], v[84:87], v[156:159], 0
	v_add_u32_e32 v187, s52, v168
	ds_read_b64_tr_b16 v[188:189], v187 offset:24576
	ds_read_b64_tr_b16 v[190:191], v187 offset:25088
	v_add_f32_e32 v88, v64, v65
	v_add_f32_e32 v88, v66, v88
	v_add_f32_e32 v88, v67, v88
	v_add_f32_e32 v88, v68, v88
	v_add_f32_e32 v88, v69, v88
	v_cvt_pk_bf16_f32 v140, v64, v65
	v_cvt_pk_bf16_f32 v141, v66, v67
	ds_read_b64_tr_b16 v[64:65], v187 offset:28672
	ds_read_b64_tr_b16 v[66:67], v187 offset:29184
	v_add_f32_e32 v84, v70, v88
	v_add_f32_e32 v84, v71, v84
	v_add_f32_e32 v84, v72, v84
	v_add_f32_e32 v128, v73, v84
	v_mfma_f32_32x32x16_bf16 v[80:95], v[80:83], v[156:159], 0
	v_cvt_pk_bf16_f32 v142, v68, v69
	v_cvt_pk_bf16_f32 v143, v70, v71
	ds_read_b64_tr_b16 v[68:69], v187 offset:25600
	ds_read_b64_tr_b16 v[70:71], v187 offset:26112
	v_add_f32_e32 v128, v74, v128
	v_add_f32_e32 v128, v75, v128
	v_add_f32_e32 v128, v76, v128
	v_add_f32_e32 v128, v77, v128
	v_cvt_pk_bf16_f32 v136, v72, v73
	v_cvt_pk_bf16_f32 v137, v74, v75
	v_mfma_f32_32x32x16_bf16 v[96:111], v[164:167], v[152:155], v[96:111]
	ds_read_b64_tr_b16 v[72:73], v187 offset:29696
	ds_read_b64_tr_b16 v[74:75], v187 offset:30208
	v_mfma_f32_32x32x16_bf16 v[80:95], v[160:163], v[152:155], v[80:95]
	v_add_f32_e32 v128, v78, v128
	v_add_f32_e32 v128, v79, v128
	v_add_f32_e32 v128, v48, v128
	v_add_f32_e32 v128, v49, v128
	v_cvt_pk_bf16_f32 v138, v76, v77
	v_cvt_pk_bf16_f32 v139, v78, v79
	ds_read_b64_tr_b16 v[76:77], v187 offset:26624
	ds_read_b64_tr_b16 v[78:79], v187 offset:27136
	v_add_f32_e32 v128, v50, v128
	v_add_f32_e32 v128, v51, v128
	v_add_f32_e32 v128, v52, v128
	v_add_f32_e32 v128, v53, v128
	v_cvt_pk_bf16_f32 v132, v48, v49
	v_cvt_pk_bf16_f32 v133, v50, v51
	v_mfma_f32_32x32x16_bf16 v[96:111], v[124:127], v[148:151], v[96:111]
	ds_read_b64_tr_b16 v[48:49], v187 offset:30720
	ds_read_b64_tr_b16 v[50:51], v187 offset:31232
	v_mfma_f32_32x32x16_bf16 v[80:95], v[120:123], v[148:151], v[80:95]
	v_add_f32_e32 v124, v54, v128
	v_add_f32_e32 v124, v55, v124
	v_add_f32_e32 v124, v56, v124
	v_add_f32_e32 v124, v57, v124
	v_cvt_pk_bf16_f32 v134, v52, v53
	v_cvt_pk_bf16_f32 v135, v54, v55
	ds_read_b64_tr_b16 v[52:53], v187 offset:27648
	ds_read_b64_tr_b16 v[54:55], v187 offset:28160
	v_add_f32_e32 v120, v58, v124
	v_add_f32_e32 v120, v59, v120
	v_add_f32_e32 v120, v60, v120
	v_add_f32_e32 v120, v61, v120
	v_cvt_pk_bf16_f32 v128, v56, v57
	v_cvt_pk_bf16_f32 v129, v58, v59
	v_mfma_f32_32x32x16_bf16 v[96:111], v[116:119], v[144:147], v[96:111]
	ds_read_b64_tr_b16 v[56:57], v187 offset:31744
	ds_read_b64_tr_b16 v[58:59], v187 offset:32256
	v_mfma_f32_32x32x16_bf16 v[80:95], v[112:115], v[144:147], v[80:95]
	v_add_f32_e32 v116, v62, v120
	v_add_f32_e32 v116, v63, v116
	v_cvt_pk_bf16_f32 v130, v60, v61
	v_cvt_pk_bf16_f32 v131, v62, v63
	s_add_i32 m0, s34, s17
	v_lshl_add_u64 v[60:61], v[176:177], 0, s[38:39]
	global_load_lds_dwordx4 v[60:61], off
	s_add_i32 m0, s33, s16
	v_lshl_add_u64 v[60:61], v[174:175], 0, s[38:39]
	global_load_lds_dwordx4 v[60:61], off
	v_add_f32_e32 v202, v186, v116
	s_waitcnt lgkmcnt(12)
	v_mfma_f32_32x32x16_bf16 v[16:31], v[140:143], v[188:191], v[16:31]
	v_exp_f32_e32 v96, v96
	v_exp_f32_e32 v97, v97
	v_exp_f32_e32 v98, v98
	v_exp_f32_e32 v99, v99
	v_mfma_f32_32x32x16_bf16 v[32:47], v[140:143], v[64:67], v[32:47]
	v_exp_f32_e32 v100, v100
	v_exp_f32_e32 v101, v101
	v_exp_f32_e32 v102, v102
	v_exp_f32_e32 v103, v103
	v_add_u32_e32 v242, s33, v234
	v_add_u32_e32 v243, s33, v235
	v_add_u32_e32 v244, s33, v236
	v_add_u32_e32 v245, s33, v237
	ds_read_b128 v[60:63], v242
	ds_read_b128 v[112:115], v242 offset:4096
	s_waitcnt lgkmcnt(10)
	v_mfma_f32_32x32x16_bf16 v[16:31], v[136:139], v[68:71], v[16:31]
	v_exp_f32_e32 v104, v104
	v_exp_f32_e32 v105, v105
	v_exp_f32_e32 v106, v106
	v_exp_f32_e32 v107, v107
	ds_read_b128 v[116:119], v243
	ds_read_b128 v[120:123], v243 offset:4096
	v_mfma_f32_32x32x16_bf16 v[32:47], v[136:139], v[72:75], v[32:47]
	v_exp_f32_e32 v108, v108
	v_exp_f32_e32 v109, v109
	v_exp_f32_e32 v110, v110
	v_exp_f32_e32 v111, v111
	ds_read_b128 v[124:127], v244
	ds_read_b128 v[160:163], v244 offset:4096
	s_waitcnt lgkmcnt(10)
	v_mfma_f32_32x32x16_bf16 v[16:31], v[132:135], v[76:79], v[16:31]
	v_exp_f32_e32 v80, v80
	v_exp_f32_e32 v81, v81
	v_exp_f32_e32 v82, v82
	v_exp_f32_e32 v83, v83
	ds_read_b128 v[164:167], v245
	ds_read_b128 v[186:189], v245 offset:4096
	v_mfma_f32_32x32x16_bf16 v[32:47], v[132:135], v[48:51], v[32:47]
	v_exp_f32_e32 v84, v84
	v_exp_f32_e32 v85, v85
	v_exp_f32_e32 v86, v86
	v_exp_f32_e32 v87, v87
	s_waitcnt lgkmcnt(8)
	v_mfma_f32_32x32x16_bf16 v[16:31], v[128:131], v[52:55], v[16:31]
	v_exp_f32_e32 v88, v88
	v_exp_f32_e32 v89, v89
	v_exp_f32_e32 v90, v90
	v_exp_f32_e32 v91, v91
	v_mfma_f32_32x32x16_bf16 v[32:47], v[128:131], v[56:59], v[32:47]
	v_exp_f32_e32 v92, v92
	v_exp_f32_e32 v93, v93
	v_exp_f32_e32 v94, v94
	v_exp_f32_e32 v95, v95
	s_waitcnt vmcnt(2) lgkmcnt(0)
	s_barrier
; #define WAIT_BAR(N) asm volatile("s_waitcnt vmcnt(" #N ") lgkmcnt(0)\n\ts_barrier":::"memory")
;   #define RESC() do{ if(!NOMAX&&resc){ asm volatile("s_waitcnt lgkmcnt(0)":::"memory"); \
;       _Pragma("unroll") for(int d_=0;d_<2*VM;++d_) _Pragma("unroll") for(int r=0;r<16;++r)o[d_][r]*=wsf[crow(r,hi)]; } }while(0)
;   #define ROT() do{sl_prev=sl_cur;sl_cur=sl_next;sl_next=(sl_next==(NSLOT-1)*SLOTB)?0:sl_next+SLOTB;}while(0)
; template<int THRL,int VM,bool NOMAX> __device__ __forceinline__ void attn_unit(const bf16*Qb,const bf16*__restrict__ Kh,const bf16*__restrict__ Vh,bf16*Ob,const int NT,const int sp,float*wscr,char*shm){
;     ...
;     STEP(pB0,pB1,pA0,pA1,t,true,true,true);     if constexpr(VM==2){WAIT_BAR(3);}else{WAIT_BAR(2);} RESC(); ROT();
;     STEP(pA0,pA1,pB0,pB1,t+1,true,true,true);   if constexpr(VM==2){WAIT_BAR(3);}else{WAIT_BAR(2);} RESC(); ROT();
	v_mfma_f32_32x32x16_bf16 v[64:79], v[60:63], v[156:159], 0
	s_add_i32 s35, s33, 0x2000
	s_cmpk_lg_i32 s33, 0x4000
	s_cselect_b32 s35, s35, 0
	v_add_u32_e32 v203, s34, v168
	ds_read_b64_tr_b16 v[190:191], v203 offset:24576
	ds_read_b64_tr_b16 v[192:193], v203 offset:25088
	v_add_f32_e32 v48, v96, v97
	v_add_f32_e32 v48, v98, v48
	v_add_f32_e32 v48, v99, v48
	v_add_f32_e32 v48, v100, v48
	v_add_f32_e32 v48, v101, v48
	v_cvt_pk_bf16_f32 v140, v96, v97
	v_cvt_pk_bf16_f32 v141, v98, v99
	ds_read_b64_tr_b16 v[96:97], v203 offset:28672
	ds_read_b64_tr_b16 v[98:99], v203 offset:29184
	v_add_f32_e32 v48, v102, v48
	v_add_f32_e32 v48, v103, v48
	v_add_f32_e32 v48, v104, v48
	v_add_f32_e32 v128, v105, v48
	v_mfma_f32_32x32x16_bf16 v[48:63], v[112:115], v[156:159], 0
	v_cvt_pk_bf16_f32 v142, v100, v101
	v_cvt_pk_bf16_f32 v143, v102, v103
	ds_read_b64_tr_b16 v[100:101], v203 offset:25600
	ds_read_b64_tr_b16 v[102:103], v203 offset:26112
	v_mfma_f32_32x32x16_bf16 v[64:79], v[116:119], v[152:155], v[64:79]
	v_add_f32_e32 v112, v106, v128
	v_add_f32_e32 v112, v107, v112
	v_add_f32_e32 v112, v108, v112
	v_add_f32_e32 v112, v109, v112
	v_cvt_pk_bf16_f32 v136, v104, v105
	v_cvt_pk_bf16_f32 v137, v106, v107
	ds_read_b64_tr_b16 v[104:105], v203 offset:29696
	ds_read_b64_tr_b16 v[106:107], v203 offset:30208
	v_mfma_f32_32x32x16_bf16 v[48:63], v[120:123], v[152:155], v[48:63]
	v_add_f32_e32 v112, v110, v112
	v_add_f32_e32 v112, v111, v112
	v_add_f32_e32 v112, v80, v112
	v_add_f32_e32 v112, v81, v112
	v_cvt_pk_bf16_f32 v138, v108, v109
	v_cvt_pk_bf16_f32 v139, v110, v111
	ds_read_b64_tr_b16 v[108:109], v203 offset:26624
	ds_read_b64_tr_b16 v[110:111], v203 offset:27136
	v_mfma_f32_32x32x16_bf16 v[64:79], v[124:127], v[148:151], v[64:79]
	v_add_f32_e32 v112, v82, v112
	v_add_f32_e32 v112, v83, v112
	v_add_f32_e32 v112, v84, v112
	v_add_f32_e32 v112, v85, v112
	v_cvt_pk_bf16_f32 v132, v80, v81
	v_cvt_pk_bf16_f32 v133, v82, v83
	ds_read_b64_tr_b16 v[194:195], v203 offset:30720
	ds_read_b64_tr_b16 v[196:197], v203 offset:31232
	v_mfma_f32_32x32x16_bf16 v[48:63], v[160:163], v[148:151], v[48:63]
	v_add_f32_e32 v80, v86, v112
	v_add_f32_e32 v80, v87, v80
	v_add_f32_e32 v80, v88, v80
	v_add_f32_e32 v80, v89, v80
	v_cvt_pk_bf16_f32 v134, v84, v85
	v_cvt_pk_bf16_f32 v135, v86, v87
	ds_read_b64_tr_b16 v[198:199], v203 offset:27648
	ds_read_b64_tr_b16 v[200:201], v203 offset:28160
	v_mfma_f32_32x32x16_bf16 v[64:79], v[164:167], v[144:147], v[64:79]
	v_add_f32_e32 v80, v90, v80
	v_add_f32_e32 v80, v91, v80
	v_add_f32_e32 v80, v92, v80
	v_add_f32_e32 v80, v93, v80
	v_cvt_pk_bf16_f32 v128, v88, v89
	v_cvt_pk_bf16_f32 v129, v90, v91
	ds_read_b64_tr_b16 v[88:89], v203 offset:31744
	ds_read_b64_tr_b16 v[90:91], v203 offset:32256
	v_mfma_f32_32x32x16_bf16 v[48:63], v[186:189], v[144:147], v[48:63]
	v_add_f32_e32 v80, v94, v80
	v_add_f32_e32 v80, v95, v80
	v_cvt_pk_bf16_f32 v130, v92, v93
	v_cvt_pk_bf16_f32 v131, v94, v95
	s_add_i32 m0, s33, s17
	s_nop 0
	global_load_lds_dwordx4 v[176:177], off
	s_add_i32 m0, s35, s16
	s_nop 0
	global_load_lds_dwordx4 v[174:175], off
	v_add_f32_e32 v186, v202, v80
	s_waitcnt lgkmcnt(12)
	v_mfma_f32_32x32x16_bf16 v[16:31], v[140:143], v[190:193], v[16:31]
	v_exp_f32_e32 v64, v64
	v_exp_f32_e32 v65, v65
	v_exp_f32_e32 v66, v66
	v_exp_f32_e32 v67, v67
	v_mfma_f32_32x32x16_bf16 v[32:47], v[140:143], v[96:99], v[32:47]
	v_exp_f32_e32 v68, v68
	v_exp_f32_e32 v69, v69
	v_exp_f32_e32 v70, v70
	v_exp_f32_e32 v71, v71
	v_add_u32_e32 v242, s35, v234
	v_add_u32_e32 v243, s35, v235
	v_add_u32_e32 v244, s35, v236
	v_add_u32_e32 v245, s35, v237
	ds_read_b128 v[84:87], v242
	ds_read_b128 v[80:83], v242 offset:4096
	s_waitcnt lgkmcnt(10)
	v_mfma_f32_32x32x16_bf16 v[16:31], v[136:139], v[100:103], v[16:31]
	v_exp_f32_e32 v72, v72
	v_exp_f32_e32 v73, v73
	v_exp_f32_e32 v74, v74
	v_exp_f32_e32 v75, v75
	ds_read_b128 v[164:167], v243
	ds_read_b128 v[160:163], v243 offset:4096
	v_mfma_f32_32x32x16_bf16 v[32:47], v[136:139], v[104:107], v[32:47]
	v_exp_f32_e32 v76, v76
	v_exp_f32_e32 v77, v77
	v_exp_f32_e32 v78, v78
	v_exp_f32_e32 v79, v79
	ds_read_b128 v[124:127], v244
	ds_read_b128 v[120:123], v244 offset:4096
	s_waitcnt lgkmcnt(10)
	v_mfma_f32_32x32x16_bf16 v[16:31], v[132:135], v[108:111], v[16:31]
	v_exp_f32_e32 v48, v48
	v_exp_f32_e32 v49, v49
	v_exp_f32_e32 v50, v50
	v_exp_f32_e32 v51, v51
	ds_read_b128 v[116:119], v245
	ds_read_b128 v[112:115], v245 offset:4096
	v_mfma_f32_32x32x16_bf16 v[32:47], v[132:135], v[194:197], v[32:47]
	v_exp_f32_e32 v52, v52
	v_exp_f32_e32 v53, v53
	v_exp_f32_e32 v54, v54
	v_exp_f32_e32 v55, v55
	s_waitcnt lgkmcnt(8)
	v_mfma_f32_32x32x16_bf16 v[16:31], v[128:131], v[198:201], v[16:31]
	v_exp_f32_e32 v56, v56
	v_exp_f32_e32 v57, v57
	v_exp_f32_e32 v58, v58
	v_exp_f32_e32 v59, v59
	v_mfma_f32_32x32x16_bf16 v[32:47], v[128:131], v[88:91], v[32:47]
	v_exp_f32_e32 v60, v60
	v_exp_f32_e32 v61, v61
	v_exp_f32_e32 v62, v62
	v_exp_f32_e32 v63, v63
	s_add_i32 s53, s35, 0x2000
	s_cmpk_lg_i32 s35, 0x4000
	s_mov_b32 s52, s33
	s_cselect_b32 s33, s53, 0
	s_add_i32 s29, s29, 2
	v_lshl_add_u64 v[174:175], v[174:175], 0, s[8:9]
	v_lshl_add_u64 v[176:177], v[176:177], 0, s[8:9]
	s_mov_b32 s34, s35
	s_cmp_lt_u32 s29, 57
	s_waitcnt vmcnt(2) lgkmcnt(0)
	s_barrier
	s_cbranch_scc1 .LBB0_891
;   #define RESC() do{ if(!NOMAX&&resc){ asm volatile("s_waitcnt lgkmcnt(0)":::"memory"); \
;       _Pragma("unroll") for(int d_=0;d_<2*VM;++d_) _Pragma("unroll") for(int r=0;r<16;++r)o[d_][r]*=wsf[crow(r,hi)]; } }while(0)
;   #define ROT() do{sl_prev=sl_cur;sl_cur=sl_next;sl_next=(sl_next==(NSLOT-1)*SLOTB)?0:sl_next+SLOTB;}while(0)
;   #define ENDW(tt) do{ if((tt)+3<NT){ if constexpr(VM==2){WAIT_BAR(3);}else{WAIT_BAR(2);} } else if((tt)+2<NT){ if constexpr(VM==2){WAIT_BAR(2);}else{WAIT_BAR(1);} } else {WAIT_BAR(0);} }while(0)
; template<int THRL,int VM,bool NOMAX> __device__ __forceinline__ void attn_unit(const bf16*Qb,const bf16*__restrict__ Kh,const bf16*__restrict__ Vh,bf16*Ob,const int NT,const int sp,float*wscr,char*shm){
;     ...
;   for(;t+1<NT;t+=2){
;     STEP(pB0,pB1,pA0,pA1,t,(t+3<NT),(t+1<NT),(t+1<NT));       ENDW(t);   RESC(); ROT();
;     STEP(pA0,pA1,pB0,pB1,t+1,(t+4<NT),(t+2<NT),(t+2<NT));     ENDW(t+1); RESC(); ROT();
	s_and_b32 s19, s19, 0x3fffffc0
	s_lshl_b32 s19, s19, 2
	s_add_i32 s19, s19, 0
	s_cmp_lg_u32 0, -1
	s_cselect_b32 s29, 0, 0
	s_add_i32 s33, s29, 0x6000
	v_add_u32_e32 v88, s33, v184
	v_add3_u32 v174, v88, v183, v185
	ds_read_b64_tr_b16 v[188:189], v168 offset:32768
	ds_read_b64_tr_b16 v[190:191], v168 offset:33280
	v_add_f32_e32 v88, v64, v65
	v_add_f32_e32 v88, v66, v88
	v_add_f32_e32 v88, v67, v88
	v_add_f32_e32 v88, v68, v88
	v_add_f32_e32 v88, v69, v88
	v_cvt_pk_bf16_f32 v140, v64, v65
	v_cvt_pk_bf16_f32 v141, v66, v67
	s_waitcnt lgkmcnt(9)
	v_mfma_f32_32x32x16_bf16 v[96:111], v[84:87], v[156:159], 0
	ds_read_b64_tr_b16 v[64:65], v168 offset:36864
	ds_read_b64_tr_b16 v[66:67], v168 offset:37376
	v_add_f32_e32 v84, v70, v88
	v_add_f32_e32 v84, v71, v84
	v_add_f32_e32 v84, v72, v84
	v_add_f32_e32 v128, v73, v84
	v_cvt_pk_bf16_f32 v142, v68, v69
	v_cvt_pk_bf16_f32 v143, v70, v71
	s_waitcnt lgkmcnt(10)
	v_mfma_f32_32x32x16_bf16 v[80:95], v[80:83], v[156:159], 0
	ds_read_b64_tr_b16 v[68:69], v168 offset:33792
	ds_read_b64_tr_b16 v[70:71], v168 offset:34304
	v_add_f32_e32 v128, v74, v128
	v_add_f32_e32 v128, v75, v128
	v_add_f32_e32 v128, v76, v128
	v_add_f32_e32 v128, v77, v128
	v_cvt_pk_bf16_f32 v136, v72, v73
	v_cvt_pk_bf16_f32 v137, v74, v75
	s_waitcnt lgkmcnt(11)
	v_mfma_f32_32x32x16_bf16 v[96:111], v[164:167], v[152:155], v[96:111]
	ds_read_b64_tr_b16 v[72:73], v168 offset:37888
	ds_read_b64_tr_b16 v[74:75], v168 offset:38400
	v_add_f32_e32 v128, v78, v128
	v_add_f32_e32 v128, v79, v128
	v_add_f32_e32 v128, v48, v128
	v_add_f32_e32 v128, v49, v128
	v_cvt_pk_bf16_f32 v138, v76, v77
	v_cvt_pk_bf16_f32 v139, v78, v79
	s_waitcnt lgkmcnt(12)
	v_mfma_f32_32x32x16_bf16 v[80:95], v[160:163], v[152:155], v[80:95]
	ds_read_b64_tr_b16 v[76:77], v168 offset:34816
	ds_read_b64_tr_b16 v[78:79], v168 offset:35328
	v_add_f32_e32 v128, v50, v128
	v_add_f32_e32 v128, v51, v128
	v_add_f32_e32 v128, v52, v128
	v_add_f32_e32 v128, v53, v128
	v_cvt_pk_bf16_f32 v132, v48, v49
	v_cvt_pk_bf16_f32 v133, v50, v51
	s_waitcnt lgkmcnt(13)
	v_mfma_f32_32x32x16_bf16 v[96:111], v[124:127], v[148:151], v[96:111]
	ds_read_b64_tr_b16 v[48:49], v168 offset:38912
	ds_read_b64_tr_b16 v[50:51], v168 offset:39424
	v_add_f32_e32 v124, v54, v128
	v_add_f32_e32 v124, v55, v124
	v_add_f32_e32 v124, v56, v124
	v_add_f32_e32 v124, v57, v124
	v_cvt_pk_bf16_f32 v134, v52, v53
	v_cvt_pk_bf16_f32 v135, v54, v55
	s_waitcnt lgkmcnt(14)
	v_mfma_f32_32x32x16_bf16 v[80:95], v[120:123], v[148:151], v[80:95]
	ds_read_b64_tr_b16 v[52:53], v168 offset:35840
	ds_read_b64_tr_b16 v[54:55], v168 offset:36352
	v_add_f32_e32 v120, v58, v124
	v_add_f32_e32 v120, v59, v120
	v_add_f32_e32 v120, v60, v120
	v_add_f32_e32 v120, v61, v120
	v_cvt_pk_bf16_f32 v128, v56, v57
	v_cvt_pk_bf16_f32 v129, v58, v59
	s_waitcnt lgkmcnt(14)
	v_mfma_f32_32x32x16_bf16 v[96:111], v[116:119], v[144:147], v[96:111]
	ds_read_b64_tr_b16 v[56:57], v168 offset:39936
	ds_read_b64_tr_b16 v[58:59], v168 offset:40448
	v_add_f32_e32 v116, v62, v120
	v_add_f32_e32 v116, v63, v116
	v_add_f32_e32 v116, 0, v116
	v_cvt_pk_bf16_f32 v130, v60, v61
	v_cvt_pk_bf16_f32 v131, v62, v63
	v_mfma_f32_32x32x16_bf16 v[80:95], v[112:115], v[144:147], v[80:95]
	s_add_i32 s28, s29, s28
	v_lshl_add_u64 v[60:61], v[172:173], 0, s[40:41]
	s_add_i32 s29, s28, 0x4000
	s_mov_b32 s33, m0
	s_mov_b32 m0, s29
	s_nop 0
	global_load_lds_dwordx4 v[60:61], off
	s_mov_b32 m0, s33
	v_lshl_add_u64 v[60:61], v[170:171], 0, s[42:43]
	s_mov_b32 s29, m0
	s_mov_b32 m0, s16
	s_nop 0
	global_load_lds_dwordx4 v[60:61], off
	s_mov_b32 m0, s29
	v_add_f32_e32 v175, v186, v116
	s_waitcnt lgkmcnt(14)
	v_mfma_f32_32x32x16_bf16 v[16:31], v[140:143], v[188:191], v[16:31]
	v_exp_f32_e32 v96, v96
	v_exp_f32_e32 v97, v97
	v_exp_f32_e32 v98, v98
	v_exp_f32_e32 v99, v99
	s_waitcnt lgkmcnt(12)
	v_mfma_f32_32x32x16_bf16 v[32:47], v[140:143], v[64:67], v[32:47]
	v_exp_f32_e32 v100, v100
	v_exp_f32_e32 v101, v101
	v_exp_f32_e32 v102, v102
	v_exp_f32_e32 v103, v103
	ds_read_b128 v[60:63], v234
	ds_read_b128 v[64:67], v234 offset:4096
	s_waitcnt lgkmcnt(12)
	v_mfma_f32_32x32x16_bf16 v[16:31], v[136:139], v[68:71], v[16:31]
	v_exp_f32_e32 v104, v104
	v_exp_f32_e32 v105, v105
	v_exp_f32_e32 v106, v106
	v_exp_f32_e32 v107, v107
	ds_read_b128 v[68:71], v235
	ds_read_b128 v[160:163], v235 offset:4096
	s_waitcnt lgkmcnt(12)
	v_mfma_f32_32x32x16_bf16 v[32:47], v[136:139], v[72:75], v[32:47]
	v_exp_f32_e32 v108, v108
	v_exp_f32_e32 v109, v109
	v_exp_f32_e32 v110, v110
	v_exp_f32_e32 v111, v111
	ds_read_b128 v[72:75], v236
	ds_read_b128 v[164:167], v236 offset:4096
	s_waitcnt lgkmcnt(12)
	v_mfma_f32_32x32x16_bf16 v[16:31], v[132:135], v[76:79], v[16:31]
	v_exp_f32_e32 v80, v80
	v_exp_f32_e32 v81, v81
	v_exp_f32_e32 v82, v82
	v_exp_f32_e32 v83, v83
	ds_read_b128 v[76:79], v237
	ds_read_b128 v[184:187], v237 offset:4096
	s_waitcnt lgkmcnt(12)
	v_mfma_f32_32x32x16_bf16 v[32:47], v[132:135], v[48:51], v[32:47]
	v_exp_f32_e32 v84, v84
	v_exp_f32_e32 v85, v85
	v_exp_f32_e32 v86, v86
	v_exp_f32_e32 v87, v87
	s_waitcnt lgkmcnt(10)
	v_mfma_f32_32x32x16_bf16 v[16:31], v[128:131], v[52:55], v[16:31]
	v_exp_f32_e32 v88, v88
	v_exp_f32_e32 v89, v89
	v_exp_f32_e32 v90, v90
	v_exp_f32_e32 v91, v91
	s_waitcnt lgkmcnt(8)
	v_mfma_f32_32x32x16_bf16 v[32:47], v[128:131], v[56:59], v[32:47]
	v_exp_f32_e32 v92, v92
	v_exp_f32_e32 v93, v93
	v_exp_f32_e32 v94, v94
	v_exp_f32_e32 v95, v95
	s_waitcnt vmcnt(2) lgkmcnt(0)
	s_barrier
;   #define RESC() do{ if(!NOMAX&&resc){ asm volatile("s_waitcnt lgkmcnt(0)":::"memory"); \
;       _Pragma("unroll") for(int d_=0;d_<2*VM;++d_) _Pragma("unroll") for(int r=0;r<16;++r)o[d_][r]*=wsf[crow(r,hi)]; } }while(0)
;   #define ROT() do{sl_prev=sl_cur;sl_cur=sl_next;sl_next=(sl_next==(NSLOT-1)*SLOTB)?0:sl_next+SLOTB;}while(0)
;   #define ENDW(tt) do{ if((tt)+3<NT){ if constexpr(VM==2){WAIT_BAR(3);}else{WAIT_BAR(2);} } else if((tt)+2<NT){ if constexpr(VM==2){WAIT_BAR(2);}else{WAIT_BAR(1);} } else {WAIT_BAR(0);} }while(0)
; template<int THRL,int VM,bool NOMAX> __device__ __forceinline__ void attn_unit(const bf16*Qb,const bf16*__restrict__ Kh,const bf16*__restrict__ Vh,bf16*Ob,const int NT,const int sp,float*wscr,char*shm){
;     ...
;   for(;t+1<NT;t+=2){
;     STEP(pB0,pB1,pA0,pA1,t,(t+3<NT),(t+1<NT),(t+1<NT));       ENDW(t);   RESC(); ROT();
;     STEP(pA0,pA1,pB0,pB1,t+1,(t+4<NT),(t+2<NT),(t+2<NT));     ENDW(t+1); RESC(); ROT();
	ds_read_b64_tr_b16 v[188:189], v168 offset:40960
	ds_read_b64_tr_b16 v[190:191], v168 offset:41472
	v_add_f32_e32 v48, v96, v97
	v_add_f32_e32 v48, v98, v48
	v_add_f32_e32 v48, v99, v48
	v_add_f32_e32 v48, v100, v48
	v_add_f32_e32 v48, v101, v48
	v_cvt_pk_bf16_f32 v140, v96, v97
	v_cvt_pk_bf16_f32 v141, v98, v99
	s_waitcnt lgkmcnt(9)
	v_mfma_f32_32x32x16_bf16 v[112:127], v[60:63], v[156:159], 0
	ds_read_b64_tr_b16 v[96:97], v168 offset:45056
	ds_read_b64_tr_b16 v[98:99], v168 offset:45568
	v_add_f32_e32 v48, v102, v48
	v_add_f32_e32 v48, v103, v48
	v_add_f32_e32 v48, v104, v48
	v_add_f32_e32 v128, v105, v48
	s_waitcnt lgkmcnt(10)
	v_mfma_f32_32x32x16_bf16 v[48:63], v[64:67], v[156:159], 0
	v_cvt_pk_bf16_f32 v142, v100, v101
	v_cvt_pk_bf16_f32 v143, v102, v103
	ds_read_b64_tr_b16 v[64:65], v168 offset:41984
	ds_read_b64_tr_b16 v[66:67], v168 offset:42496
	v_add_f32_e32 v100, v106, v128
	v_add_f32_e32 v100, v107, v100
	v_add_f32_e32 v100, v108, v100
	v_add_f32_e32 v100, v109, v100
	v_cvt_pk_bf16_f32 v136, v104, v105
	v_cvt_pk_bf16_f32 v137, v106, v107
	s_waitcnt lgkmcnt(11)
	v_mfma_f32_32x32x16_bf16 v[112:127], v[68:71], v[152:155], v[112:127]
	ds_read_b64_tr_b16 v[68:69], v168 offset:46080
	ds_read_b64_tr_b16 v[70:71], v168 offset:46592
	s_waitcnt lgkmcnt(12)
	v_mfma_f32_32x32x16_bf16 v[48:63], v[160:163], v[152:155], v[48:63]
	v_add_f32_e32 v100, v110, v100
	v_add_f32_e32 v100, v111, v100
	v_add_f32_e32 v100, v80, v100
	v_add_f32_e32 v104, v81, v100
	v_cvt_pk_bf16_f32 v138, v108, v109
	v_cvt_pk_bf16_f32 v139, v110, v111
	ds_read_b64_tr_b16 v[100:101], v168 offset:43008
	ds_read_b64_tr_b16 v[102:103], v168 offset:43520
	v_add_f32_e32 v104, v82, v104
	v_add_f32_e32 v104, v83, v104
	v_add_f32_e32 v104, v84, v104
	v_add_f32_e32 v104, v85, v104
	v_cvt_pk_bf16_f32 v132, v80, v81
	v_cvt_pk_bf16_f32 v133, v82, v83
	s_waitcnt lgkmcnt(13)
	v_mfma_f32_32x32x16_bf16 v[112:127], v[72:75], v[148:151], v[112:127]
	ds_read_b64_tr_b16 v[72:73], v168 offset:47104
	ds_read_b64_tr_b16 v[74:75], v168 offset:47616
	s_waitcnt lgkmcnt(14)
	v_mfma_f32_32x32x16_bf16 v[48:63], v[164:167], v[148:151], v[48:63]
	v_add_f32_e32 v80, v86, v104
	v_add_f32_e32 v80, v87, v80
	v_add_f32_e32 v80, v88, v80
	v_add_f32_e32 v104, v89, v80
	v_cvt_pk_bf16_f32 v134, v84, v85
	v_cvt_pk_bf16_f32 v135, v86, v87
	ds_read_b64_tr_b16 v[80:81], v168 offset:44032
	ds_read_b64_tr_b16 v[82:83], v168 offset:44544
	v_add_f32_e32 v84, v90, v104
	v_add_f32_e32 v84, v91, v84
	v_add_f32_e32 v84, v92, v84
	v_add_f32_e32 v84, v93, v84
	v_cvt_pk_bf16_f32 v128, v88, v89
	v_cvt_pk_bf16_f32 v129, v90, v91
	s_waitcnt lgkmcnt(14)
	v_mfma_f32_32x32x16_bf16 v[112:127], v[76:79], v[144:147], v[112:127]
	ds_read_b64_tr_b16 v[76:77], v168 offset:48128
	ds_read_b64_tr_b16 v[78:79], v168 offset:48640
	v_mfma_f32_32x32x16_bf16 v[48:63], v[184:187], v[144:147], v[48:63]
	v_add_f32_e32 v84, v94, v84
	v_add_f32_e32 v84, v95, v84
	v_add_f32_e32 v84, 0, v84
	v_cvt_pk_bf16_f32 v130, v92, v93
	v_cvt_pk_bf16_f32 v131, v94, v95
	s_nop 0
	v_add_f32_e32 v175, v175, v84
	v_lshl_add_u64 v[84:85], v[172:173], 0, s[44:45]
	s_mov_b32 s29, m0
	s_mov_b32 m0, s17
	s_nop 0
	global_load_lds_dwordx4 v[84:85], off
	s_mov_b32 m0, s29
	v_lshl_add_u64 v[84:85], v[170:171], 0, s[48:49]
	s_add_i32 s17, s28, 0x8000
	s_mov_b32 s29, m0
	s_mov_b32 m0, s17
	s_nop 0
	global_load_lds_dwordx4 v[84:85], off
	s_mov_b32 m0, s29
	s_waitcnt lgkmcnt(14)
	v_mfma_f32_32x32x16_bf16 v[16:31], v[140:143], v[188:191], v[16:31]
	v_exp_f32_e32 v112, v112
	v_exp_f32_e32 v113, v113
	v_exp_f32_e32 v114, v114
	v_exp_f32_e32 v115, v115
	s_waitcnt lgkmcnt(12)
	v_mfma_f32_32x32x16_bf16 v[32:47], v[140:143], v[96:99], v[32:47]
	v_exp_f32_e32 v116, v116
	v_exp_f32_e32 v117, v117
	v_exp_f32_e32 v118, v118
	v_exp_f32_e32 v119, v119
	ds_read_b128 v[84:87], v234 offset:8192
	ds_read_b128 v[96:99], v234 offset:12288
	s_waitcnt lgkmcnt(12)
	v_mfma_f32_32x32x16_bf16 v[16:31], v[136:139], v[64:67], v[16:31]
	v_exp_f32_e32 v120, v120
	v_exp_f32_e32 v121, v121
	v_exp_f32_e32 v122, v122
	v_exp_f32_e32 v123, v123
	ds_read_b128 v[104:107], v235 offset:8192
	ds_read_b128 v[108:111], v235 offset:12288
	s_waitcnt lgkmcnt(12)
	v_mfma_f32_32x32x16_bf16 v[32:47], v[136:139], v[68:71], v[32:47]
	v_exp_f32_e32 v124, v124
	v_exp_f32_e32 v125, v125
	v_exp_f32_e32 v126, v126
	v_exp_f32_e32 v127, v127
	ds_read_b128 v[160:163], v236 offset:8192
	ds_read_b128 v[164:167], v236 offset:12288
	s_waitcnt lgkmcnt(12)
	v_mfma_f32_32x32x16_bf16 v[16:31], v[132:135], v[100:103], v[16:31]
	v_exp_f32_e32 v48, v48
	v_exp_f32_e32 v49, v49
	v_exp_f32_e32 v50, v50
	v_exp_f32_e32 v51, v51
	ds_read_b128 v[100:103], v237 offset:8192
	ds_read_b128 v[184:187], v237 offset:12288
	s_waitcnt lgkmcnt(12)
	v_mfma_f32_32x32x16_bf16 v[32:47], v[132:135], v[72:75], v[32:47]
	v_exp_f32_e32 v52, v52
	v_exp_f32_e32 v53, v53
	v_exp_f32_e32 v54, v54
	v_exp_f32_e32 v55, v55
	s_waitcnt lgkmcnt(10)
	v_mfma_f32_32x32x16_bf16 v[16:31], v[128:131], v[80:83], v[16:31]
	v_exp_f32_e32 v56, v56
	v_exp_f32_e32 v57, v57
	v_exp_f32_e32 v58, v58
	v_exp_f32_e32 v59, v59
	s_waitcnt lgkmcnt(8)
	v_mfma_f32_32x32x16_bf16 v[32:47], v[128:131], v[76:79], v[32:47]
	v_exp_f32_e32 v60, v60
	v_exp_f32_e32 v61, v61
	v_exp_f32_e32 v62, v62
	v_exp_f32_e32 v63, v63
	s_waitcnt vmcnt(2) lgkmcnt(0)
	s_barrier
;   #define RESC() do{ if(!NOMAX&&resc){ asm volatile("s_waitcnt lgkmcnt(0)":::"memory"); \
;       _Pragma("unroll") for(int d_=0;d_<2*VM;++d_) _Pragma("unroll") for(int r=0;r<16;++r)o[d_][r]*=wsf[crow(r,hi)]; } }while(0)
;   #define ROT() do{sl_prev=sl_cur;sl_cur=sl_next;sl_next=(sl_next==(NSLOT-1)*SLOTB)?0:sl_next+SLOTB;}while(0)
;   #define ENDW(tt) do{ if((tt)+3<NT){ if constexpr(VM==2){WAIT_BAR(3);}else{WAIT_BAR(2);} } else if((tt)+2<NT){ if constexpr(VM==2){WAIT_BAR(2);}else{WAIT_BAR(1);} } else {WAIT_BAR(0);} }while(0)
; template<int THRL,int VM,bool NOMAX> __device__ __forceinline__ void attn_unit(const bf16*Qb,const bf16*__restrict__ Kh,const bf16*__restrict__ Vh,bf16*Ob,const int NT,const int sp,float*wscr,char*shm){
;     ...
;   for(;t+1<NT;t+=2){
;     STEP(pB0,pB1,pA0,pA1,t,(t+3<NT),(t+1<NT),(t+1<NT));       ENDW(t);   RESC(); ROT();
;     STEP(pA0,pA1,pB0,pB1,t+1,(t+4<NT),(t+2<NT),(t+2<NT));     ENDW(t+1); RESC(); ROT();
	ds_read_b64_tr_b16 v[188:189], v168 offset:24576
	ds_read_b64_tr_b16 v[190:191], v168 offset:25088
	v_add_f32_e32 v64, v112, v113
	v_add_f32_e32 v64, v114, v64
	v_add_f32_e32 v64, v115, v64
	v_add_f32_e32 v64, v116, v64
	v_add_f32_e32 v64, v117, v64
	v_cvt_pk_bf16_f32 v140, v112, v113
	v_cvt_pk_bf16_f32 v141, v114, v115
	s_waitcnt lgkmcnt(9)
	v_mfma_f32_32x32x16_bf16 v[80:95], v[84:87], v[156:159], 0
	ds_read_b64_tr_b16 v[112:113], v168 offset:28672
	ds_read_b64_tr_b16 v[114:115], v168 offset:29184
	v_add_f32_e32 v64, v118, v64
	v_add_f32_e32 v64, v119, v64
	v_add_f32_e32 v64, v120, v64
	v_add_f32_e32 v128, v121, v64
	v_cvt_pk_bf16_f32 v142, v116, v117
	v_cvt_pk_bf16_f32 v143, v118, v119
	s_waitcnt lgkmcnt(10)
	v_mfma_f32_32x32x16_bf16 v[64:79], v[96:99], v[156:159], 0
	ds_read_b64_tr_b16 v[96:97], v168 offset:25600
	ds_read_b64_tr_b16 v[98:99], v168 offset:26112
	v_add_f32_e32 v116, v122, v128
	v_add_f32_e32 v116, v123, v116
	v_add_f32_e32 v116, v124, v116
	v_add_f32_e32 v116, v125, v116
	v_cvt_pk_bf16_f32 v136, v120, v121
	v_cvt_pk_bf16_f32 v137, v122, v123
	s_waitcnt lgkmcnt(11)
	v_mfma_f32_32x32x16_bf16 v[80:95], v[104:107], v[152:155], v[80:95]
	ds_read_b64_tr_b16 v[104:105], v168 offset:29696
	ds_read_b64_tr_b16 v[106:107], v168 offset:30208
	v_add_f32_e32 v116, v126, v116
	v_add_f32_e32 v116, v127, v116
	v_add_f32_e32 v116, v48, v116
	v_add_f32_e32 v116, v49, v116
	v_cvt_pk_bf16_f32 v138, v124, v125
	v_cvt_pk_bf16_f32 v139, v126, v127
	s_waitcnt lgkmcnt(12)
	v_mfma_f32_32x32x16_bf16 v[64:79], v[108:111], v[152:155], v[64:79]
	ds_read_b64_tr_b16 v[108:109], v168 offset:26624
	ds_read_b64_tr_b16 v[110:111], v168 offset:27136
	v_add_f32_e32 v116, v50, v116
	v_add_f32_e32 v116, v51, v116
	v_add_f32_e32 v116, v52, v116
	v_add_f32_e32 v116, v53, v116
	v_cvt_pk_bf16_f32 v132, v48, v49
	v_cvt_pk_bf16_f32 v133, v50, v51
	s_waitcnt lgkmcnt(13)
	v_mfma_f32_32x32x16_bf16 v[80:95], v[160:163], v[148:151], v[80:95]
	ds_read_b64_tr_b16 v[48:49], v168 offset:30720
	ds_read_b64_tr_b16 v[50:51], v168 offset:31232
	v_add_f32_e32 v116, v54, v116
	v_add_f32_e32 v116, v55, v116
	v_add_f32_e32 v116, v56, v116
	v_add_f32_e32 v116, v57, v116
	v_cvt_pk_bf16_f32 v134, v52, v53
	v_cvt_pk_bf16_f32 v135, v54, v55
	s_waitcnt lgkmcnt(14)
	v_mfma_f32_32x32x16_bf16 v[64:79], v[164:167], v[148:151], v[64:79]
	ds_read_b64_tr_b16 v[52:53], v168 offset:27648
	ds_read_b64_tr_b16 v[54:55], v168 offset:28160
	v_add_f32_e32 v116, v58, v116
	v_add_f32_e32 v116, v59, v116
	v_add_f32_e32 v116, v60, v116
	v_add_f32_e32 v116, v61, v116
	v_cvt_pk_bf16_f32 v128, v56, v57
	v_cvt_pk_bf16_f32 v129, v58, v59
	s_waitcnt lgkmcnt(14)
	v_mfma_f32_32x32x16_bf16 v[80:95], v[100:103], v[144:147], v[80:95]
	ds_read_b64_tr_b16 v[56:57], v168 offset:31744
	ds_read_b64_tr_b16 v[58:59], v168 offset:32256
	v_add_f32_e32 v100, v62, v116
	v_add_f32_e32 v100, v63, v100
	v_add_f32_e32 v100, 0, v100
	v_cvt_pk_bf16_f32 v130, v60, v61
	v_cvt_pk_bf16_f32 v131, v62, v63
	v_mfma_f32_32x32x16_bf16 v[64:79], v[184:187], v[144:147], v[64:79]
	v_lshl_add_u64 v[60:61], v[170:171], 0, s[40:41]
	s_add_i32 s28, s28, 0xa000
	s_mov_b32 s17, m0
	s_mov_b32 m0, s28
	s_nop 0
	global_load_lds_dwordx4 v[60:61], off
	s_mov_b32 m0, s17
	v_add_f32_e32 v172, v175, v100
	s_waitcnt lgkmcnt(14)
	v_mfma_f32_32x32x16_bf16 v[16:31], v[140:143], v[188:191], v[16:31]
	v_exp_f32_e32 v80, v80
	v_exp_f32_e32 v81, v81
	v_exp_f32_e32 v82, v82
	v_exp_f32_e32 v83, v83
	s_waitcnt lgkmcnt(12)
	v_mfma_f32_32x32x16_bf16 v[32:47], v[140:143], v[112:115], v[32:47]
	v_exp_f32_e32 v84, v84
	v_exp_f32_e32 v85, v85
	v_exp_f32_e32 v86, v86
	v_exp_f32_e32 v87, v87
	ds_read_b128 v[60:63], v234 offset:16384
	ds_read_b128 v[112:115], v234 offset:20480
	s_waitcnt lgkmcnt(12)
	v_mfma_f32_32x32x16_bf16 v[16:31], v[136:139], v[96:99], v[16:31]
	v_exp_f32_e32 v88, v88
	v_exp_f32_e32 v89, v89
	v_exp_f32_e32 v90, v90
	v_exp_f32_e32 v91, v91
	ds_read_b128 v[116:119], v235 offset:16384
	ds_read_b128 v[120:123], v235 offset:20480
	s_waitcnt lgkmcnt(12)
	v_mfma_f32_32x32x16_bf16 v[32:47], v[136:139], v[104:107], v[32:47]
	v_exp_f32_e32 v92, v92
	v_exp_f32_e32 v93, v93
	v_exp_f32_e32 v94, v94
	v_exp_f32_e32 v95, v95
	ds_read_b128 v[124:127], v236 offset:16384
	ds_read_b128 v[160:163], v236 offset:20480
	s_waitcnt lgkmcnt(12)
	v_mfma_f32_32x32x16_bf16 v[16:31], v[132:135], v[108:111], v[16:31]
	v_exp_f32_e32 v64, v64
	v_exp_f32_e32 v65, v65
	v_exp_f32_e32 v66, v66
	v_exp_f32_e32 v67, v67
	ds_read_b128 v[164:167], v237 offset:16384
	ds_read_b128 v[184:187], v237 offset:20480
	s_waitcnt lgkmcnt(12)
	v_mfma_f32_32x32x16_bf16 v[32:47], v[132:135], v[48:51], v[32:47]
	v_exp_f32_e32 v68, v68
	v_exp_f32_e32 v69, v69
	v_exp_f32_e32 v70, v70
	v_exp_f32_e32 v71, v71
	s_waitcnt lgkmcnt(10)
	v_mfma_f32_32x32x16_bf16 v[16:31], v[128:131], v[52:55], v[16:31]
	v_exp_f32_e32 v72, v72
	v_exp_f32_e32 v73, v73
	v_exp_f32_e32 v74, v74
	v_exp_f32_e32 v75, v75
	s_waitcnt lgkmcnt(8)
	v_mfma_f32_32x32x16_bf16 v[32:47], v[128:131], v[56:59], v[32:47]
	v_exp_f32_e32 v76, v76
	v_exp_f32_e32 v77, v77
	v_exp_f32_e32 v78, v78
	v_exp_f32_e32 v79, v79
	s_waitcnt vmcnt(1) lgkmcnt(0)
	s_barrier
;   #define RESC() do{ if(!NOMAX&&resc){ asm volatile("s_waitcnt lgkmcnt(0)":::"memory"); \
;       _Pragma("unroll") for(int d_=0;d_<2*VM;++d_) _Pragma("unroll") for(int r=0;r<16;++r)o[d_][r]*=wsf[crow(r,hi)]; } }while(0)
;   #define ROT() do{sl_prev=sl_cur;sl_cur=sl_next;sl_next=(sl_next==(NSLOT-1)*SLOTB)?0:sl_next+SLOTB;}while(0)
;   #define ENDW(tt) do{ if((tt)+3<NT){ if constexpr(VM==2){WAIT_BAR(3);}else{WAIT_BAR(2);} } else if((tt)+2<NT){ if constexpr(VM==2){WAIT_BAR(2);}else{WAIT_BAR(1);} } else {WAIT_BAR(0);} }while(0)
; template<int THRL,int VM,bool NOMAX> __device__ __forceinline__ void attn_unit(const bf16*Qb,const bf16*__restrict__ Kh,const bf16*__restrict__ Vh,bf16*Ob,const int NT,const int sp,float*wscr,char*shm){
;     ...
;   for(;t+1<NT;t+=2){
;     STEP(pB0,pB1,pA0,pA1,t,(t+3<NT),(t+1<NT),(t+1<NT));       ENDW(t);   RESC(); ROT();
;     STEP(pA0,pA1,pB0,pB1,t+1,(t+4<NT),(t+2<NT),(t+2<NT));     ENDW(t+1); RESC(); ROT();
	ds_read_b64_tr_b16 v[188:189], v168 offset:32768
	ds_read_b64_tr_b16 v[190:191], v168 offset:33280
	v_add_f32_e32 v48, v80, v81
	v_add_f32_e32 v48, v82, v48
	v_add_f32_e32 v48, v83, v48
	v_add_f32_e32 v48, v84, v48
	v_add_f32_e32 v48, v85, v48
	v_cvt_pk_bf16_f32 v140, v80, v81
	v_cvt_pk_bf16_f32 v141, v82, v83
	s_waitcnt lgkmcnt(9)
	v_mfma_f32_32x32x16_bf16 v[96:111], v[60:63], v[156:159], 0
	ds_read_b64_tr_b16 v[80:81], v168 offset:36864
	ds_read_b64_tr_b16 v[82:83], v168 offset:37376
	v_add_f32_e32 v48, v86, v48
	v_add_f32_e32 v48, v87, v48
	v_add_f32_e32 v48, v88, v48
	v_add_f32_e32 v128, v89, v48
	s_waitcnt lgkmcnt(10)
	v_mfma_f32_32x32x16_bf16 v[48:63], v[112:115], v[156:159], 0
	v_cvt_pk_bf16_f32 v142, v84, v85
	v_cvt_pk_bf16_f32 v143, v86, v87
	ds_read_b64_tr_b16 v[84:85], v168 offset:33792
	ds_read_b64_tr_b16 v[86:87], v168 offset:34304
	v_add_f32_e32 v112, v90, v128
	v_add_f32_e32 v112, v91, v112
	v_add_f32_e32 v112, v92, v112
	v_add_f32_e32 v112, v93, v112
	v_cvt_pk_bf16_f32 v136, v88, v89
	v_cvt_pk_bf16_f32 v137, v90, v91
	s_waitcnt lgkmcnt(11)
	v_mfma_f32_32x32x16_bf16 v[96:111], v[116:119], v[152:155], v[96:111]
	ds_read_b64_tr_b16 v[88:89], v168 offset:37888
	ds_read_b64_tr_b16 v[90:91], v168 offset:38400
	s_waitcnt lgkmcnt(12)
	v_mfma_f32_32x32x16_bf16 v[48:63], v[120:123], v[152:155], v[48:63]
	v_add_f32_e32 v112, v94, v112
	v_add_f32_e32 v112, v95, v112
	v_add_f32_e32 v112, v64, v112
	v_add_f32_e32 v112, v65, v112
	v_cvt_pk_bf16_f32 v138, v92, v93
	v_cvt_pk_bf16_f32 v139, v94, v95
	ds_read_b64_tr_b16 v[92:93], v168 offset:34816
	ds_read_b64_tr_b16 v[94:95], v168 offset:35328
	v_add_f32_e32 v112, v66, v112
	v_add_f32_e32 v112, v67, v112
	v_add_f32_e32 v112, v68, v112
	v_add_f32_e32 v112, v69, v112
	v_cvt_pk_bf16_f32 v132, v64, v65
	v_cvt_pk_bf16_f32 v133, v66, v67
	s_waitcnt lgkmcnt(13)
	v_mfma_f32_32x32x16_bf16 v[96:111], v[124:127], v[148:151], v[96:111]
	ds_read_b64_tr_b16 v[64:65], v168 offset:38912
	ds_read_b64_tr_b16 v[66:67], v168 offset:39424
	s_waitcnt lgkmcnt(14)
	v_mfma_f32_32x32x16_bf16 v[48:63], v[160:163], v[148:151], v[48:63]
	v_add_f32_e32 v112, v70, v112
	v_add_f32_e32 v112, v71, v112
	v_add_f32_e32 v112, v72, v112
	v_add_f32_e32 v112, v73, v112
	v_cvt_pk_bf16_f32 v134, v68, v69
	v_cvt_pk_bf16_f32 v135, v70, v71
	ds_read_b64_tr_b16 v[68:69], v168 offset:35840
	ds_read_b64_tr_b16 v[70:71], v168 offset:36352
	v_add_f32_e32 v112, v74, v112
	v_add_f32_e32 v112, v75, v112
	v_add_f32_e32 v112, v76, v112
	v_add_f32_e32 v112, v77, v112
	v_cvt_pk_bf16_f32 v128, v72, v73
	v_cvt_pk_bf16_f32 v129, v74, v75
	s_waitcnt lgkmcnt(14)
	v_mfma_f32_32x32x16_bf16 v[96:111], v[164:167], v[144:147], v[96:111]
	ds_read_b64_tr_b16 v[72:73], v168 offset:39936
	ds_read_b64_tr_b16 v[74:75], v168 offset:40448
	v_mfma_f32_32x32x16_bf16 v[48:63], v[184:187], v[144:147], v[48:63]
	v_add_f32_e32 v112, v78, v112
	v_add_f32_e32 v112, v79, v112
	v_add_f32_e32 v112, 0, v112
	v_cvt_pk_bf16_f32 v130, v76, v77
	v_cvt_pk_bf16_f32 v131, v78, v79
	v_lshl_add_u64 v[76:77], v[170:171], 0, s[44:45]
	s_mov_b32 s17, m0
	s_mov_b32 m0, s16
	s_nop 0
	global_load_lds_dwordx4 v[76:77], off
	s_mov_b32 m0, s17
	v_add_f32_e32 v120, v172, v112
	s_waitcnt lgkmcnt(14)
	v_mfma_f32_32x32x16_bf16 v[16:31], v[140:143], v[188:191], v[16:31]
	v_exp_f32_e32 v96, v96
	v_exp_f32_e32 v97, v97
	v_exp_f32_e32 v98, v98
	v_exp_f32_e32 v99, v99
	s_waitcnt lgkmcnt(12)
	v_mfma_f32_32x32x16_bf16 v[32:47], v[140:143], v[80:83], v[32:47]
	v_exp_f32_e32 v100, v100
	v_exp_f32_e32 v101, v101
	v_exp_f32_e32 v102, v102
	v_exp_f32_e32 v103, v103
	ds_read_b128 v[76:79], v234
	ds_read_b128 v[80:83], v234 offset:4096
	s_waitcnt lgkmcnt(12)
	v_mfma_f32_32x32x16_bf16 v[16:31], v[136:139], v[84:87], v[16:31]
	v_exp_f32_e32 v104, v104
	v_exp_f32_e32 v105, v105
	v_exp_f32_e32 v106, v106
	v_exp_f32_e32 v107, v107
	ds_read_b128 v[122:125], v235
	ds_read_b128 v[160:163], v235 offset:4096
	s_waitcnt lgkmcnt(12)
	v_mfma_f32_32x32x16_bf16 v[32:47], v[136:139], v[88:91], v[32:47]
	v_exp_f32_e32 v108, v108
	v_exp_f32_e32 v109, v109
	v_exp_f32_e32 v110, v110
	v_exp_f32_e32 v111, v111
	ds_read_b128 v[164:167], v236
	ds_read_b128 v[170:173], v236 offset:4096
	s_waitcnt lgkmcnt(12)
	v_mfma_f32_32x32x16_bf16 v[16:31], v[132:135], v[92:95], v[16:31]
	v_exp_f32_e32 v48, v48
	v_exp_f32_e32 v49, v49
	v_exp_f32_e32 v50, v50
	v_exp_f32_e32 v51, v51
	ds_read_b128 v[184:187], v237
	ds_read_b128 v[188:191], v237 offset:4096
	s_waitcnt lgkmcnt(12)
	v_mfma_f32_32x32x16_bf16 v[32:47], v[132:135], v[64:67], v[32:47]
	v_exp_f32_e32 v52, v52
	v_exp_f32_e32 v53, v53
	v_exp_f32_e32 v54, v54
	v_exp_f32_e32 v55, v55
	s_waitcnt lgkmcnt(10)
	v_mfma_f32_32x32x16_bf16 v[16:31], v[128:131], v[68:71], v[16:31]
	v_exp_f32_e32 v56, v56
	v_exp_f32_e32 v57, v57
	v_exp_f32_e32 v58, v58
	v_exp_f32_e32 v59, v59
	s_waitcnt lgkmcnt(8)
	v_mfma_f32_32x32x16_bf16 v[32:47], v[128:131], v[72:75], v[32:47]
	v_exp_f32_e32 v60, v60
	v_exp_f32_e32 v61, v61
	v_exp_f32_e32 v62, v62
	v_exp_f32_e32 v63, v63
	s_waitcnt vmcnt(0) lgkmcnt(0)
	s_barrier
;   #define RESC() do{ if(!NOMAX&&resc){ asm volatile("s_waitcnt lgkmcnt(0)":::"memory"); \
;       _Pragma("unroll") for(int d_=0;d_<2*VM;++d_) _Pragma("unroll") for(int r=0;r<16;++r)o[d_][r]*=wsf[crow(r,hi)]; } }while(0)
; template<int THRL,int VM,bool NOMAX> __device__ __forceinline__ void attn_unit(const bf16*Qb,const bf16*__restrict__ Kh,const bf16*__restrict__ Vh,bf16*Ob,const int NT,const int sp,float*wscr,char*shm){
;     ...
;   STEP(pB0,pB1,pA0,pA1,NT-1,false,false,false); RESC();
	ds_read_b64_tr_b16 v[112:113], v168 offset:40960
	ds_read_b64_tr_b16 v[114:115], v168 offset:41472
	v_add_f32_e32 v64, v96, v97
	v_add_f32_e32 v64, v98, v64
	v_add_f32_e32 v64, v99, v64
	v_add_f32_e32 v64, v100, v64
	v_add_f32_e32 v84, v101, v64
	v_cvt_pk_bf16_f32 v140, v96, v97
	v_cvt_pk_bf16_f32 v141, v98, v99
	s_waitcnt lgkmcnt(9)
	v_mfma_f32_32x32x16_bf16 v[64:79], v[76:79], v[156:159], 0
	ds_read_b64_tr_b16 v[96:97], v168 offset:45056
	ds_read_b64_tr_b16 v[98:99], v168 offset:45568
	v_add_f32_e32 v84, v102, v84
	v_add_f32_e32 v84, v103, v84
	v_add_f32_e32 v84, v104, v84
	v_add_f32_e32 v121, v105, v84
	v_cvt_pk_bf16_f32 v142, v100, v101
	v_cvt_pk_bf16_f32 v143, v102, v103
	s_waitcnt lgkmcnt(10)
	v_mfma_f32_32x32x16_bf16 v[80:95], v[80:83], v[156:159], 0
	ds_read_b64_tr_b16 v[116:117], v168 offset:41984
	ds_read_b64_tr_b16 v[118:119], v168 offset:42496
	v_add_f32_e32 v100, v106, v121
	v_add_f32_e32 v100, v107, v100
	v_add_f32_e32 v100, v108, v100
	v_add_f32_e32 v121, v109, v100
	v_cvt_pk_bf16_f32 v136, v104, v105
	v_cvt_pk_bf16_f32 v137, v106, v107
	s_waitcnt lgkmcnt(11)
	v_mfma_f32_32x32x16_bf16 v[64:79], v[122:125], v[152:155], v[64:79]
	ds_read_b64_tr_b16 v[100:101], v168 offset:46080
	ds_read_b64_tr_b16 v[102:103], v168 offset:46592
	v_add_f32_e32 v104, v110, v121
	v_add_f32_e32 v104, v111, v104
	v_add_f32_e32 v104, v48, v104
	v_add_f32_e32 v121, v49, v104
	v_cvt_pk_bf16_f32 v138, v108, v109
	v_cvt_pk_bf16_f32 v139, v110, v111
	s_waitcnt lgkmcnt(12)
	v_mfma_f32_32x32x16_bf16 v[80:95], v[160:163], v[152:155], v[80:95]
	ds_read_b64_tr_b16 v[104:105], v168 offset:43008
	ds_read_b64_tr_b16 v[106:107], v168 offset:43520
	v_add_f32_e32 v108, v50, v121
	v_add_f32_e32 v108, v51, v108
	v_add_f32_e32 v108, v52, v108
	v_add_f32_e32 v108, v53, v108
	v_cvt_pk_bf16_f32 v132, v48, v49
	v_cvt_pk_bf16_f32 v133, v50, v51
	s_waitcnt lgkmcnt(13)
	v_mfma_f32_32x32x16_bf16 v[64:79], v[164:167], v[148:151], v[64:79]
	ds_read_b64_tr_b16 v[48:49], v168 offset:47104
	ds_read_b64_tr_b16 v[50:51], v168 offset:47616
	v_add_f32_e32 v108, v54, v108
	v_add_f32_e32 v108, v55, v108
	v_add_f32_e32 v108, v56, v108
	v_add_f32_e32 v121, v57, v108
	v_cvt_pk_bf16_f32 v134, v52, v53
	v_cvt_pk_bf16_f32 v135, v54, v55
	s_waitcnt lgkmcnt(14)
	v_mfma_f32_32x32x16_bf16 v[80:95], v[170:173], v[148:151], v[80:95]
	ds_read_b64_tr_b16 v[108:109], v168 offset:44032
	ds_read_b64_tr_b16 v[110:111], v168 offset:44544
	v_add_f32_e32 v52, v58, v121
	v_add_f32_e32 v52, v59, v52
	v_add_f32_e32 v52, v60, v52
	v_add_f32_e32 v121, v61, v52
	v_cvt_pk_bf16_f32 v128, v56, v57
	v_cvt_pk_bf16_f32 v129, v58, v59
	s_waitcnt lgkmcnt(14)
	v_mfma_f32_32x32x16_bf16 v[64:79], v[184:187], v[144:147], v[64:79]
	ds_read_b64_tr_b16 v[52:53], v168 offset:48128
	ds_read_b64_tr_b16 v[54:55], v168 offset:48640
	v_add_f32_e32 v56, v62, v121
	v_add_f32_e32 v56, v63, v56
	v_add_f32_e32 v56, 0, v56
	v_cvt_pk_bf16_f32 v130, v60, v61
	v_cvt_pk_bf16_f32 v131, v62, v63
	v_mfma_f32_32x32x16_bf16 v[80:95], v[188:191], v[144:147], v[80:95]
	s_nop 3
	v_exp_f32_e32 v64, v64
	v_exp_f32_e32 v65, v65
	v_exp_f32_e32 v66, v66
	v_exp_f32_e32 v67, v67
	s_nop 0
	v_exp_f32_e32 v68, v68
	v_exp_f32_e32 v69, v69
	v_exp_f32_e32 v70, v70
	v_exp_f32_e32 v71, v71
	s_nop 0
	v_exp_f32_e32 v72, v72
	v_exp_f32_e32 v73, v73
	v_exp_f32_e32 v74, v74
	v_exp_f32_e32 v75, v75
	s_nop 0
	v_exp_f32_e32 v76, v76
	v_exp_f32_e32 v77, v77
	v_exp_f32_e32 v78, v78
	v_exp_f32_e32 v79, v79
	v_exp_f32_e32 v80, v80
	v_exp_f32_e32 v81, v81
	v_exp_f32_e32 v82, v82
	v_exp_f32_e32 v83, v83
	s_nop 0
	v_exp_f32_e32 v84, v84
	v_exp_f32_e32 v85, v85
	v_exp_f32_e32 v86, v86
	v_exp_f32_e32 v87, v87
	s_nop 0
	v_exp_f32_e32 v88, v88
	v_exp_f32_e32 v89, v89
	v_exp_f32_e32 v90, v90
	v_exp_f32_e32 v91, v91
	s_nop 0
	v_exp_f32_e32 v92, v92
	v_exp_f32_e32 v93, v93
	v_exp_f32_e32 v94, v94
	v_exp_f32_e32 v95, v95
	s_waitcnt lgkmcnt(14)
; #define SBAR() __builtin_amdgcn_sched_barrier(0)
;   #define PKW(P,B) cvtpk_s(P[B],P[B+1])
; template<int THRL,int VM,bool NOMAX> __device__ __forceinline__ void attn_unit(const bf16*Qb,const bf16*__restrict__ Kh,const bf16*__restrict__ Vh,bf16*Ob,const int NT,const int sp,float*wscr,char*shm){
;     ...
;   { float sacc=pB0[0]+pB0[1]; _Pragma("unroll") for(int r=2;r<16;++r)sacc+=pB0[r]; _Pragma("unroll") for(int r=0;r<16;++r)sacc+=pB1[r]; l_reg+=sacc;
;     pw0=(u32x4){PKW(pB0,0),PKW(pB0,2),PKW(pB0,4),PKW(pB0,6)};pw1=(u32x4){PKW(pB0,8),PKW(pB0,10),PKW(pB0,12),PKW(pB0,14)};pw2=(u32x4){PKW(pB1,0),PKW(pB1,2),PKW(pB1,4),PKW(pB1,6)};pw3=(u32x4){PKW(pB1,8),PKW(pB1,10),PKW(pB1,12),PKW(pB1,14)};
;     SBAR(); pv(o,vb0+VM*sl_cur,PAF(0),PAF(1),PAF(2),PAF(3)); if constexpr(VM==2) pv(o+2,vb0+VM*sl_cur+8192,PAF(0),PAF(1),PAF(2),PAF(3)); }
;     ...
;   {auto rr=__builtin_amdgcn_permlane32_swap(__float_as_uint(l_reg),__float_as_uint(l_reg),false,false);l_reg=__uint_as_float(rr[0])+__uint_as_float(rr[1]);}
;   if(hi==0)wsf[32+r32]=l_reg;asm volatile("s_waitcnt lgkmcnt(0)":::"memory");
	v_mfma_f32_32x32x16_bf16 v[16:31], v[140:143], v[112:115], v[16:31]
	v_add_f32_e32 v57, v64, v65
	v_add_f32_e32 v57, v66, v57
	v_add_f32_e32 v57, v67, v57
	v_add_f32_e32 v57, v68, v57
	v_add_f32_e32 v57, v69, v57
	v_add_f32_e32 v57, v70, v57
	v_add_f32_e32 v57, v71, v57
	s_waitcnt lgkmcnt(12)
	v_mfma_f32_32x32x16_bf16 v[32:47], v[140:143], v[96:99], v[32:47]
	v_add_f32_e32 v57, v72, v57
	v_add_f32_e32 v57, v73, v57
	v_add_f32_e32 v57, v74, v57
	v_add_f32_e32 v57, v75, v57
	v_add_f32_e32 v57, v76, v57
	v_add_f32_e32 v57, v77, v57
	v_add_f32_e32 v57, v78, v57
	s_waitcnt lgkmcnt(10)
	v_mfma_f32_32x32x16_bf16 v[16:31], v[136:139], v[116:119], v[16:31]
	v_add_f32_e32 v57, v79, v57
	v_add_f32_e32 v57, v80, v57
	v_add_f32_e32 v57, v81, v57
	v_add_f32_e32 v57, v82, v57
	v_add_f32_e32 v57, v83, v57
	v_add_f32_e32 v57, v84, v57
	v_add_f32_e32 v57, v85, v57
	s_waitcnt lgkmcnt(8)
	v_mfma_f32_32x32x16_bf16 v[32:47], v[136:139], v[100:103], v[32:47]
	v_add_f32_e32 v57, v86, v57
	v_add_f32_e32 v57, v87, v57
	v_add_f32_e32 v57, v88, v57
	v_add_f32_e32 v57, v89, v57
	v_add_f32_e32 v57, v90, v57
	v_add_f32_e32 v57, v91, v57
	v_add_f32_e32 v57, v92, v57
	s_waitcnt lgkmcnt(6)
	v_mfma_f32_32x32x16_bf16 v[16:31], v[132:135], v[104:107], v[16:31]
	v_add_f32_e32 v57, v93, v57
	v_add_f32_e32 v57, v94, v57
	v_add_f32_e32 v57, v95, v57
	v_add_f32_e32 v56, v120, v56
	v_add_f32_e32 v56, v56, v57
	v_cvt_pk_bf16_f32 v58, v64, v65
	v_cvt_pk_bf16_f32 v59, v66, v67
	s_waitcnt lgkmcnt(4)
	v_mfma_f32_32x32x16_bf16 v[32:47], v[132:135], v[48:51], v[32:47]
	v_cvt_pk_bf16_f32 v48, v80, v81
	v_cvt_pk_bf16_f32 v60, v68, v69
	v_cvt_pk_bf16_f32 v61, v70, v71
	v_cvt_pk_bf16_f32 v62, v72, v73
	v_cvt_pk_bf16_f32 v63, v74, v75
	v_cvt_pk_bf16_f32 v64, v76, v77
	v_cvt_pk_bf16_f32 v65, v78, v79
	s_waitcnt lgkmcnt(2)
	v_mfma_f32_32x32x16_bf16 v[16:31], v[128:131], v[108:111], v[16:31]
	v_cvt_pk_bf16_f32 v49, v82, v83
	v_cvt_pk_bf16_f32 v50, v84, v85
	v_cvt_pk_bf16_f32 v51, v86, v87
	v_cvt_pk_bf16_f32 v66, v88, v89
	v_cvt_pk_bf16_f32 v67, v90, v91
	v_cvt_pk_bf16_f32 v68, v92, v93
	v_cvt_pk_bf16_f32 v69, v94, v95
	s_waitcnt lgkmcnt(0)
	v_mfma_f32_32x32x16_bf16 v[32:47], v[128:131], v[52:55], v[32:47]
	ds_read_b64_tr_b16 v[52:53],v174 offset:0
	ds_read_b64_tr_b16 v[54:55],v174 offset:512
	ds_read_b64_tr_b16 v[70:71],v174 offset:1024
	ds_read_b64_tr_b16 v[72:73],v174 offset:1536
	ds_read_b64_tr_b16 v[74:75],v174 offset:2048
	ds_read_b64_tr_b16 v[76:77],v174 offset:2560
	ds_read_b64_tr_b16 v[78:79],v174 offset:3072
	ds_read_b64_tr_b16 v[80:81],v174 offset:3584
	s_waitcnt lgkmcnt(0)
	s_nop 0
	v_mfma_f32_32x32x16_bf16 v[16:31], v[58:61], v[52:55], v[16:31]
	ds_read_b64_tr_b16 v[52:53],v174 offset:4096
	ds_read_b64_tr_b16 v[54:55],v174 offset:4608
	v_mfma_f32_32x32x16_bf16 v[16:31], v[62:65], v[70:73], v[16:31]
	ds_read_b64_tr_b16 v[70:71],v174 offset:5120
	ds_read_b64_tr_b16 v[72:73],v174 offset:5632
	v_mfma_f32_32x32x16_bf16 v[16:31], v[48:51], v[74:77], v[16:31]
	ds_read_b64_tr_b16 v[74:75],v174 offset:6144
	ds_read_b64_tr_b16 v[76:77],v174 offset:6656
	ds_read_b64_tr_b16 v[82:83],v174 offset:7168
	ds_read_b64_tr_b16 v[84:85],v174 offset:7680
	s_waitcnt lgkmcnt(0)
	v_mfma_f32_32x32x16_bf16 v[16:31], v[66:69], v[78:81], v[16:31]
	v_mfma_f32_32x32x16_bf16 v[32:47], v[58:61], v[52:55], v[32:47]
	v_cmp_gt_u32_e32 vcc, 32, v178
	v_mfma_f32_32x32x16_bf16 v[32:47], v[62:65], v[70:73], v[32:47]
	v_mfma_f32_32x32x16_bf16 v[32:47], v[48:51], v[74:77], v[32:47]
	v_mov_b32_e32 v48, v56
	s_nop 1
	v_permlane32_swap_b32_e32 v56, v48
	v_mfma_f32_32x32x16_bf16 v[32:47], v[66:69], v[82:85], v[32:47]
	s_and_saveexec_b64 s[16:17], vcc
	s_cbranch_execz .LBB0_887
	v_add_f32_e32 v48, v56, v48
	v_lshl_add_u32 v49, v180, 2, s19
	ds_write_b32 v49, v48 offset:49280
	s_branch .LBB0_887
